# combo10 + redundant post-barrier lgkmcnt(0) waits removed from the GEMM K-loops
# speedup vs baseline: 1.0158x; 1.0036x over previous
; #define PG8_STAGE(bufoff, gbase, voff) do { _Pragma("unroll") for (int _i = 0; _i < 2; ++_i) \
;         __builtin_amdgcn_global_load_lds((const unsigned*)((const char*)(gbase) + (voff)[_i]), (LAS unsigned*)(lds + (bufoff) + ldsw + _i * 8192), 16, 0, 0); } while (0)
; #define PG8_LDA(dst, b, h) do { _Pragma("unroll") for (int m = 0; m < 4; ++m) _Pragma("unroll") for (int k = 0; k < 2; ++k) dst[m][k] = *(const LAS bf16x8*)(lds + PG8_SA(b, h) + aoff + m * 2048 + k * 1024); } while (0)
; #define PG8_LDB(dst, b, h) do { _Pragma("unroll") for (int n = 0; n < 2; ++n) _Pragma("unroll") for (int k = 0; k < 2; ++k) dst[n][k] = *(const LAS bf16x8*)(lds + PG8_SB(b, h) + boff + n * 2048 + k * 1024); } while (0)
; #define PG8_MMA(ai, bj, At, Bt) do { __builtin_amdgcn_s_setprio(1); _Pragma("unroll") for (int m = 0; m < 4; ++m) _Pragma("unroll") for (int n = 0; n < 2; ++n) _Pragma("unroll") for (int k = 0; k < 2; ++k) \
;         acc[ai][bj][m][n] = __builtin_amdgcn_mfma_f32_16x16x32_bf16(Bt[n][k], At[m][k], acc[ai][bj][m][n], 0, 0, 0); __builtin_amdgcn_s_setprio(0); } while (0)
; #define PG8_WAIT_V(n) asm volatile("s_waitcnt vmcnt(" #n ")" ::: "memory")
; #define PG8_WAIT_L(n) asm volatile("s_waitcnt lgkmcnt(" #n ")" ::: "memory")
; #define PG8_BAR __builtin_amdgcn_s_barrier()
; #define PG8_SCHED __builtin_amdgcn_sched_barrier(0)
; template <class Epi>
; __device__ __forceinline__ void gemm_phase(LAS unsigned char* lds, const Gemm g, const StaticOrder& S, const Epi& E, const int tid) {
;     ...
;             const char* a1 = cA + (size_t)(t + 1) * kstep;
;             const char* a2 = last ? nA : cA + (size_t)(t + 2) * kstep; const char* b2 = last ? nB : cB + (size_t)(t + 2) * kstep;
;             const char* a3 = a2 + kstep; const char* b3 = b2 + kstep;
;             PG8_LDB(B0, 0, 0); PG8_LDB(B1, 0, 1); PG8_SCHED; PG8_LDA(At, 0, 0); PG8_STAGE(PG8_SA(1, 1), a1 + hsA, voffA);
;             PG8_WAIT_V(8); PG8_WAIT_L(0); PG8_BAR; PG8_MMA(0, 0, At, B0); PG8_MMA(0, 1, At, B1); PG8_BAR; PG8_SCHED;
;             PG8_LDA(At, 0, 1); PG8_STAGE(PG8_SB(0, 0), b2, voffB); PG8_STAGE(PG8_SB(0, 1), b2 + hsB, voffB); PG8_STAGE(PG8_SA(0, 0), a2, voffA);
;             PG8_WAIT_V(8); PG8_WAIT_L(0); PG8_BAR; PG8_MMA(1, 0, At, B0); PG8_MMA(1, 1, At, B1); PG8_BAR; PG8_SCHED;
.Lgprio_a:
.LBB0_161:
	s_add_u32 s0, s34, 0xfff80080
	s_addc_u32 s1, s35, -1
	s_add_i32 s24, 0, 0x10000
	s_cmp_eq_u32 s59, 28
	s_cselect_b32 s39, s15, s1
	s_cselect_b32 s38, s53, s0
	s_cselect_b32 s1, s13, s58
	s_cselect_b32 s0, s56, s57
	s_add_i32 s25, 0, 0x14000
	v_add_u32_e32 v154, s24, v143
	v_add_u32_e32 v166, s25, v143
	ds_read_b128 v[138:141], v154
	ds_read_b128 v[146:149], v154 offset:1024
	ds_read_b128 v[150:153], v154 offset:2048
	ds_read_b128 v[154:157], v154 offset:3072
	ds_read_b128 v[158:161], v166
	ds_read_b128 v[162:165], v166 offset:1024
	ds_read_b128 v[184:187], v166 offset:2048
	ds_read_b128 v[188:191], v166 offset:3072
	v_lshl_add_u64 v[166:167], s[34:35], 0, v[134:135]
	s_add_i32 m0, s42, 0xc000
	ds_read_b128 v[192:195], v145
	ds_read_b128 v[196:199], v145 offset:1024
	ds_read_b128 v[200:203], v145 offset:2048
	ds_read_b128 v[204:207], v145 offset:3072
	ds_read_b128 v[208:211], v145 offset:4096
	ds_read_b128 v[230:233], v145 offset:5120
	ds_read_b128 v[234:237], v145 offset:6144
	ds_read_b128 v[238:241], v145 offset:7168
	global_load_lds_dwordx4 v[166:167], off
	v_lshl_add_u64 v[166:167], s[34:35], 0, v[136:137]
	s_add_i32 m0, s42, 0xe000
	s_nop 0
	global_load_lds_dwordx4 v[166:167], off
	s_waitcnt vmcnt(8)
	s_waitcnt lgkmcnt(0)
	s_barrier
	v_mfma_f32_16x16x32_bf16 v[124:127], v[138:141], v[192:195], v[124:127]
	v_mfma_f32_16x16x32_bf16 v[116:119], v[150:153], v[192:195], v[116:119]
	v_mfma_f32_16x16x32_bf16 v[108:111], v[138:141], v[200:203], v[108:111]
	v_mfma_f32_16x16x32_bf16 v[100:103], v[150:153], v[200:203], v[100:103]
	v_mfma_f32_16x16x32_bf16 v[92:95], v[138:141], v[208:211], v[92:95]
	v_mfma_f32_16x16x32_bf16 v[84:87], v[150:153], v[208:211], v[84:87]
	v_mfma_f32_16x16x32_bf16 v[76:79], v[138:141], v[234:237], v[76:79]
	v_mfma_f32_16x16x32_bf16 v[68:71], v[150:153], v[234:237], v[68:71]
	v_mfma_f32_16x16x32_bf16 v[124:127], v[146:149], v[196:199], v[124:127]
	v_mfma_f32_16x16x32_bf16 v[116:119], v[154:157], v[196:199], v[116:119]
	v_mfma_f32_16x16x32_bf16 v[108:111], v[146:149], v[204:207], v[108:111]
	v_mfma_f32_16x16x32_bf16 v[100:103], v[154:157], v[204:207], v[100:103]
	v_mfma_f32_16x16x32_bf16 v[92:95], v[146:149], v[230:233], v[92:95]
	v_mfma_f32_16x16x32_bf16 v[84:87], v[154:157], v[230:233], v[84:87]
	v_mfma_f32_16x16x32_bf16 v[76:79], v[146:149], v[238:241], v[76:79]
	v_mfma_f32_16x16x32_bf16 v[68:71], v[154:157], v[238:241], v[68:71]
	v_mfma_f32_16x16x32_bf16 v[120:123], v[158:161], v[192:195], v[120:123]
	v_mfma_f32_16x16x32_bf16 v[112:115], v[184:187], v[192:195], v[112:115]
	v_mfma_f32_16x16x32_bf16 v[104:107], v[158:161], v[200:203], v[104:107]
	v_mfma_f32_16x16x32_bf16 v[96:99], v[184:187], v[200:203], v[96:99]
	v_mfma_f32_16x16x32_bf16 v[88:91], v[158:161], v[208:211], v[88:91]
	v_mfma_f32_16x16x32_bf16 v[80:83], v[184:187], v[208:211], v[80:83]
	v_mfma_f32_16x16x32_bf16 v[72:75], v[158:161], v[234:237], v[72:75]
	v_mfma_f32_16x16x32_bf16 v[64:67], v[184:187], v[234:237], v[64:67]
	v_mfma_f32_16x16x32_bf16 v[120:123], v[162:165], v[196:199], v[120:123]
	v_mfma_f32_16x16x32_bf16 v[112:115], v[188:191], v[196:199], v[112:115]
	v_mfma_f32_16x16x32_bf16 v[104:107], v[162:165], v[204:207], v[104:107]
	v_mfma_f32_16x16x32_bf16 v[96:99], v[188:191], v[204:207], v[96:99]
	v_mfma_f32_16x16x32_bf16 v[88:91], v[162:165], v[230:233], v[88:91]
	v_mfma_f32_16x16x32_bf16 v[80:83], v[188:191], v[230:233], v[80:83]
	v_mfma_f32_16x16x32_bf16 v[72:75], v[162:165], v[238:241], v[72:75]
	v_mfma_f32_16x16x32_bf16 v[64:67], v[188:191], v[238:241], v[64:67]
	s_barrier
	s_add_i32 s24, s24, s27
	v_lshl_add_u64 v[166:167], s[0:1], 0, v[168:169]
	s_mov_b32 m0, s24
	ds_read_b128 v[192:195], v145 offset:16384
	ds_read_b128 v[196:199], v145 offset:17408
	ds_read_b128 v[200:203], v145 offset:18432
	ds_read_b128 v[204:207], v145 offset:19456
	ds_read_b128 v[208:211], v145 offset:20480
	ds_read_b128 v[230:233], v145 offset:21504
	ds_read_b128 v[234:237], v145 offset:22528
	ds_read_b128 v[238:241], v145 offset:23552
	global_load_lds_dwordx4 v[166:167], off
	s_add_i32 m0, s24, 0x2000
	s_add_u32 s68, s0, 0x80000
	v_lshl_add_u64 v[212:213], s[0:1], 0, v[132:133]
	s_addc_u32 s69, s1, 0
	s_add_i32 s24, s25, s27
	global_load_lds_dwordx4 v[212:213], off
	v_lshl_add_u64 v[242:243], s[68:69], 0, v[168:169]
	s_mov_b32 m0, s24
	v_lshl_add_u64 v[244:245], s[38:39], 0, v[130:131]
	global_load_lds_dwordx4 v[242:243], off
	v_lshl_add_u64 v[242:243], s[68:69], 0, v[132:133]
	s_add_i32 m0, s24, 0x2000
	s_nop 0
	global_load_lds_dwordx4 v[242:243], off
	v_lshl_add_u64 v[242:243], s[38:39], 0, v[128:129]
	s_mov_b32 m0, s42
	s_nop 0
	global_load_lds_dwordx4 v[242:243], off
	s_mov_b32 m0, s43
	s_nop 0
	global_load_lds_dwordx4 v[244:245], off
	s_waitcnt vmcnt(8)
	s_waitcnt lgkmcnt(0)
	s_barrier
; #define PG8_STAGE(bufoff, gbase, voff) do { _Pragma("unroll") for (int _i = 0; _i < 2; ++_i) \
;         __builtin_amdgcn_global_load_lds((const unsigned*)((const char*)(gbase) + (voff)[_i]), (LAS unsigned*)(lds + (bufoff) + ldsw + _i * 8192), 16, 0, 0); } while (0)
; #define PG8_LDA(dst, b, h) do { _Pragma("unroll") for (int m = 0; m < 4; ++m) _Pragma("unroll") for (int k = 0; k < 2; ++k) dst[m][k] = *(const LAS bf16x8*)(lds + PG8_SA(b, h) + aoff + m * 2048 + k * 1024); } while (0)
; #define PG8_LDB(dst, b, h) do { _Pragma("unroll") for (int n = 0; n < 2; ++n) _Pragma("unroll") for (int k = 0; k < 2; ++k) dst[n][k] = *(const LAS bf16x8*)(lds + PG8_SB(b, h) + boff + n * 2048 + k * 1024); } while (0)
; #define PG8_MMA(ai, bj, At, Bt) do { __builtin_amdgcn_s_setprio(1); _Pragma("unroll") for (int m = 0; m < 4; ++m) _Pragma("unroll") for (int n = 0; n < 2; ++n) _Pragma("unroll") for (int k = 0; k < 2; ++k) \
;         acc[ai][bj][m][n] = __builtin_amdgcn_mfma_f32_16x16x32_bf16(Bt[n][k], At[m][k], acc[ai][bj][m][n], 0, 0, 0); __builtin_amdgcn_s_setprio(0); } while (0)
; #define PG8_WAIT_V(n) asm volatile("s_waitcnt vmcnt(" #n ")" ::: "memory")
; #define PG8_WAIT_L(n) asm volatile("s_waitcnt lgkmcnt(" #n ")" ::: "memory")
; #define PG8_BAR __builtin_amdgcn_s_barrier()
; #define PG8_SCHED __builtin_amdgcn_sched_barrier(0)
; template <class Epi>
; __device__ __forceinline__ void gemm_phase(LAS unsigned char* lds, const Gemm g, const StaticOrder& S, const Epi& E, const int tid) {
;     ...
;             PG8_WAIT_V(8); PG8_WAIT_L(0); PG8_BAR; PG8_MMA(1, 0, At, B0); PG8_MMA(1, 1, At, B1); PG8_BAR; PG8_SCHED;
;             PG8_LDB(B0, 1, 0); PG8_LDB(B1, 1, 1); PG8_SCHED; PG8_LDA(At, 1, 0); PG8_STAGE(PG8_SA(0, 1), a2 + hsA, voffA);
;             PG8_WAIT_V(8); PG8_WAIT_L(0); PG8_BAR; PG8_MMA(0, 0, At, B0); PG8_MMA(0, 1, At, B1); PG8_BAR; PG8_SCHED;
	v_mfma_f32_16x16x32_bf16 v[60:63], v[138:141], v[192:195], v[60:63]
	v_mfma_f32_16x16x32_bf16 v[52:55], v[150:153], v[192:195], v[52:55]
	v_mfma_f32_16x16x32_bf16 v[44:47], v[138:141], v[200:203], v[44:47]
	v_mfma_f32_16x16x32_bf16 v[36:39], v[150:153], v[200:203], v[36:39]
	v_mfma_f32_16x16x32_bf16 v[28:31], v[138:141], v[208:211], v[28:31]
	v_mfma_f32_16x16x32_bf16 v[20:23], v[150:153], v[208:211], v[20:23]
	v_mfma_f32_16x16x32_bf16 v[12:15], v[138:141], v[234:237], v[12:15]
	v_mfma_f32_16x16x32_bf16 v[4:7], v[150:153], v[234:237], v[4:7]
	v_mfma_f32_16x16x32_bf16 v[60:63], v[146:149], v[196:199], v[60:63]
	v_mfma_f32_16x16x32_bf16 v[52:55], v[154:157], v[196:199], v[52:55]
	v_mfma_f32_16x16x32_bf16 v[44:47], v[146:149], v[204:207], v[44:47]
	v_mfma_f32_16x16x32_bf16 v[36:39], v[154:157], v[204:207], v[36:39]
	v_mfma_f32_16x16x32_bf16 v[28:31], v[146:149], v[230:233], v[28:31]
	v_mfma_f32_16x16x32_bf16 v[20:23], v[154:157], v[230:233], v[20:23]
	v_mfma_f32_16x16x32_bf16 v[12:15], v[146:149], v[238:241], v[12:15]
	v_mfma_f32_16x16x32_bf16 v[4:7], v[154:157], v[238:241], v[4:7]
	v_mfma_f32_16x16x32_bf16 v[56:59], v[158:161], v[192:195], v[56:59]
	v_mfma_f32_16x16x32_bf16 v[48:51], v[184:187], v[192:195], v[48:51]
	v_mfma_f32_16x16x32_bf16 v[40:43], v[158:161], v[200:203], v[40:43]
	v_mfma_f32_16x16x32_bf16 v[32:35], v[184:187], v[200:203], v[32:35]
	v_mfma_f32_16x16x32_bf16 v[24:27], v[158:161], v[208:211], v[24:27]
	v_mfma_f32_16x16x32_bf16 v[16:19], v[184:187], v[208:211], v[16:19]
	v_mfma_f32_16x16x32_bf16 v[8:11], v[158:161], v[234:237], v[8:11]
	v_mfma_f32_16x16x32_bf16 v[0:3], v[184:187], v[234:237], v[0:3]
	v_mfma_f32_16x16x32_bf16 v[56:59], v[162:165], v[196:199], v[56:59]
	v_mfma_f32_16x16x32_bf16 v[48:51], v[188:191], v[196:199], v[48:51]
	v_mfma_f32_16x16x32_bf16 v[40:43], v[162:165], v[204:207], v[40:43]
	v_mfma_f32_16x16x32_bf16 v[32:35], v[188:191], v[204:207], v[32:35]
	v_mfma_f32_16x16x32_bf16 v[24:27], v[162:165], v[230:233], v[24:27]
	v_mfma_f32_16x16x32_bf16 v[16:19], v[188:191], v[230:233], v[16:19]
	v_mfma_f32_16x16x32_bf16 v[8:11], v[162:165], v[238:241], v[8:11]
	v_mfma_f32_16x16x32_bf16 v[0:3], v[188:191], v[238:241], v[0:3]
	s_barrier
	s_add_i32 s24, 0, 0x18000
	s_add_i32 s25, 0, 0x1c000
	v_add_u32_e32 v154, s24, v143
	v_add_u32_e32 v170, s25, v143
	ds_read_b128 v[138:141], v154
	ds_read_b128 v[146:149], v154 offset:1024
	ds_read_b128 v[150:153], v154 offset:2048
	ds_read_b128 v[154:157], v154 offset:3072
	ds_read_b128 v[158:161], v170
	ds_read_b128 v[162:165], v170 offset:1024
	ds_read_b128 v[184:187], v170 offset:2048
	ds_read_b128 v[188:191], v170 offset:3072
	s_add_u32 s38, s38, 0x80000
	s_addc_u32 s39, s39, 0
	s_mov_b32 m0, s44
	v_lshl_add_u64 v[246:247], s[38:39], 0, v[128:129]
	ds_read_b128 v[192:195], v145 offset:32768
	ds_read_b128 v[196:199], v145 offset:33792
	ds_read_b128 v[200:203], v145 offset:34816
	ds_read_b128 v[204:207], v145 offset:35840
	ds_read_b128 v[208:211], v145 offset:36864
	ds_read_b128 v[230:233], v145 offset:37888
	ds_read_b128 v[234:237], v145 offset:38912
	ds_read_b128 v[238:241], v145 offset:39936
	global_load_lds_dwordx4 v[246:247], off
	v_lshl_add_u64 v[246:247], s[38:39], 0, v[130:131]
	s_mov_b32 m0, s45
	s_nop 0
	global_load_lds_dwordx4 v[246:247], off
	s_waitcnt vmcnt(8)
	s_waitcnt lgkmcnt(0)
	s_barrier
	v_mfma_f32_16x16x32_bf16 v[124:127], v[138:141], v[192:195], v[124:127]
	v_mfma_f32_16x16x32_bf16 v[116:119], v[150:153], v[192:195], v[116:119]
	v_mfma_f32_16x16x32_bf16 v[108:111], v[138:141], v[200:203], v[108:111]
	v_mfma_f32_16x16x32_bf16 v[100:103], v[150:153], v[200:203], v[100:103]
	v_mfma_f32_16x16x32_bf16 v[92:95], v[138:141], v[208:211], v[92:95]
	v_mfma_f32_16x16x32_bf16 v[84:87], v[150:153], v[208:211], v[84:87]
	v_mfma_f32_16x16x32_bf16 v[76:79], v[138:141], v[234:237], v[76:79]
	v_mfma_f32_16x16x32_bf16 v[68:71], v[150:153], v[234:237], v[68:71]
	v_mfma_f32_16x16x32_bf16 v[124:127], v[146:149], v[196:199], v[124:127]
	v_mfma_f32_16x16x32_bf16 v[116:119], v[154:157], v[196:199], v[116:119]
	v_mfma_f32_16x16x32_bf16 v[108:111], v[146:149], v[204:207], v[108:111]
	v_mfma_f32_16x16x32_bf16 v[100:103], v[154:157], v[204:207], v[100:103]
	v_mfma_f32_16x16x32_bf16 v[92:95], v[146:149], v[230:233], v[92:95]
	v_mfma_f32_16x16x32_bf16 v[84:87], v[154:157], v[230:233], v[84:87]
	v_mfma_f32_16x16x32_bf16 v[76:79], v[146:149], v[238:241], v[76:79]
	v_mfma_f32_16x16x32_bf16 v[68:71], v[154:157], v[238:241], v[68:71]
	v_mfma_f32_16x16x32_bf16 v[120:123], v[158:161], v[192:195], v[120:123]
	v_mfma_f32_16x16x32_bf16 v[112:115], v[184:187], v[192:195], v[112:115]
	v_mfma_f32_16x16x32_bf16 v[104:107], v[158:161], v[200:203], v[104:107]
	v_mfma_f32_16x16x32_bf16 v[96:99], v[184:187], v[200:203], v[96:99]
	v_mfma_f32_16x16x32_bf16 v[88:91], v[158:161], v[208:211], v[88:91]
	v_mfma_f32_16x16x32_bf16 v[80:83], v[184:187], v[208:211], v[80:83]
	v_mfma_f32_16x16x32_bf16 v[72:75], v[158:161], v[234:237], v[72:75]
	v_mfma_f32_16x16x32_bf16 v[64:67], v[184:187], v[234:237], v[64:67]
	v_mfma_f32_16x16x32_bf16 v[120:123], v[162:165], v[196:199], v[120:123]
	v_mfma_f32_16x16x32_bf16 v[112:115], v[188:191], v[196:199], v[112:115]
	v_mfma_f32_16x16x32_bf16 v[104:107], v[162:165], v[204:207], v[104:107]
	v_mfma_f32_16x16x32_bf16 v[96:99], v[188:191], v[204:207], v[96:99]
	v_mfma_f32_16x16x32_bf16 v[88:91], v[162:165], v[230:233], v[88:91]
	v_mfma_f32_16x16x32_bf16 v[80:83], v[188:191], v[230:233], v[80:83]
	v_mfma_f32_16x16x32_bf16 v[72:75], v[162:165], v[238:241], v[72:75]
	v_mfma_f32_16x16x32_bf16 v[64:67], v[188:191], v[238:241], v[64:67]
	s_barrier
; #define PG8_STAGE(bufoff, gbase, voff) do { _Pragma("unroll") for (int _i = 0; _i < 2; ++_i) \
;         __builtin_amdgcn_global_load_lds((const unsigned*)((const char*)(gbase) + (voff)[_i]), (LAS unsigned*)(lds + (bufoff) + ldsw + _i * 8192), 16, 0, 0); } while (0)
; #define PG8_LDA(dst, b, h) do { _Pragma("unroll") for (int m = 0; m < 4; ++m) _Pragma("unroll") for (int k = 0; k < 2; ++k) dst[m][k] = *(const LAS bf16x8*)(lds + PG8_SA(b, h) + aoff + m * 2048 + k * 1024); } while (0)
; #define PG8_MMA(ai, bj, At, Bt) do { __builtin_amdgcn_s_setprio(1); _Pragma("unroll") for (int m = 0; m < 4; ++m) _Pragma("unroll") for (int n = 0; n < 2; ++n) _Pragma("unroll") for (int k = 0; k < 2; ++k) \
;         acc[ai][bj][m][n] = __builtin_amdgcn_mfma_f32_16x16x32_bf16(Bt[n][k], At[m][k], acc[ai][bj][m][n], 0, 0, 0); __builtin_amdgcn_s_setprio(0); } while (0)
; #define PG8_WAIT_V(n) asm volatile("s_waitcnt vmcnt(" #n ")" ::: "memory")
; #define PG8_WAIT_L(n) asm volatile("s_waitcnt lgkmcnt(" #n ")" ::: "memory")
; #define PG8_BAR __builtin_amdgcn_s_barrier()
; #define PG8_SCHED __builtin_amdgcn_sched_barrier(0)
; template <class Epi>
; __device__ __forceinline__ void gemm_phase(LAS unsigned char* lds, const Gemm g, const StaticOrder& S, const Epi& E, const int tid) {
;     ...
;             PG8_LDA(At, 1, 1); PG8_STAGE(PG8_SB(1, 0), b3, voffB); PG8_STAGE(PG8_SB(1, 1), b3 + hsB, voffB); PG8_STAGE(PG8_SA(1, 0), a3, voffA);
;             PG8_WAIT_V(8); PG8_WAIT_L(0); PG8_BAR; PG8_MMA(1, 0, At, B0); PG8_MMA(1, 1, At, B1); PG8_BAR; PG8_SCHED;
;         }
;         if (wr == 0) PG8_BAR;
	s_add_i32 s24, s24, s27
	v_lshl_add_u64 v[166:167], v[166:167], 0, s[28:29]
	s_mov_b32 m0, s24
	ds_read_b128 v[192:195], v145 offset:49152
	ds_read_b128 v[196:199], v145 offset:50176
	ds_read_b128 v[200:203], v145 offset:51200
	ds_read_b128 v[204:207], v145 offset:52224
	ds_read_b128 v[208:211], v145 offset:53248
	ds_read_b128 v[230:233], v145 offset:54272
	ds_read_b128 v[234:237], v145 offset:55296
	ds_read_b128 v[238:241], v145 offset:56320
	global_load_lds_dwordx4 v[166:167], off
	s_add_i32 m0, s24, 0x2000
	s_add_u32 s0, s0, 0x80080
	v_lshl_add_u64 v[166:167], v[212:213], 0, s[28:29]
	s_addc_u32 s1, s1, 0
	s_add_i32 s24, s25, s27
	global_load_lds_dwordx4 v[166:167], off
	v_lshl_add_u64 v[166:167], s[0:1], 0, v[168:169]
	s_mov_b32 m0, s24
	s_nop 0
	global_load_lds_dwordx4 v[166:167], off
	v_lshl_add_u64 v[166:167], s[0:1], 0, v[132:133]
	s_add_i32 m0, s24, 0x2000
	s_nop 0
	global_load_lds_dwordx4 v[166:167], off
	v_lshl_add_u64 v[166:167], v[242:243], 0, s[28:29]
	s_mov_b32 m0, s46
	s_nop 0
	global_load_lds_dwordx4 v[166:167], off
	v_lshl_add_u64 v[166:167], v[244:245], 0, s[28:29]
	s_mov_b32 m0, s47
	s_nop 0
	global_load_lds_dwordx4 v[166:167], off
	s_waitcnt vmcnt(8)
	s_waitcnt lgkmcnt(0)
	s_barrier
	v_mfma_f32_16x16x32_bf16 v[60:63], v[138:141], v[192:195], v[60:63]
	v_mfma_f32_16x16x32_bf16 v[52:55], v[150:153], v[192:195], v[52:55]
	v_mfma_f32_16x16x32_bf16 v[44:47], v[138:141], v[200:203], v[44:47]
	v_mfma_f32_16x16x32_bf16 v[36:39], v[150:153], v[200:203], v[36:39]
	v_mfma_f32_16x16x32_bf16 v[28:31], v[138:141], v[208:211], v[28:31]
	v_mfma_f32_16x16x32_bf16 v[20:23], v[150:153], v[208:211], v[20:23]
	v_mfma_f32_16x16x32_bf16 v[12:15], v[138:141], v[234:237], v[12:15]
	v_mfma_f32_16x16x32_bf16 v[4:7], v[150:153], v[234:237], v[4:7]
	v_mfma_f32_16x16x32_bf16 v[60:63], v[146:149], v[196:199], v[60:63]
	v_mfma_f32_16x16x32_bf16 v[52:55], v[154:157], v[196:199], v[52:55]
	v_mfma_f32_16x16x32_bf16 v[44:47], v[146:149], v[204:207], v[44:47]
	v_mfma_f32_16x16x32_bf16 v[36:39], v[154:157], v[204:207], v[36:39]
	v_mfma_f32_16x16x32_bf16 v[28:31], v[146:149], v[230:233], v[28:31]
	v_mfma_f32_16x16x32_bf16 v[20:23], v[154:157], v[230:233], v[20:23]
	v_mfma_f32_16x16x32_bf16 v[12:15], v[146:149], v[238:241], v[12:15]
	v_mfma_f32_16x16x32_bf16 v[4:7], v[154:157], v[238:241], v[4:7]
	v_mfma_f32_16x16x32_bf16 v[56:59], v[158:161], v[192:195], v[56:59]
	v_mfma_f32_16x16x32_bf16 v[48:51], v[184:187], v[192:195], v[48:51]
	v_mfma_f32_16x16x32_bf16 v[40:43], v[158:161], v[200:203], v[40:43]
	v_mfma_f32_16x16x32_bf16 v[32:35], v[184:187], v[200:203], v[32:35]
	v_mfma_f32_16x16x32_bf16 v[24:27], v[158:161], v[208:211], v[24:27]
	v_mfma_f32_16x16x32_bf16 v[16:19], v[184:187], v[208:211], v[16:19]
	v_mfma_f32_16x16x32_bf16 v[8:11], v[158:161], v[234:237], v[8:11]
	v_mfma_f32_16x16x32_bf16 v[0:3], v[184:187], v[234:237], v[0:3]
	v_mfma_f32_16x16x32_bf16 v[56:59], v[162:165], v[196:199], v[56:59]
	v_mfma_f32_16x16x32_bf16 v[48:51], v[188:191], v[196:199], v[48:51]
	v_mfma_f32_16x16x32_bf16 v[40:43], v[162:165], v[204:207], v[40:43]
	v_mfma_f32_16x16x32_bf16 v[32:35], v[188:191], v[204:207], v[32:35]
	v_mfma_f32_16x16x32_bf16 v[24:27], v[162:165], v[230:233], v[24:27]
	v_mfma_f32_16x16x32_bf16 v[16:19], v[188:191], v[230:233], v[16:19]
	v_mfma_f32_16x16x32_bf16 v[8:11], v[162:165], v[238:241], v[8:11]
	v_mfma_f32_16x16x32_bf16 v[0:3], v[188:191], v[238:241], v[0:3]
	s_barrier
	s_add_i32 s59, s59, 2
	s_add_u32 s34, s34, 0x100
	s_addc_u32 s35, s35, 0
	s_add_u32 s57, s57, 0x100
	s_addc_u32 s58, s58, 0
	s_cmp_gt_u32 s59, 29
	s_cbranch_scc0 .LBB0_161
	s_and_b64 vcc, exec, s[10:11]
	s_cbranch_vccz .LBB0_164
	s_barrier

; #define PG8_STAGE(bufoff, gbase, voff) do { _Pragma("unroll") for (int _i = 0; _i < 2; ++_i) \
;         __builtin_amdgcn_global_load_lds((const unsigned*)((const char*)(gbase) + (voff)[_i]), (LAS unsigned*)(lds + (bufoff) + ldsw + _i * 8192), 16, 0, 0); } while (0)
; #define PG8_LDA(dst, b, h) do { _Pragma("unroll") for (int m = 0; m < 4; ++m) _Pragma("unroll") for (int k = 0; k < 2; ++k) dst[m][k] = *(const LAS bf16x8*)(lds + PG8_SA(b, h) + aoff + m * 2048 + k * 1024); } while (0)
; #define PG8_LDB(dst, b, h) do { _Pragma("unroll") for (int n = 0; n < 2; ++n) _Pragma("unroll") for (int k = 0; k < 2; ++k) dst[n][k] = *(const LAS bf16x8*)(lds + PG8_SB(b, h) + boff + n * 2048 + k * 1024); } while (0)
; #define PG8_MMA(ai, bj, At, Bt) do { __builtin_amdgcn_s_setprio(1); _Pragma("unroll") for (int m = 0; m < 4; ++m) _Pragma("unroll") for (int n = 0; n < 2; ++n) _Pragma("unroll") for (int k = 0; k < 2; ++k) \
;         acc[ai][bj][m][n] = __builtin_amdgcn_mfma_f32_16x16x32_bf16(Bt[n][k], At[m][k], acc[ai][bj][m][n], 0, 0, 0); __builtin_amdgcn_s_setprio(0); } while (0)
; #define PG8_WAIT_V(n) asm volatile("s_waitcnt vmcnt(" #n ")" ::: "memory")
; #define PG8_WAIT_L(n) asm volatile("s_waitcnt lgkmcnt(" #n ")" ::: "memory")
; #define PG8_BAR __builtin_amdgcn_s_barrier()
; #define PG8_SCHED __builtin_amdgcn_sched_barrier(0)
; template <class Epi>
; __device__ __forceinline__ void gemm_phase(LAS unsigned char* lds, const Gemm g, const StaticOrder& S, const Epi& E, const int tid) {
;     ...
;             const char* a1 = cA + (size_t)(t + 1) * kstep;
;             const char* a2 = last ? nA : cA + (size_t)(t + 2) * kstep; const char* b2 = last ? nB : cB + (size_t)(t + 2) * kstep;
;             const char* a3 = a2 + kstep; const char* b3 = b2 + kstep;
;             PG8_LDB(B0, 0, 0); PG8_LDB(B1, 0, 1); PG8_SCHED; PG8_LDA(At, 0, 0); PG8_STAGE(PG8_SA(1, 1), a1 + hsA, voffA);
;             PG8_WAIT_V(8); PG8_WAIT_L(0); PG8_BAR; PG8_MMA(0, 0, At, B0); PG8_MMA(0, 1, At, B1); PG8_BAR; PG8_SCHED;
;             PG8_LDA(At, 0, 1); PG8_STAGE(PG8_SB(0, 0), b2, voffB); PG8_STAGE(PG8_SB(0, 1), b2 + hsB, voffB); PG8_STAGE(PG8_SA(0, 0), a2, voffA);
;             PG8_WAIT_V(8); PG8_WAIT_L(0); PG8_BAR; PG8_MMA(1, 0, At, B0); PG8_MMA(1, 1, At, B1); PG8_BAR; PG8_SCHED;
.Lgprio_b:
.LBB0_233:
	s_add_u32 s0, s18, 0x100
	s_addc_u32 s1, s19, 0
	s_add_i32 s24, 0, 0x10000
	s_cmpk_eq_i32 s69, 0x54
	s_cselect_b32 s37, s15, s1
	s_cselect_b32 s36, s14, s0
	s_cselect_b32 s35, s17, s43
	s_cselect_b32 s34, s16, s42
	s_add_i32 s25, 0, 0x14000
	v_add_u32_e32 v152, s24, v193
	v_add_u32_e32 v170, s25, v193
	ds_read_b128 v[128:131], v152
	ds_read_b128 v[132:135], v152 offset:1024
	ds_read_b128 v[136:139], v152 offset:2048
	ds_read_b128 v[152:155], v152 offset:3072
	ds_read_b128 v[156:159], v170
	ds_read_b128 v[160:163], v170 offset:1024
	ds_read_b128 v[164:167], v170 offset:2048
	ds_read_b128 v[184:187], v170 offset:3072
	v_lshl_add_u64 v[212:213], s[18:19], 0, v[148:149]
	s_add_i32 m0, s44, 0xc000
	ds_read_b128 v[188:191], v198
	ds_read_b128 v[200:203], v198 offset:1024
	ds_read_b128 v[204:207], v198 offset:2048
	ds_read_b128 v[208:211], v198 offset:3072
	ds_read_b128 v[230:233], v198 offset:4096
	ds_read_b128 v[234:237], v198 offset:5120
	ds_read_b128 v[238:241], v198 offset:6144
	ds_read_b128 v[242:245], v198 offset:7168
	global_load_lds_dwordx4 v[212:213], off
	v_lshl_add_u64 v[212:213], s[18:19], 0, v[150:151]
	s_add_i32 m0, s44, 0xe000
	s_nop 0
	global_load_lds_dwordx4 v[212:213], off
	s_waitcnt vmcnt(8)
	s_waitcnt lgkmcnt(0)
	s_barrier
	v_mfma_f32_16x16x32_bf16 v[124:127], v[128:131], v[188:191], v[124:127]
	v_mfma_f32_16x16x32_bf16 v[120:123], v[136:139], v[188:191], v[120:123]
	v_mfma_f32_16x16x32_bf16 v[116:119], v[128:131], v[204:207], v[116:119]
	v_mfma_f32_16x16x32_bf16 v[108:111], v[136:139], v[204:207], v[108:111]
	v_mfma_f32_16x16x32_bf16 v[92:95], v[128:131], v[230:233], v[92:95]
	v_mfma_f32_16x16x32_bf16 v[88:91], v[136:139], v[230:233], v[88:91]
	v_mfma_f32_16x16x32_bf16 v[80:83], v[128:131], v[238:241], v[80:83]
	v_mfma_f32_16x16x32_bf16 v[72:75], v[136:139], v[238:241], v[72:75]
	v_mfma_f32_16x16x32_bf16 v[124:127], v[132:135], v[200:203], v[124:127]
	v_mfma_f32_16x16x32_bf16 v[120:123], v[152:155], v[200:203], v[120:123]
	v_mfma_f32_16x16x32_bf16 v[116:119], v[132:135], v[208:211], v[116:119]
	v_mfma_f32_16x16x32_bf16 v[108:111], v[152:155], v[208:211], v[108:111]
	v_mfma_f32_16x16x32_bf16 v[92:95], v[132:135], v[234:237], v[92:95]
	v_mfma_f32_16x16x32_bf16 v[88:91], v[152:155], v[234:237], v[88:91]
	v_mfma_f32_16x16x32_bf16 v[80:83], v[132:135], v[242:245], v[80:83]
	v_mfma_f32_16x16x32_bf16 v[72:75], v[152:155], v[242:245], v[72:75]
	v_mfma_f32_16x16x32_bf16 v[112:115], v[156:159], v[188:191], v[112:115]
	v_mfma_f32_16x16x32_bf16 v[104:107], v[164:167], v[188:191], v[104:107]
	v_mfma_f32_16x16x32_bf16 v[100:103], v[156:159], v[204:207], v[100:103]
	v_mfma_f32_16x16x32_bf16 v[96:99], v[164:167], v[204:207], v[96:99]
	v_mfma_f32_16x16x32_bf16 v[84:87], v[156:159], v[230:233], v[84:87]
	v_mfma_f32_16x16x32_bf16 v[76:79], v[164:167], v[230:233], v[76:79]
	v_mfma_f32_16x16x32_bf16 v[68:71], v[156:159], v[238:241], v[68:71]
	v_mfma_f32_16x16x32_bf16 v[64:67], v[164:167], v[238:241], v[64:67]
	v_mfma_f32_16x16x32_bf16 v[112:115], v[160:163], v[200:203], v[112:115]
	v_mfma_f32_16x16x32_bf16 v[104:107], v[184:187], v[200:203], v[104:107]
	v_mfma_f32_16x16x32_bf16 v[100:103], v[160:163], v[208:211], v[100:103]
	v_mfma_f32_16x16x32_bf16 v[96:99], v[184:187], v[208:211], v[96:99]
	v_mfma_f32_16x16x32_bf16 v[84:87], v[160:163], v[234:237], v[84:87]
	v_mfma_f32_16x16x32_bf16 v[76:79], v[184:187], v[234:237], v[76:79]
	v_mfma_f32_16x16x32_bf16 v[68:71], v[160:163], v[242:245], v[68:71]
	v_mfma_f32_16x16x32_bf16 v[64:67], v[184:187], v[242:245], v[64:67]
	s_barrier
	s_add_i32 s18, s24, s39
	v_lshl_add_u64 v[212:213], s[34:35], 0, v[144:145]
	s_mov_b32 m0, s18
	ds_read_b128 v[188:191], v198 offset:16384
	ds_read_b128 v[200:203], v198 offset:17408
	ds_read_b128 v[204:207], v198 offset:18432
	ds_read_b128 v[208:211], v198 offset:19456
	ds_read_b128 v[230:233], v198 offset:20480
	ds_read_b128 v[234:237], v198 offset:21504
	ds_read_b128 v[238:241], v198 offset:22528
	ds_read_b128 v[242:245], v198 offset:23552
	global_load_lds_dwordx4 v[212:213], off
	s_add_i32 m0, s18, 0x2000
	s_add_u32 s18, s34, 0x160000
	v_lshl_add_u64 v[246:247], s[34:35], 0, v[140:141]
	s_addc_u32 s19, s35, 0
	s_add_i32 s24, s25, s39
	global_load_lds_dwordx4 v[246:247], off
	v_lshl_add_u64 v[248:249], s[18:19], 0, v[144:145]
	s_mov_b32 m0, s24
	v_lshl_add_u64 v[250:251], s[36:37], 0, v[142:143]
	global_load_lds_dwordx4 v[248:249], off
	v_lshl_add_u64 v[248:249], s[18:19], 0, v[140:141]
	s_add_i32 m0, s24, 0x2000
	s_nop 0
	global_load_lds_dwordx4 v[248:249], off
	v_lshl_add_u64 v[248:249], s[36:37], 0, v[146:147]
	s_mov_b32 m0, s44
	s_nop 0
	global_load_lds_dwordx4 v[248:249], off
	s_mov_b32 m0, s45
	s_nop 0
	global_load_lds_dwordx4 v[250:251], off
	s_waitcnt vmcnt(8)
	s_waitcnt lgkmcnt(0)
	s_barrier
; #define PG8_STAGE(bufoff, gbase, voff) do { _Pragma("unroll") for (int _i = 0; _i < 2; ++_i) \
;         __builtin_amdgcn_global_load_lds((const unsigned*)((const char*)(gbase) + (voff)[_i]), (LAS unsigned*)(lds + (bufoff) + ldsw + _i * 8192), 16, 0, 0); } while (0)
; #define PG8_LDA(dst, b, h) do { _Pragma("unroll") for (int m = 0; m < 4; ++m) _Pragma("unroll") for (int k = 0; k < 2; ++k) dst[m][k] = *(const LAS bf16x8*)(lds + PG8_SA(b, h) + aoff + m * 2048 + k * 1024); } while (0)
; #define PG8_LDB(dst, b, h) do { _Pragma("unroll") for (int n = 0; n < 2; ++n) _Pragma("unroll") for (int k = 0; k < 2; ++k) dst[n][k] = *(const LAS bf16x8*)(lds + PG8_SB(b, h) + boff + n * 2048 + k * 1024); } while (0)
; #define PG8_MMA(ai, bj, At, Bt) do { __builtin_amdgcn_s_setprio(1); _Pragma("unroll") for (int m = 0; m < 4; ++m) _Pragma("unroll") for (int n = 0; n < 2; ++n) _Pragma("unroll") for (int k = 0; k < 2; ++k) \
;         acc[ai][bj][m][n] = __builtin_amdgcn_mfma_f32_16x16x32_bf16(Bt[n][k], At[m][k], acc[ai][bj][m][n], 0, 0, 0); __builtin_amdgcn_s_setprio(0); } while (0)
; #define PG8_WAIT_V(n) asm volatile("s_waitcnt vmcnt(" #n ")" ::: "memory")
; #define PG8_WAIT_L(n) asm volatile("s_waitcnt lgkmcnt(" #n ")" ::: "memory")
; #define PG8_BAR __builtin_amdgcn_s_barrier()
; #define PG8_SCHED __builtin_amdgcn_sched_barrier(0)
; template <class Epi>
; __device__ __forceinline__ void gemm_phase(LAS unsigned char* lds, const Gemm g, const StaticOrder& S, const Epi& E, const int tid) {
;     ...
;             PG8_WAIT_V(8); PG8_WAIT_L(0); PG8_BAR; PG8_MMA(1, 0, At, B0); PG8_MMA(1, 1, At, B1); PG8_BAR; PG8_SCHED;
;             PG8_LDB(B0, 1, 0); PG8_LDB(B1, 1, 1); PG8_SCHED; PG8_LDA(At, 1, 0); PG8_STAGE(PG8_SA(0, 1), a2 + hsA, voffA);
;             PG8_WAIT_V(8); PG8_WAIT_L(0); PG8_BAR; PG8_MMA(0, 0, At, B0); PG8_MMA(0, 1, At, B1); PG8_BAR; PG8_SCHED;
	v_mfma_f32_16x16x32_bf16 v[60:63], v[128:131], v[188:191], v[60:63]
	v_mfma_f32_16x16x32_bf16 v[56:59], v[136:139], v[188:191], v[56:59]
	v_mfma_f32_16x16x32_bf16 v[44:47], v[128:131], v[204:207], v[44:47]
	v_mfma_f32_16x16x32_bf16 v[40:43], v[136:139], v[204:207], v[40:43]
	v_mfma_f32_16x16x32_bf16 v[28:31], v[128:131], v[230:233], v[28:31]
	v_mfma_f32_16x16x32_bf16 v[24:27], v[136:139], v[230:233], v[24:27]
	v_mfma_f32_16x16x32_bf16 v[12:15], v[128:131], v[238:241], v[12:15]
	v_mfma_f32_16x16x32_bf16 v[8:11], v[136:139], v[238:241], v[8:11]
	v_mfma_f32_16x16x32_bf16 v[60:63], v[132:135], v[200:203], v[60:63]
	v_mfma_f32_16x16x32_bf16 v[56:59], v[152:155], v[200:203], v[56:59]
	v_mfma_f32_16x16x32_bf16 v[44:47], v[132:135], v[208:211], v[44:47]
	v_mfma_f32_16x16x32_bf16 v[40:43], v[152:155], v[208:211], v[40:43]
	v_mfma_f32_16x16x32_bf16 v[28:31], v[132:135], v[234:237], v[28:31]
	v_mfma_f32_16x16x32_bf16 v[24:27], v[152:155], v[234:237], v[24:27]
	v_mfma_f32_16x16x32_bf16 v[12:15], v[132:135], v[242:245], v[12:15]
	v_mfma_f32_16x16x32_bf16 v[8:11], v[152:155], v[242:245], v[8:11]
	v_mfma_f32_16x16x32_bf16 v[52:55], v[156:159], v[188:191], v[52:55]
	v_mfma_f32_16x16x32_bf16 v[48:51], v[164:167], v[188:191], v[48:51]
	v_mfma_f32_16x16x32_bf16 v[36:39], v[156:159], v[204:207], v[36:39]
	v_mfma_f32_16x16x32_bf16 v[32:35], v[164:167], v[204:207], v[32:35]
	v_mfma_f32_16x16x32_bf16 v[20:23], v[156:159], v[230:233], v[20:23]
	v_mfma_f32_16x16x32_bf16 v[16:19], v[164:167], v[230:233], v[16:19]
	v_mfma_f32_16x16x32_bf16 v[4:7], v[156:159], v[238:241], v[4:7]
	v_mfma_f32_16x16x32_bf16 v[0:3], v[164:167], v[238:241], v[0:3]
	v_mfma_f32_16x16x32_bf16 v[52:55], v[160:163], v[200:203], v[52:55]
	v_mfma_f32_16x16x32_bf16 v[48:51], v[184:187], v[200:203], v[48:51]
	v_mfma_f32_16x16x32_bf16 v[36:39], v[160:163], v[208:211], v[36:39]
	v_mfma_f32_16x16x32_bf16 v[32:35], v[184:187], v[208:211], v[32:35]
	v_mfma_f32_16x16x32_bf16 v[20:23], v[160:163], v[234:237], v[20:23]
	v_mfma_f32_16x16x32_bf16 v[16:19], v[184:187], v[234:237], v[16:19]
	v_mfma_f32_16x16x32_bf16 v[4:7], v[160:163], v[242:245], v[4:7]
	v_mfma_f32_16x16x32_bf16 v[0:3], v[184:187], v[242:245], v[0:3]
	s_barrier
	s_add_i32 s24, 0, 0x18000
	s_add_i32 s25, 0, 0x1c000
	v_add_u32_e32 v152, s24, v193
	v_add_u32_e32 v170, s25, v193
	ds_read_b128 v[128:131], v152
	ds_read_b128 v[132:135], v152 offset:1024
	ds_read_b128 v[136:139], v152 offset:2048
	ds_read_b128 v[152:155], v152 offset:3072
	ds_read_b128 v[156:159], v170
	ds_read_b128 v[160:163], v170 offset:1024
	ds_read_b128 v[164:167], v170 offset:2048
	ds_read_b128 v[184:187], v170 offset:3072
	s_add_u32 s18, s36, 0x160000
	s_addc_u32 s19, s37, 0
	s_mov_b32 m0, s46
	v_lshl_add_u64 v[170:171], s[18:19], 0, v[146:147]
	ds_read_b128 v[188:191], v198 offset:32768
	ds_read_b128 v[200:203], v198 offset:33792
	ds_read_b128 v[204:207], v198 offset:34816
	ds_read_b128 v[208:211], v198 offset:35840
	ds_read_b128 v[230:233], v198 offset:36864
	ds_read_b128 v[234:237], v198 offset:37888
	ds_read_b128 v[238:241], v198 offset:38912
	ds_read_b128 v[242:245], v198 offset:39936
	global_load_lds_dwordx4 v[170:171], off
	v_lshl_add_u64 v[170:171], s[18:19], 0, v[142:143]
	s_mov_b32 m0, s47
	s_nop 0
	global_load_lds_dwordx4 v[170:171], off
	s_waitcnt vmcnt(8)
	s_waitcnt lgkmcnt(0)
	s_barrier
	v_mfma_f32_16x16x32_bf16 v[124:127], v[128:131], v[188:191], v[124:127]
	v_mfma_f32_16x16x32_bf16 v[120:123], v[136:139], v[188:191], v[120:123]
	v_mfma_f32_16x16x32_bf16 v[116:119], v[128:131], v[204:207], v[116:119]
	v_mfma_f32_16x16x32_bf16 v[108:111], v[136:139], v[204:207], v[108:111]
	v_mfma_f32_16x16x32_bf16 v[92:95], v[128:131], v[230:233], v[92:95]
	v_mfma_f32_16x16x32_bf16 v[88:91], v[136:139], v[230:233], v[88:91]
	v_mfma_f32_16x16x32_bf16 v[80:83], v[128:131], v[238:241], v[80:83]
	v_mfma_f32_16x16x32_bf16 v[72:75], v[136:139], v[238:241], v[72:75]
	v_mfma_f32_16x16x32_bf16 v[124:127], v[132:135], v[200:203], v[124:127]
	v_mfma_f32_16x16x32_bf16 v[120:123], v[152:155], v[200:203], v[120:123]
	v_mfma_f32_16x16x32_bf16 v[116:119], v[132:135], v[208:211], v[116:119]
	v_mfma_f32_16x16x32_bf16 v[108:111], v[152:155], v[208:211], v[108:111]
	v_mfma_f32_16x16x32_bf16 v[92:95], v[132:135], v[234:237], v[92:95]
	v_mfma_f32_16x16x32_bf16 v[88:91], v[152:155], v[234:237], v[88:91]
	v_mfma_f32_16x16x32_bf16 v[80:83], v[132:135], v[242:245], v[80:83]
	v_mfma_f32_16x16x32_bf16 v[72:75], v[152:155], v[242:245], v[72:75]
	v_mfma_f32_16x16x32_bf16 v[112:115], v[156:159], v[188:191], v[112:115]
	v_mfma_f32_16x16x32_bf16 v[104:107], v[164:167], v[188:191], v[104:107]
	v_mfma_f32_16x16x32_bf16 v[100:103], v[156:159], v[204:207], v[100:103]
	v_mfma_f32_16x16x32_bf16 v[96:99], v[164:167], v[204:207], v[96:99]
	v_mfma_f32_16x16x32_bf16 v[84:87], v[156:159], v[230:233], v[84:87]
	v_mfma_f32_16x16x32_bf16 v[76:79], v[164:167], v[230:233], v[76:79]
	v_mfma_f32_16x16x32_bf16 v[68:71], v[156:159], v[238:241], v[68:71]
	v_mfma_f32_16x16x32_bf16 v[64:67], v[164:167], v[238:241], v[64:67]
	v_mfma_f32_16x16x32_bf16 v[112:115], v[160:163], v[200:203], v[112:115]
	v_mfma_f32_16x16x32_bf16 v[104:107], v[184:187], v[200:203], v[104:107]
	v_mfma_f32_16x16x32_bf16 v[100:103], v[160:163], v[208:211], v[100:103]
	v_mfma_f32_16x16x32_bf16 v[96:99], v[184:187], v[208:211], v[96:99]
	v_mfma_f32_16x16x32_bf16 v[84:87], v[160:163], v[234:237], v[84:87]
	v_mfma_f32_16x16x32_bf16 v[76:79], v[184:187], v[234:237], v[76:79]
	v_mfma_f32_16x16x32_bf16 v[68:71], v[160:163], v[242:245], v[68:71]
	v_mfma_f32_16x16x32_bf16 v[64:67], v[184:187], v[242:245], v[64:67]
	s_barrier
; #define PG8_STAGE(bufoff, gbase, voff) do { _Pragma("unroll") for (int _i = 0; _i < 2; ++_i) \
;         __builtin_amdgcn_global_load_lds((const unsigned*)((const char*)(gbase) + (voff)[_i]), (LAS unsigned*)(lds + (bufoff) + ldsw + _i * 8192), 16, 0, 0); } while (0)
; #define PG8_LDA(dst, b, h) do { _Pragma("unroll") for (int m = 0; m < 4; ++m) _Pragma("unroll") for (int k = 0; k < 2; ++k) dst[m][k] = *(const LAS bf16x8*)(lds + PG8_SA(b, h) + aoff + m * 2048 + k * 1024); } while (0)
; #define PG8_MMA(ai, bj, At, Bt) do { __builtin_amdgcn_s_setprio(1); _Pragma("unroll") for (int m = 0; m < 4; ++m) _Pragma("unroll") for (int n = 0; n < 2; ++n) _Pragma("unroll") for (int k = 0; k < 2; ++k) \
;         acc[ai][bj][m][n] = __builtin_amdgcn_mfma_f32_16x16x32_bf16(Bt[n][k], At[m][k], acc[ai][bj][m][n], 0, 0, 0); __builtin_amdgcn_s_setprio(0); } while (0)
; #define PG8_WAIT_V(n) asm volatile("s_waitcnt vmcnt(" #n ")" ::: "memory")
; #define PG8_WAIT_L(n) asm volatile("s_waitcnt lgkmcnt(" #n ")" ::: "memory")
; #define PG8_BAR __builtin_amdgcn_s_barrier()
; #define PG8_SCHED __builtin_amdgcn_sched_barrier(0)
; template <class Epi>
; __device__ __forceinline__ void gemm_phase(LAS unsigned char* lds, const Gemm g, const StaticOrder& S, const Epi& E, const int tid) {
;     ...
;             PG8_LDA(At, 1, 1); PG8_STAGE(PG8_SB(1, 0), b3, voffB); PG8_STAGE(PG8_SB(1, 1), b3 + hsB, voffB); PG8_STAGE(PG8_SA(1, 0), a3, voffA);
;             PG8_WAIT_V(8); PG8_WAIT_L(0); PG8_BAR; PG8_MMA(1, 0, At, B0); PG8_MMA(1, 1, At, B1); PG8_BAR; PG8_SCHED;
;         }
;         if (wr == 0) PG8_BAR;
	s_add_i32 s18, s24, s39
	v_lshl_add_u64 v[170:171], v[212:213], 0, s[28:29]
	s_mov_b32 m0, s18
	ds_read_b128 v[188:191], v198 offset:49152
	ds_read_b128 v[200:203], v198 offset:50176
	ds_read_b128 v[204:207], v198 offset:51200
	ds_read_b128 v[208:211], v198 offset:52224
	ds_read_b128 v[230:233], v198 offset:53248
	ds_read_b128 v[234:237], v198 offset:54272
	ds_read_b128 v[238:241], v198 offset:55296
	ds_read_b128 v[242:245], v198 offset:56320
	global_load_lds_dwordx4 v[170:171], off
	s_add_i32 m0, s18, 0x2000
	s_add_u32 s18, s34, 0x160080
	v_lshl_add_u64 v[170:171], v[246:247], 0, s[28:29]
	s_addc_u32 s19, s35, 0
	s_add_i32 s24, s25, s39
	global_load_lds_dwordx4 v[170:171], off
	v_lshl_add_u64 v[170:171], s[18:19], 0, v[144:145]
	s_mov_b32 m0, s24
	s_nop 0
	global_load_lds_dwordx4 v[170:171], off
	v_lshl_add_u64 v[170:171], s[18:19], 0, v[140:141]
	s_add_i32 m0, s24, 0x2000
	s_nop 0
	global_load_lds_dwordx4 v[170:171], off
	v_lshl_add_u64 v[170:171], v[248:249], 0, s[28:29]
	s_mov_b32 m0, s56
	s_nop 0
	global_load_lds_dwordx4 v[170:171], off
	v_lshl_add_u64 v[170:171], v[250:251], 0, s[28:29]
	s_mov_b32 m0, s57
	s_nop 0
	global_load_lds_dwordx4 v[170:171], off
	s_waitcnt vmcnt(8)
	s_waitcnt lgkmcnt(0)
	s_barrier
	v_mfma_f32_16x16x32_bf16 v[60:63], v[128:131], v[188:191], v[60:63]
	v_mfma_f32_16x16x32_bf16 v[56:59], v[136:139], v[188:191], v[56:59]
	v_mfma_f32_16x16x32_bf16 v[44:47], v[128:131], v[204:207], v[44:47]
	v_mfma_f32_16x16x32_bf16 v[40:43], v[136:139], v[204:207], v[40:43]
	v_mfma_f32_16x16x32_bf16 v[28:31], v[128:131], v[230:233], v[28:31]
	v_mfma_f32_16x16x32_bf16 v[24:27], v[136:139], v[230:233], v[24:27]
	v_mfma_f32_16x16x32_bf16 v[12:15], v[128:131], v[238:241], v[12:15]
	v_mfma_f32_16x16x32_bf16 v[8:11], v[136:139], v[238:241], v[8:11]
	v_mfma_f32_16x16x32_bf16 v[60:63], v[132:135], v[200:203], v[60:63]
	v_mfma_f32_16x16x32_bf16 v[56:59], v[152:155], v[200:203], v[56:59]
	v_mfma_f32_16x16x32_bf16 v[44:47], v[132:135], v[208:211], v[44:47]
	v_mfma_f32_16x16x32_bf16 v[40:43], v[152:155], v[208:211], v[40:43]
	v_mfma_f32_16x16x32_bf16 v[28:31], v[132:135], v[234:237], v[28:31]
	v_mfma_f32_16x16x32_bf16 v[24:27], v[152:155], v[234:237], v[24:27]
	v_mfma_f32_16x16x32_bf16 v[12:15], v[132:135], v[242:245], v[12:15]
	v_mfma_f32_16x16x32_bf16 v[8:11], v[152:155], v[242:245], v[8:11]
	v_mfma_f32_16x16x32_bf16 v[52:55], v[156:159], v[188:191], v[52:55]
	v_mfma_f32_16x16x32_bf16 v[48:51], v[164:167], v[188:191], v[48:51]
	v_mfma_f32_16x16x32_bf16 v[36:39], v[156:159], v[204:207], v[36:39]
	v_mfma_f32_16x16x32_bf16 v[32:35], v[164:167], v[204:207], v[32:35]
	v_mfma_f32_16x16x32_bf16 v[20:23], v[156:159], v[230:233], v[20:23]
	v_mfma_f32_16x16x32_bf16 v[16:19], v[164:167], v[230:233], v[16:19]
	v_mfma_f32_16x16x32_bf16 v[4:7], v[156:159], v[238:241], v[4:7]
	v_mfma_f32_16x16x32_bf16 v[0:3], v[164:167], v[238:241], v[0:3]
	v_mfma_f32_16x16x32_bf16 v[52:55], v[160:163], v[200:203], v[52:55]
	v_mfma_f32_16x16x32_bf16 v[48:51], v[184:187], v[200:203], v[48:51]
	v_mfma_f32_16x16x32_bf16 v[36:39], v[160:163], v[208:211], v[36:39]
	v_mfma_f32_16x16x32_bf16 v[32:35], v[184:187], v[208:211], v[32:35]
	v_mfma_f32_16x16x32_bf16 v[20:23], v[160:163], v[234:237], v[20:23]
	v_mfma_f32_16x16x32_bf16 v[16:19], v[184:187], v[234:237], v[16:19]
	v_mfma_f32_16x16x32_bf16 v[4:7], v[160:163], v[242:245], v[4:7]
	v_mfma_f32_16x16x32_bf16 v[0:3], v[184:187], v[242:245], v[0:3]
	s_barrier
	s_add_i32 s69, s69, 2
	s_add_u32 s42, s42, 0x100
	s_addc_u32 s43, s43, 0
	s_cmpk_gt_u32 s69, 0x55
	s_mov_b64 s[18:19], s[0:1]
	s_cbranch_scc0 .LBB0_233
	s_and_b64 vcc, exec, s[10:11]
	s_cbranch_vccz .LBB0_236
	s_barrier

; #define PG8_STAGE(bufoff, gbase, voff) do { _Pragma("unroll") for (int _i = 0; _i < 2; ++_i) \
;         __builtin_amdgcn_global_load_lds((const unsigned*)((const char*)(gbase) + (voff)[_i]), (LAS unsigned*)(lds + (bufoff) + ldsw + _i * 8192), 16, 0, 0); } while (0)
; #define PG8_LDA(dst, b, h) do { _Pragma("unroll") for (int m = 0; m < 4; ++m) _Pragma("unroll") for (int k = 0; k < 2; ++k) dst[m][k] = *(const LAS bf16x8*)(lds + PG8_SA(b, h) + aoff + m * 2048 + k * 1024); } while (0)
; #define PG8_LDB(dst, b, h) do { _Pragma("unroll") for (int n = 0; n < 2; ++n) _Pragma("unroll") for (int k = 0; k < 2; ++k) dst[n][k] = *(const LAS bf16x8*)(lds + PG8_SB(b, h) + boff + n * 2048 + k * 1024); } while (0)
; #define PG8_MMA(ai, bj, At, Bt) do { __builtin_amdgcn_s_setprio(1); _Pragma("unroll") for (int m = 0; m < 4; ++m) _Pragma("unroll") for (int n = 0; n < 2; ++n) _Pragma("unroll") for (int k = 0; k < 2; ++k) \
;         acc[ai][bj][m][n] = __builtin_amdgcn_mfma_f32_16x16x32_bf16(Bt[n][k], At[m][k], acc[ai][bj][m][n], 0, 0, 0); __builtin_amdgcn_s_setprio(0); } while (0)
; #define PG8_WAIT_V(n) asm volatile("s_waitcnt vmcnt(" #n ")" ::: "memory")
; #define PG8_WAIT_L(n) asm volatile("s_waitcnt lgkmcnt(" #n ")" ::: "memory")
; #define PG8_BAR __builtin_amdgcn_s_barrier()
; #define PG8_SCHED __builtin_amdgcn_sched_barrier(0)
; template <class Epi>
; __device__ __forceinline__ void gemm_phase(LAS unsigned char* lds, const Gemm g, const StaticOrder& S, const Epi& E, const int tid) {
;     ...
;             const char* a1 = cA + (size_t)(t + 1) * kstep;
;             const char* a2 = last ? nA : cA + (size_t)(t + 2) * kstep; const char* b2 = last ? nB : cB + (size_t)(t + 2) * kstep;
;             const char* a3 = a2 + kstep; const char* b3 = b2 + kstep;
;             PG8_LDB(B0, 0, 0); PG8_LDB(B1, 0, 1); PG8_SCHED; PG8_LDA(At, 0, 0); PG8_STAGE(PG8_SA(1, 1), a1 + hsA, voffA);
;             PG8_WAIT_V(8); PG8_WAIT_L(0); PG8_BAR; PG8_MMA(0, 0, At, B0); PG8_MMA(0, 1, At, B1); PG8_BAR; PG8_SCHED;
;             PG8_LDA(At, 0, 1); PG8_STAGE(PG8_SB(0, 0), b2, voffB); PG8_STAGE(PG8_SB(0, 1), b2 + hsB, voffB); PG8_STAGE(PG8_SA(0, 0), a2, voffA);
;             PG8_WAIT_V(8); PG8_WAIT_L(0); PG8_BAR; PG8_MMA(1, 0, At, B0); PG8_MMA(1, 1, At, B1); PG8_BAR; PG8_SCHED;
.Lgprio_c:
.LBB0_354:
	s_add_u32 s0, s36, 0xfff80080
	s_addc_u32 s1, s37, -1
	s_add_i32 s24, 0, 0x10000
	s_cmp_eq_u32 vcc_hi, 28
	s_cselect_b32 s43, s10, s1
	s_cselect_b32 s42, s11, s0
	v_add_u32_e32 v143, s24, v163
	s_cselect_b32 s1, s47, vcc_lo
	s_cselect_b32 s0, s49, s69
	s_add_i32 s55, 0, 0x14000
	ds_read_b128 v[144:147], v143
	ds_read_b128 v[148:151], v143 offset:1024
	ds_read_b128 v[152:155], v143 offset:2048
	ds_read_b128 v[156:159], v143 offset:3072
	v_add_u32_e32 v143, s55, v163
	ds_read_b128 v[184:187], v143
	ds_read_b128 v[188:191], v143 offset:1024
	ds_read_b128 v[192:195], v143 offset:2048
	ds_read_b128 v[196:199], v143 offset:3072
	v_lshl_add_u64 v[160:161], s[36:37], 0, v[138:139]
	s_add_i32 m0, s58, 0xc000
	ds_read_b128 v[200:203], v165
	ds_read_b128 v[204:207], v165 offset:1024
	ds_read_b128 v[208:211], v165 offset:2048
	ds_read_b128 v[232:235], v165 offset:3072
	ds_read_b128 v[236:239], v165 offset:4096
	ds_read_b128 v[240:243], v165 offset:5120
	ds_read_b128 v[244:247], v165 offset:6144
	ds_read_b128 v[248:251], v165 offset:7168
	global_load_lds_dwordx4 v[160:161], off
	v_lshl_add_u64 v[160:161], s[36:37], 0, v[140:141]
	s_add_i32 m0, s58, 0xe000
	s_nop 0
	global_load_lds_dwordx4 v[160:161], off
	s_waitcnt vmcnt(8)
	s_waitcnt lgkmcnt(0)
	s_barrier
	v_mfma_f32_16x16x32_bf16 v[124:127], v[144:147], v[200:203], v[124:127]
	v_mfma_f32_16x16x32_bf16 v[120:123], v[152:155], v[200:203], v[120:123]
	v_mfma_f32_16x16x32_bf16 v[108:111], v[144:147], v[208:211], v[108:111]
	v_mfma_f32_16x16x32_bf16 v[104:107], v[152:155], v[208:211], v[104:107]
	v_mfma_f32_16x16x32_bf16 v[92:95], v[144:147], v[236:239], v[92:95]
	v_mfma_f32_16x16x32_bf16 v[88:91], v[152:155], v[236:239], v[88:91]
	v_mfma_f32_16x16x32_bf16 v[76:79], v[144:147], v[244:247], v[76:79]
	v_mfma_f32_16x16x32_bf16 v[72:75], v[152:155], v[244:247], v[72:75]
	v_mfma_f32_16x16x32_bf16 v[124:127], v[148:151], v[204:207], v[124:127]
	v_mfma_f32_16x16x32_bf16 v[120:123], v[156:159], v[204:207], v[120:123]
	v_mfma_f32_16x16x32_bf16 v[108:111], v[148:151], v[232:235], v[108:111]
	v_mfma_f32_16x16x32_bf16 v[104:107], v[156:159], v[232:235], v[104:107]
	v_mfma_f32_16x16x32_bf16 v[92:95], v[148:151], v[240:243], v[92:95]
	v_mfma_f32_16x16x32_bf16 v[88:91], v[156:159], v[240:243], v[88:91]
	v_mfma_f32_16x16x32_bf16 v[76:79], v[148:151], v[248:251], v[76:79]
	v_mfma_f32_16x16x32_bf16 v[72:75], v[156:159], v[248:251], v[72:75]
	v_mfma_f32_16x16x32_bf16 v[116:119], v[184:187], v[200:203], v[116:119]
	v_mfma_f32_16x16x32_bf16 v[112:115], v[192:195], v[200:203], v[112:115]
	v_mfma_f32_16x16x32_bf16 v[100:103], v[184:187], v[208:211], v[100:103]
	v_mfma_f32_16x16x32_bf16 v[96:99], v[192:195], v[208:211], v[96:99]
	v_mfma_f32_16x16x32_bf16 v[84:87], v[184:187], v[236:239], v[84:87]
	v_mfma_f32_16x16x32_bf16 v[80:83], v[192:195], v[236:239], v[80:83]
	v_mfma_f32_16x16x32_bf16 v[68:71], v[184:187], v[244:247], v[68:71]
	v_mfma_f32_16x16x32_bf16 v[64:67], v[192:195], v[244:247], v[64:67]
	v_mfma_f32_16x16x32_bf16 v[116:119], v[188:191], v[204:207], v[116:119]
	v_mfma_f32_16x16x32_bf16 v[112:115], v[196:199], v[204:207], v[112:115]
	v_mfma_f32_16x16x32_bf16 v[100:103], v[188:191], v[232:235], v[100:103]
	v_mfma_f32_16x16x32_bf16 v[96:99], v[196:199], v[232:235], v[96:99]
	v_mfma_f32_16x16x32_bf16 v[84:87], v[188:191], v[240:243], v[84:87]
	v_mfma_f32_16x16x32_bf16 v[80:83], v[196:199], v[240:243], v[80:83]
	v_mfma_f32_16x16x32_bf16 v[68:71], v[188:191], v[248:251], v[68:71]
	v_mfma_f32_16x16x32_bf16 v[64:67], v[196:199], v[248:251], v[64:67]
	s_barrier
	s_add_i32 s24, s24, s57
	v_lshl_add_u64 v[160:161], s[0:1], 0, v[132:133]
	s_mov_b32 m0, s24
	ds_read_b128 v[200:203], v165 offset:16384
	ds_read_b128 v[204:207], v165 offset:17408
	ds_read_b128 v[208:211], v165 offset:18432
	ds_read_b128 v[232:235], v165 offset:19456
	ds_read_b128 v[236:239], v165 offset:20480
	ds_read_b128 v[240:243], v165 offset:21504
	ds_read_b128 v[244:247], v165 offset:22528
	ds_read_b128 v[248:251], v165 offset:23552
	global_load_lds_dwordx4 v[160:161], off
	s_add_i32 m0, s24, 0x2000
	s_add_u32 s24, s0, 0x80000
	v_lshl_add_u64 v[166:167], s[0:1], 0, v[128:129]
	s_addc_u32 s25, s1, 0
	s_add_i32 s55, s55, s57
	global_load_lds_dwordx4 v[166:167], off
	v_lshl_add_u64 v[170:171], s[24:25], 0, v[132:133]
	s_mov_b32 m0, s55
	v_lshl_add_u64 v[212:213], s[42:43], 0, v[130:131]
	global_load_lds_dwordx4 v[170:171], off
	v_lshl_add_u64 v[170:171], s[24:25], 0, v[128:129]
	s_add_i32 m0, s55, 0x2000
	s_nop 0
	global_load_lds_dwordx4 v[170:171], off
	v_lshl_add_u64 v[170:171], s[42:43], 0, v[134:135]
	s_mov_b32 m0, s58
	s_nop 0
	global_load_lds_dwordx4 v[170:171], off
	s_mov_b32 m0, s59
	s_nop 0
	global_load_lds_dwordx4 v[212:213], off
	s_waitcnt vmcnt(8)
	s_waitcnt lgkmcnt(0)
	s_barrier
; #define PG8_STAGE(bufoff, gbase, voff) do { _Pragma("unroll") for (int _i = 0; _i < 2; ++_i) \
;         __builtin_amdgcn_global_load_lds((const unsigned*)((const char*)(gbase) + (voff)[_i]), (LAS unsigned*)(lds + (bufoff) + ldsw + _i * 8192), 16, 0, 0); } while (0)
; #define PG8_LDA(dst, b, h) do { _Pragma("unroll") for (int m = 0; m < 4; ++m) _Pragma("unroll") for (int k = 0; k < 2; ++k) dst[m][k] = *(const LAS bf16x8*)(lds + PG8_SA(b, h) + aoff + m * 2048 + k * 1024); } while (0)
; #define PG8_LDB(dst, b, h) do { _Pragma("unroll") for (int n = 0; n < 2; ++n) _Pragma("unroll") for (int k = 0; k < 2; ++k) dst[n][k] = *(const LAS bf16x8*)(lds + PG8_SB(b, h) + boff + n * 2048 + k * 1024); } while (0)
; #define PG8_MMA(ai, bj, At, Bt) do { __builtin_amdgcn_s_setprio(1); _Pragma("unroll") for (int m = 0; m < 4; ++m) _Pragma("unroll") for (int n = 0; n < 2; ++n) _Pragma("unroll") for (int k = 0; k < 2; ++k) \
;         acc[ai][bj][m][n] = __builtin_amdgcn_mfma_f32_16x16x32_bf16(Bt[n][k], At[m][k], acc[ai][bj][m][n], 0, 0, 0); __builtin_amdgcn_s_setprio(0); } while (0)
; #define PG8_WAIT_V(n) asm volatile("s_waitcnt vmcnt(" #n ")" ::: "memory")
; #define PG8_WAIT_L(n) asm volatile("s_waitcnt lgkmcnt(" #n ")" ::: "memory")
; #define PG8_BAR __builtin_amdgcn_s_barrier()
; #define PG8_SCHED __builtin_amdgcn_sched_barrier(0)
; template <class Epi>
; __device__ __forceinline__ void gemm_phase(LAS unsigned char* lds, const Gemm g, const StaticOrder& S, const Epi& E, const int tid) {
;     ...
;             PG8_WAIT_V(8); PG8_WAIT_L(0); PG8_BAR; PG8_MMA(1, 0, At, B0); PG8_MMA(1, 1, At, B1); PG8_BAR; PG8_SCHED;
;             PG8_LDB(B0, 1, 0); PG8_LDB(B1, 1, 1); PG8_SCHED; PG8_LDA(At, 1, 0); PG8_STAGE(PG8_SA(0, 1), a2 + hsA, voffA);
;             PG8_WAIT_V(8); PG8_WAIT_L(0); PG8_BAR; PG8_MMA(0, 0, At, B0); PG8_MMA(0, 1, At, B1); PG8_BAR; PG8_SCHED;
	v_mfma_f32_16x16x32_bf16 v[60:63], v[144:147], v[200:203], v[60:63]
	v_mfma_f32_16x16x32_bf16 v[56:59], v[152:155], v[200:203], v[56:59]
	v_mfma_f32_16x16x32_bf16 v[44:47], v[144:147], v[208:211], v[44:47]
	v_mfma_f32_16x16x32_bf16 v[40:43], v[152:155], v[208:211], v[40:43]
	v_mfma_f32_16x16x32_bf16 v[28:31], v[144:147], v[236:239], v[28:31]
	v_mfma_f32_16x16x32_bf16 v[24:27], v[152:155], v[236:239], v[24:27]
	v_mfma_f32_16x16x32_bf16 v[12:15], v[144:147], v[244:247], v[12:15]
	v_mfma_f32_16x16x32_bf16 v[8:11], v[152:155], v[244:247], v[8:11]
	v_mfma_f32_16x16x32_bf16 v[60:63], v[148:151], v[204:207], v[60:63]
	v_mfma_f32_16x16x32_bf16 v[56:59], v[156:159], v[204:207], v[56:59]
	v_mfma_f32_16x16x32_bf16 v[44:47], v[148:151], v[232:235], v[44:47]
	v_mfma_f32_16x16x32_bf16 v[40:43], v[156:159], v[232:235], v[40:43]
	v_mfma_f32_16x16x32_bf16 v[28:31], v[148:151], v[240:243], v[28:31]
	v_mfma_f32_16x16x32_bf16 v[24:27], v[156:159], v[240:243], v[24:27]
	v_mfma_f32_16x16x32_bf16 v[12:15], v[148:151], v[248:251], v[12:15]
	v_mfma_f32_16x16x32_bf16 v[8:11], v[156:159], v[248:251], v[8:11]
	v_mfma_f32_16x16x32_bf16 v[52:55], v[184:187], v[200:203], v[52:55]
	v_mfma_f32_16x16x32_bf16 v[48:51], v[192:195], v[200:203], v[48:51]
	v_mfma_f32_16x16x32_bf16 v[36:39], v[184:187], v[208:211], v[36:39]
	v_mfma_f32_16x16x32_bf16 v[32:35], v[192:195], v[208:211], v[32:35]
	v_mfma_f32_16x16x32_bf16 v[20:23], v[184:187], v[236:239], v[20:23]
	v_mfma_f32_16x16x32_bf16 v[16:19], v[192:195], v[236:239], v[16:19]
	v_mfma_f32_16x16x32_bf16 v[4:7], v[184:187], v[244:247], v[4:7]
	v_mfma_f32_16x16x32_bf16 v[0:3], v[192:195], v[244:247], v[0:3]
	v_mfma_f32_16x16x32_bf16 v[52:55], v[188:191], v[204:207], v[52:55]
	v_mfma_f32_16x16x32_bf16 v[48:51], v[196:199], v[204:207], v[48:51]
	v_mfma_f32_16x16x32_bf16 v[36:39], v[188:191], v[232:235], v[36:39]
	v_mfma_f32_16x16x32_bf16 v[32:35], v[196:199], v[232:235], v[32:35]
	v_mfma_f32_16x16x32_bf16 v[20:23], v[188:191], v[240:243], v[20:23]
	v_mfma_f32_16x16x32_bf16 v[16:19], v[196:199], v[240:243], v[16:19]
	v_mfma_f32_16x16x32_bf16 v[4:7], v[188:191], v[248:251], v[4:7]
	v_mfma_f32_16x16x32_bf16 v[0:3], v[196:199], v[248:251], v[0:3]
	s_barrier
	s_add_i32 s55, 0, 0x18000
	v_add_u32_e32 v143, s55, v163
	s_add_i32 s67, 0, 0x1c000
	ds_read_b128 v[144:147], v143
	ds_read_b128 v[148:151], v143 offset:1024
	ds_read_b128 v[152:155], v143 offset:2048
	ds_read_b128 v[156:159], v143 offset:3072
	v_add_u32_e32 v143, s67, v163
	ds_read_b128 v[184:187], v143
	ds_read_b128 v[188:191], v143 offset:1024
	ds_read_b128 v[192:195], v143 offset:2048
	ds_read_b128 v[196:199], v143 offset:3072
	s_add_u32 s24, s42, 0x80000
	s_addc_u32 s25, s43, 0
	s_mov_b32 m0, s27
	v_lshl_add_u64 v[172:173], s[24:25], 0, v[134:135]
	ds_read_b128 v[200:203], v165 offset:32768
	ds_read_b128 v[204:207], v165 offset:33792
	ds_read_b128 v[208:211], v165 offset:34816
	ds_read_b128 v[232:235], v165 offset:35840
	ds_read_b128 v[236:239], v165 offset:36864
	ds_read_b128 v[240:243], v165 offset:37888
	ds_read_b128 v[244:247], v165 offset:38912
	ds_read_b128 v[248:251], v165 offset:39936
	global_load_lds_dwordx4 v[172:173], off
	v_lshl_add_u64 v[172:173], s[24:25], 0, v[130:131]
	s_mov_b32 m0, s96
	s_nop 0
	global_load_lds_dwordx4 v[172:173], off
	s_waitcnt vmcnt(8)
	s_waitcnt lgkmcnt(0)
	s_barrier
	v_mfma_f32_16x16x32_bf16 v[124:127], v[144:147], v[200:203], v[124:127]
	v_mfma_f32_16x16x32_bf16 v[120:123], v[152:155], v[200:203], v[120:123]
	v_mfma_f32_16x16x32_bf16 v[108:111], v[144:147], v[208:211], v[108:111]
	v_mfma_f32_16x16x32_bf16 v[104:107], v[152:155], v[208:211], v[104:107]
	v_mfma_f32_16x16x32_bf16 v[92:95], v[144:147], v[236:239], v[92:95]
	v_mfma_f32_16x16x32_bf16 v[88:91], v[152:155], v[236:239], v[88:91]
	v_mfma_f32_16x16x32_bf16 v[76:79], v[144:147], v[244:247], v[76:79]
	v_mfma_f32_16x16x32_bf16 v[72:75], v[152:155], v[244:247], v[72:75]
	v_mfma_f32_16x16x32_bf16 v[124:127], v[148:151], v[204:207], v[124:127]
	v_mfma_f32_16x16x32_bf16 v[120:123], v[156:159], v[204:207], v[120:123]
	v_mfma_f32_16x16x32_bf16 v[108:111], v[148:151], v[232:235], v[108:111]
	v_mfma_f32_16x16x32_bf16 v[104:107], v[156:159], v[232:235], v[104:107]
	v_mfma_f32_16x16x32_bf16 v[92:95], v[148:151], v[240:243], v[92:95]
	v_mfma_f32_16x16x32_bf16 v[88:91], v[156:159], v[240:243], v[88:91]
	v_mfma_f32_16x16x32_bf16 v[76:79], v[148:151], v[248:251], v[76:79]
	v_mfma_f32_16x16x32_bf16 v[72:75], v[156:159], v[248:251], v[72:75]
	v_mfma_f32_16x16x32_bf16 v[116:119], v[184:187], v[200:203], v[116:119]
	v_mfma_f32_16x16x32_bf16 v[112:115], v[192:195], v[200:203], v[112:115]
	v_mfma_f32_16x16x32_bf16 v[100:103], v[184:187], v[208:211], v[100:103]
	v_mfma_f32_16x16x32_bf16 v[96:99], v[192:195], v[208:211], v[96:99]
	v_mfma_f32_16x16x32_bf16 v[84:87], v[184:187], v[236:239], v[84:87]
	v_mfma_f32_16x16x32_bf16 v[80:83], v[192:195], v[236:239], v[80:83]
	v_mfma_f32_16x16x32_bf16 v[68:71], v[184:187], v[244:247], v[68:71]
	v_mfma_f32_16x16x32_bf16 v[64:67], v[192:195], v[244:247], v[64:67]
	v_mfma_f32_16x16x32_bf16 v[116:119], v[188:191], v[204:207], v[116:119]
	v_mfma_f32_16x16x32_bf16 v[112:115], v[196:199], v[204:207], v[112:115]
	v_mfma_f32_16x16x32_bf16 v[100:103], v[188:191], v[232:235], v[100:103]
	v_mfma_f32_16x16x32_bf16 v[96:99], v[196:199], v[232:235], v[96:99]
	v_mfma_f32_16x16x32_bf16 v[84:87], v[188:191], v[240:243], v[84:87]
	v_mfma_f32_16x16x32_bf16 v[80:83], v[196:199], v[240:243], v[80:83]
	v_mfma_f32_16x16x32_bf16 v[68:71], v[188:191], v[248:251], v[68:71]
	v_mfma_f32_16x16x32_bf16 v[64:67], v[196:199], v[248:251], v[64:67]
	s_barrier
; #define PG8_STAGE(bufoff, gbase, voff) do { _Pragma("unroll") for (int _i = 0; _i < 2; ++_i) \
;         __builtin_amdgcn_global_load_lds((const unsigned*)((const char*)(gbase) + (voff)[_i]), (LAS unsigned*)(lds + (bufoff) + ldsw + _i * 8192), 16, 0, 0); } while (0)
; #define PG8_LDA(dst, b, h) do { _Pragma("unroll") for (int m = 0; m < 4; ++m) _Pragma("unroll") for (int k = 0; k < 2; ++k) dst[m][k] = *(const LAS bf16x8*)(lds + PG8_SA(b, h) + aoff + m * 2048 + k * 1024); } while (0)
; #define PG8_MMA(ai, bj, At, Bt) do { __builtin_amdgcn_s_setprio(1); _Pragma("unroll") for (int m = 0; m < 4; ++m) _Pragma("unroll") for (int n = 0; n < 2; ++n) _Pragma("unroll") for (int k = 0; k < 2; ++k) \
;         acc[ai][bj][m][n] = __builtin_amdgcn_mfma_f32_16x16x32_bf16(Bt[n][k], At[m][k], acc[ai][bj][m][n], 0, 0, 0); __builtin_amdgcn_s_setprio(0); } while (0)
; #define PG8_WAIT_V(n) asm volatile("s_waitcnt vmcnt(" #n ")" ::: "memory")
; #define PG8_WAIT_L(n) asm volatile("s_waitcnt lgkmcnt(" #n ")" ::: "memory")
; #define PG8_BAR __builtin_amdgcn_s_barrier()
; #define PG8_SCHED __builtin_amdgcn_sched_barrier(0)
; template <class Epi>
; __device__ __forceinline__ void gemm_phase(LAS unsigned char* lds, const Gemm g, const StaticOrder& S, const Epi& E, const int tid) {
;     ...
;             PG8_LDA(At, 1, 1); PG8_STAGE(PG8_SB(1, 0), b3, voffB); PG8_STAGE(PG8_SB(1, 1), b3 + hsB, voffB); PG8_STAGE(PG8_SA(1, 0), a3, voffA);
;             PG8_WAIT_V(8); PG8_WAIT_L(0); PG8_BAR; PG8_MMA(1, 0, At, B0); PG8_MMA(1, 1, At, B1); PG8_BAR; PG8_SCHED;
;         }
;         if (wr == 0) PG8_BAR;
	s_add_i32 s24, s55, s57
	v_lshl_add_u64 v[160:161], v[160:161], 0, s[28:29]
	s_mov_b32 m0, s24
	ds_read_b128 v[200:203], v165 offset:49152
	ds_read_b128 v[204:207], v165 offset:50176
	ds_read_b128 v[208:211], v165 offset:51200
	ds_read_b128 v[232:235], v165 offset:52224
	ds_read_b128 v[236:239], v165 offset:53248
	ds_read_b128 v[240:243], v165 offset:54272
	ds_read_b128 v[244:247], v165 offset:55296
	ds_read_b128 v[248:251], v165 offset:56320
	global_load_lds_dwordx4 v[160:161], off
	s_add_i32 m0, s24, 0x2000
	s_add_u32 s0, s0, 0x80080
	v_lshl_add_u64 v[160:161], v[166:167], 0, s[28:29]
	s_addc_u32 s1, s1, 0
	s_add_i32 s24, s67, s57
	global_load_lds_dwordx4 v[160:161], off
	v_lshl_add_u64 v[160:161], s[0:1], 0, v[132:133]
	s_mov_b32 m0, s24
	s_nop 0
	global_load_lds_dwordx4 v[160:161], off
	v_lshl_add_u64 v[160:161], s[0:1], 0, v[128:129]
	s_add_i32 m0, s24, 0x2000
	s_nop 0
	global_load_lds_dwordx4 v[160:161], off
	v_lshl_add_u64 v[160:161], v[170:171], 0, s[28:29]
	s_mov_b32 m0, s6
	s_nop 0
	global_load_lds_dwordx4 v[160:161], off
	v_lshl_add_u64 v[160:161], v[212:213], 0, s[28:29]
	s_mov_b32 m0, s7
	s_nop 0
	global_load_lds_dwordx4 v[160:161], off
	s_waitcnt vmcnt(8)
	s_waitcnt lgkmcnt(0)
	s_barrier
	v_mfma_f32_16x16x32_bf16 v[60:63], v[144:147], v[200:203], v[60:63]
	v_mfma_f32_16x16x32_bf16 v[56:59], v[152:155], v[200:203], v[56:59]
	v_mfma_f32_16x16x32_bf16 v[44:47], v[144:147], v[208:211], v[44:47]
	v_mfma_f32_16x16x32_bf16 v[40:43], v[152:155], v[208:211], v[40:43]
	v_mfma_f32_16x16x32_bf16 v[28:31], v[144:147], v[236:239], v[28:31]
	v_mfma_f32_16x16x32_bf16 v[24:27], v[152:155], v[236:239], v[24:27]
	v_mfma_f32_16x16x32_bf16 v[12:15], v[144:147], v[244:247], v[12:15]
	v_mfma_f32_16x16x32_bf16 v[8:11], v[152:155], v[244:247], v[8:11]
	v_mfma_f32_16x16x32_bf16 v[60:63], v[148:151], v[204:207], v[60:63]
	v_mfma_f32_16x16x32_bf16 v[56:59], v[156:159], v[204:207], v[56:59]
	v_mfma_f32_16x16x32_bf16 v[44:47], v[148:151], v[232:235], v[44:47]
	v_mfma_f32_16x16x32_bf16 v[40:43], v[156:159], v[232:235], v[40:43]
	v_mfma_f32_16x16x32_bf16 v[28:31], v[148:151], v[240:243], v[28:31]
	v_mfma_f32_16x16x32_bf16 v[24:27], v[156:159], v[240:243], v[24:27]
	v_mfma_f32_16x16x32_bf16 v[12:15], v[148:151], v[248:251], v[12:15]
	v_mfma_f32_16x16x32_bf16 v[8:11], v[156:159], v[248:251], v[8:11]
	v_mfma_f32_16x16x32_bf16 v[52:55], v[184:187], v[200:203], v[52:55]
	v_mfma_f32_16x16x32_bf16 v[48:51], v[192:195], v[200:203], v[48:51]
	v_mfma_f32_16x16x32_bf16 v[36:39], v[184:187], v[208:211], v[36:39]
	v_mfma_f32_16x16x32_bf16 v[32:35], v[192:195], v[208:211], v[32:35]
	v_mfma_f32_16x16x32_bf16 v[20:23], v[184:187], v[236:239], v[20:23]
	v_mfma_f32_16x16x32_bf16 v[16:19], v[192:195], v[236:239], v[16:19]
	v_mfma_f32_16x16x32_bf16 v[4:7], v[184:187], v[244:247], v[4:7]
	v_mfma_f32_16x16x32_bf16 v[0:3], v[192:195], v[244:247], v[0:3]
	v_mfma_f32_16x16x32_bf16 v[52:55], v[188:191], v[204:207], v[52:55]
	v_mfma_f32_16x16x32_bf16 v[48:51], v[196:199], v[204:207], v[48:51]
	v_mfma_f32_16x16x32_bf16 v[36:39], v[188:191], v[232:235], v[36:39]
	v_mfma_f32_16x16x32_bf16 v[32:35], v[196:199], v[232:235], v[32:35]
	v_mfma_f32_16x16x32_bf16 v[20:23], v[188:191], v[240:243], v[20:23]
	v_mfma_f32_16x16x32_bf16 v[16:19], v[196:199], v[240:243], v[16:19]
	v_mfma_f32_16x16x32_bf16 v[4:7], v[188:191], v[248:251], v[4:7]
	v_mfma_f32_16x16x32_bf16 v[0:3], v[196:199], v[248:251], v[0:3]
	s_barrier
	s_add_i32 vcc_hi, vcc_hi, 2
	s_add_u32 s36, s36, 0x100
	s_addc_u32 s37, s37, 0
	s_add_u32 s69, s69, 0x100
	s_addc_u32 vcc_lo, vcc_lo, 0
	s_cmp_gt_u32 vcc_hi, 29
	s_cbranch_scc0 .LBB0_354
	s_and_b64 vcc, exec, s[34:35]
	s_cbranch_vccz .LBB0_357
	s_barrier

; #define PG8_STAGE(bufoff, gbase, voff) do { _Pragma("unroll") for (int _i = 0; _i < 2; ++_i) \
;         __builtin_amdgcn_global_load_lds((const unsigned*)((const char*)(gbase) + (voff)[_i]), (LAS unsigned*)(lds + (bufoff) + ldsw + _i * 8192), 16, 0, 0); } while (0)
; #define PG8_LDA(dst, b, h) do { _Pragma("unroll") for (int m = 0; m < 4; ++m) _Pragma("unroll") for (int k = 0; k < 2; ++k) dst[m][k] = *(const LAS bf16x8*)(lds + PG8_SA(b, h) + aoff + m * 2048 + k * 1024); } while (0)
; #define PG8_LDB(dst, b, h) do { _Pragma("unroll") for (int n = 0; n < 2; ++n) _Pragma("unroll") for (int k = 0; k < 2; ++k) dst[n][k] = *(const LAS bf16x8*)(lds + PG8_SB(b, h) + boff + n * 2048 + k * 1024); } while (0)
; #define PG8_MMA(ai, bj, At, Bt) do { __builtin_amdgcn_s_setprio(1); _Pragma("unroll") for (int m = 0; m < 4; ++m) _Pragma("unroll") for (int n = 0; n < 2; ++n) _Pragma("unroll") for (int k = 0; k < 2; ++k) \
;         acc[ai][bj][m][n] = __builtin_amdgcn_mfma_f32_16x16x32_bf16(Bt[n][k], At[m][k], acc[ai][bj][m][n], 0, 0, 0); __builtin_amdgcn_s_setprio(0); } while (0)
; #define PG8_WAIT_V(n) asm volatile("s_waitcnt vmcnt(" #n ")" ::: "memory")
; #define PG8_WAIT_L(n) asm volatile("s_waitcnt lgkmcnt(" #n ")" ::: "memory")
; #define PG8_BAR __builtin_amdgcn_s_barrier()
; #define PG8_SCHED __builtin_amdgcn_sched_barrier(0)
; template <class Epi>
; __device__ __forceinline__ void gemm_phase(LAS unsigned char* lds, const Gemm g, const StaticOrder& S, const Epi& E, const int tid) {
;     ...
;             const char* a1 = cA + (size_t)(t + 1) * kstep;
;             const char* a2 = last ? nA : cA + (size_t)(t + 2) * kstep; const char* b2 = last ? nB : cB + (size_t)(t + 2) * kstep;
;             const char* a3 = a2 + kstep; const char* b3 = b2 + kstep;
;             PG8_LDB(B0, 0, 0); PG8_LDB(B1, 0, 1); PG8_SCHED; PG8_LDA(At, 0, 0); PG8_STAGE(PG8_SA(1, 1), a1 + hsA, voffA);
;             PG8_WAIT_V(8); PG8_WAIT_L(0); PG8_BAR; PG8_MMA(0, 0, At, B0); PG8_MMA(0, 1, At, B1); PG8_BAR; PG8_SCHED;
;             PG8_LDA(At, 0, 1); PG8_STAGE(PG8_SB(0, 0), b2, voffB); PG8_STAGE(PG8_SB(0, 1), b2 + hsB, voffB); PG8_STAGE(PG8_SA(0, 0), a2, voffA);
;             PG8_WAIT_V(8); PG8_WAIT_L(0); PG8_BAR; PG8_MMA(1, 0, At, B0); PG8_MMA(1, 1, At, B1); PG8_BAR; PG8_SCHED;
.Lgprio_d:
.LBB0_823:
	s_add_u32 s42, s36, 0x100
	s_addc_u32 s43, s37, 0
	s_add_i32 s24, 0, 0x10000
	s_cmp_eq_u32 s96, 12
	s_cselect_b32 vcc_hi, s47, s43
	s_cselect_b32 vcc_lo, s46, s42
	s_cselect_b32 s49, s35, s69
	s_cselect_b32 s48, s45, s68
	s_add_i32 s55, 0, 0x14000
	v_add_u32_e32 v150, s24, v232
	v_add_u32_e32 v166, s55, v232
	ds_read_b128 v[138:141], v150
	ds_read_b128 v[142:145], v150 offset:1024
	ds_read_b128 v[146:149], v150 offset:2048
	ds_read_b128 v[150:153], v150 offset:3072
	ds_read_b128 v[154:157], v166
	ds_read_b128 v[158:161], v166 offset:1024
	ds_read_b128 v[162:165], v166 offset:2048
	ds_read_b128 v[184:187], v166 offset:3072
	v_lshl_add_u64 v[166:167], s[36:37], 0, v[134:135]
	s_add_i32 m0, s7, 0xc000
	ds_read_b128 v[188:191], v234
	ds_read_b128 v[192:195], v234 offset:1024
	ds_read_b128 v[196:199], v234 offset:2048
	ds_read_b128 v[200:203], v234 offset:3072
	ds_read_b128 v[204:207], v234 offset:4096
	ds_read_b128 v[208:211], v234 offset:5120
	ds_read_b128 v[236:239], v234 offset:6144
	ds_read_b128 v[240:243], v234 offset:7168
	global_load_lds_dwordx4 v[166:167], off
	v_lshl_add_u64 v[166:167], s[36:37], 0, v[136:137]
	s_add_i32 m0, s7, 0xe000
	s_nop 0
	global_load_lds_dwordx4 v[166:167], off
	s_waitcnt vmcnt(8)
	s_waitcnt lgkmcnt(0)
	s_barrier
	v_mfma_f32_16x16x32_bf16 v[124:127], v[138:141], v[188:191], v[124:127]
	v_mfma_f32_16x16x32_bf16 v[120:123], v[146:149], v[188:191], v[120:123]
	v_mfma_f32_16x16x32_bf16 v[116:119], v[138:141], v[196:199], v[116:119]
	v_mfma_f32_16x16x32_bf16 v[112:115], v[146:149], v[196:199], v[112:115]
	v_mfma_f32_16x16x32_bf16 v[108:111], v[138:141], v[204:207], v[108:111]
	v_mfma_f32_16x16x32_bf16 v[104:107], v[146:149], v[204:207], v[104:107]
	v_mfma_f32_16x16x32_bf16 v[100:103], v[138:141], v[236:239], v[100:103]
	v_mfma_f32_16x16x32_bf16 v[96:99], v[146:149], v[236:239], v[96:99]
	v_mfma_f32_16x16x32_bf16 v[124:127], v[142:145], v[192:195], v[124:127]
	v_mfma_f32_16x16x32_bf16 v[120:123], v[150:153], v[192:195], v[120:123]
	v_mfma_f32_16x16x32_bf16 v[116:119], v[142:145], v[200:203], v[116:119]
	v_mfma_f32_16x16x32_bf16 v[112:115], v[150:153], v[200:203], v[112:115]
	v_mfma_f32_16x16x32_bf16 v[108:111], v[142:145], v[208:211], v[108:111]
	v_mfma_f32_16x16x32_bf16 v[104:107], v[150:153], v[208:211], v[104:107]
	v_mfma_f32_16x16x32_bf16 v[100:103], v[142:145], v[240:243], v[100:103]
	v_mfma_f32_16x16x32_bf16 v[96:99], v[150:153], v[240:243], v[96:99]
	v_mfma_f32_16x16x32_bf16 v[92:95], v[154:157], v[188:191], v[92:95]
	v_mfma_f32_16x16x32_bf16 v[88:91], v[162:165], v[188:191], v[88:91]
	v_mfma_f32_16x16x32_bf16 v[84:87], v[154:157], v[196:199], v[84:87]
	v_mfma_f32_16x16x32_bf16 v[80:83], v[162:165], v[196:199], v[80:83]
	v_mfma_f32_16x16x32_bf16 v[76:79], v[154:157], v[204:207], v[76:79]
	v_mfma_f32_16x16x32_bf16 v[72:75], v[162:165], v[204:207], v[72:75]
	v_mfma_f32_16x16x32_bf16 v[68:71], v[154:157], v[236:239], v[68:71]
	v_mfma_f32_16x16x32_bf16 v[64:67], v[162:165], v[236:239], v[64:67]
	v_mfma_f32_16x16x32_bf16 v[92:95], v[158:161], v[192:195], v[92:95]
	v_mfma_f32_16x16x32_bf16 v[88:91], v[184:187], v[192:195], v[88:91]
	v_mfma_f32_16x16x32_bf16 v[84:87], v[158:161], v[200:203], v[84:87]
	v_mfma_f32_16x16x32_bf16 v[80:83], v[184:187], v[200:203], v[80:83]
	v_mfma_f32_16x16x32_bf16 v[76:79], v[158:161], v[208:211], v[76:79]
	v_mfma_f32_16x16x32_bf16 v[72:75], v[184:187], v[208:211], v[72:75]
	v_mfma_f32_16x16x32_bf16 v[68:71], v[158:161], v[240:243], v[68:71]
	v_mfma_f32_16x16x32_bf16 v[64:67], v[184:187], v[240:243], v[64:67]
	s_barrier
	s_add_i32 s24, s24, s6
	v_lshl_add_u64 v[166:167], s[48:49], 0, v[168:169]
	s_mov_b32 m0, s24
	ds_read_b128 v[188:191], v234 offset:16384
	ds_read_b128 v[192:195], v234 offset:17408
	ds_read_b128 v[196:199], v234 offset:18432
	ds_read_b128 v[200:203], v234 offset:19456
	ds_read_b128 v[204:207], v234 offset:20480
	ds_read_b128 v[208:211], v234 offset:21504
	ds_read_b128 v[236:239], v234 offset:22528
	ds_read_b128 v[240:243], v234 offset:23552
	global_load_lds_dwordx4 v[166:167], off
	s_add_i32 m0, s24, 0x2000
	s_add_u32 s24, s48, 0x40000
	v_lshl_add_u64 v[170:171], s[48:49], 0, v[128:129]
	s_addc_u32 s25, s49, 0
	s_add_i32 s36, s55, s6
	global_load_lds_dwordx4 v[170:171], off
	v_lshl_add_u64 v[172:173], s[24:25], 0, v[168:169]
	s_mov_b32 m0, s36
	v_lshl_add_u64 v[212:213], vcc, 0, v[130:131]
	global_load_lds_dwordx4 v[172:173], off
	v_lshl_add_u64 v[172:173], s[24:25], 0, v[128:129]
	s_add_i32 m0, s36, 0x2000
	s_nop 0
	global_load_lds_dwordx4 v[172:173], off
	v_lshl_add_u64 v[172:173], vcc, 0, v[132:133]
	s_mov_b32 m0, s7
	s_nop 0
	global_load_lds_dwordx4 v[172:173], off
	s_mov_b32 m0, s10
	s_nop 0
	global_load_lds_dwordx4 v[212:213], off
	s_waitcnt vmcnt(8)
	s_waitcnt lgkmcnt(0)
	s_barrier
; #define PG8_STAGE(bufoff, gbase, voff) do { _Pragma("unroll") for (int _i = 0; _i < 2; ++_i) \
;         __builtin_amdgcn_global_load_lds((const unsigned*)((const char*)(gbase) + (voff)[_i]), (LAS unsigned*)(lds + (bufoff) + ldsw + _i * 8192), 16, 0, 0); } while (0)
; #define PG8_LDA(dst, b, h) do { _Pragma("unroll") for (int m = 0; m < 4; ++m) _Pragma("unroll") for (int k = 0; k < 2; ++k) dst[m][k] = *(const LAS bf16x8*)(lds + PG8_SA(b, h) + aoff + m * 2048 + k * 1024); } while (0)
; #define PG8_LDB(dst, b, h) do { _Pragma("unroll") for (int n = 0; n < 2; ++n) _Pragma("unroll") for (int k = 0; k < 2; ++k) dst[n][k] = *(const LAS bf16x8*)(lds + PG8_SB(b, h) + boff + n * 2048 + k * 1024); } while (0)
; #define PG8_MMA(ai, bj, At, Bt) do { __builtin_amdgcn_s_setprio(1); _Pragma("unroll") for (int m = 0; m < 4; ++m) _Pragma("unroll") for (int n = 0; n < 2; ++n) _Pragma("unroll") for (int k = 0; k < 2; ++k) \
;         acc[ai][bj][m][n] = __builtin_amdgcn_mfma_f32_16x16x32_bf16(Bt[n][k], At[m][k], acc[ai][bj][m][n], 0, 0, 0); __builtin_amdgcn_s_setprio(0); } while (0)
; #define PG8_WAIT_V(n) asm volatile("s_waitcnt vmcnt(" #n ")" ::: "memory")
; #define PG8_WAIT_L(n) asm volatile("s_waitcnt lgkmcnt(" #n ")" ::: "memory")
; #define PG8_BAR __builtin_amdgcn_s_barrier()
; #define PG8_SCHED __builtin_amdgcn_sched_barrier(0)
; template <class Epi>
; __device__ __forceinline__ void gemm_phase(LAS unsigned char* lds, const Gemm g, const StaticOrder& S, const Epi& E, const int tid) {
;     ...
;             PG8_WAIT_V(8); PG8_WAIT_L(0); PG8_BAR; PG8_MMA(1, 0, At, B0); PG8_MMA(1, 1, At, B1); PG8_BAR; PG8_SCHED;
;             PG8_LDB(B0, 1, 0); PG8_LDB(B1, 1, 1); PG8_SCHED; PG8_LDA(At, 1, 0); PG8_STAGE(PG8_SA(0, 1), a2 + hsA, voffA);
;             PG8_WAIT_V(8); PG8_WAIT_L(0); PG8_BAR; PG8_MMA(0, 0, At, B0); PG8_MMA(0, 1, At, B1); PG8_BAR; PG8_SCHED;
	v_mfma_f32_16x16x32_bf16 v[60:63], v[138:141], v[188:191], v[60:63]
	v_mfma_f32_16x16x32_bf16 v[56:59], v[146:149], v[188:191], v[56:59]
	v_mfma_f32_16x16x32_bf16 v[52:55], v[138:141], v[196:199], v[52:55]
	v_mfma_f32_16x16x32_bf16 v[48:51], v[146:149], v[196:199], v[48:51]
	v_mfma_f32_16x16x32_bf16 v[44:47], v[138:141], v[204:207], v[44:47]
	v_mfma_f32_16x16x32_bf16 v[40:43], v[146:149], v[204:207], v[40:43]
	v_mfma_f32_16x16x32_bf16 v[36:39], v[138:141], v[236:239], v[36:39]
	v_mfma_f32_16x16x32_bf16 v[32:35], v[146:149], v[236:239], v[32:35]
	v_mfma_f32_16x16x32_bf16 v[60:63], v[142:145], v[192:195], v[60:63]
	v_mfma_f32_16x16x32_bf16 v[56:59], v[150:153], v[192:195], v[56:59]
	v_mfma_f32_16x16x32_bf16 v[52:55], v[142:145], v[200:203], v[52:55]
	v_mfma_f32_16x16x32_bf16 v[48:51], v[150:153], v[200:203], v[48:51]
	v_mfma_f32_16x16x32_bf16 v[44:47], v[142:145], v[208:211], v[44:47]
	v_mfma_f32_16x16x32_bf16 v[40:43], v[150:153], v[208:211], v[40:43]
	v_mfma_f32_16x16x32_bf16 v[36:39], v[142:145], v[240:243], v[36:39]
	v_mfma_f32_16x16x32_bf16 v[32:35], v[150:153], v[240:243], v[32:35]
	v_mfma_f32_16x16x32_bf16 v[28:31], v[154:157], v[188:191], v[28:31]
	v_mfma_f32_16x16x32_bf16 v[24:27], v[162:165], v[188:191], v[24:27]
	v_mfma_f32_16x16x32_bf16 v[20:23], v[154:157], v[196:199], v[20:23]
	v_mfma_f32_16x16x32_bf16 v[16:19], v[162:165], v[196:199], v[16:19]
	v_mfma_f32_16x16x32_bf16 v[12:15], v[154:157], v[204:207], v[12:15]
	v_mfma_f32_16x16x32_bf16 v[8:11], v[162:165], v[204:207], v[8:11]
	v_mfma_f32_16x16x32_bf16 v[4:7], v[154:157], v[236:239], v[4:7]
	v_mfma_f32_16x16x32_bf16 v[0:3], v[162:165], v[236:239], v[0:3]
	v_mfma_f32_16x16x32_bf16 v[28:31], v[158:161], v[192:195], v[28:31]
	v_mfma_f32_16x16x32_bf16 v[24:27], v[184:187], v[192:195], v[24:27]
	v_mfma_f32_16x16x32_bf16 v[20:23], v[158:161], v[200:203], v[20:23]
	v_mfma_f32_16x16x32_bf16 v[16:19], v[184:187], v[200:203], v[16:19]
	v_mfma_f32_16x16x32_bf16 v[12:15], v[158:161], v[208:211], v[12:15]
	v_mfma_f32_16x16x32_bf16 v[8:11], v[184:187], v[208:211], v[8:11]
	v_mfma_f32_16x16x32_bf16 v[4:7], v[158:161], v[240:243], v[4:7]
	v_mfma_f32_16x16x32_bf16 v[0:3], v[184:187], v[240:243], v[0:3]
	s_barrier
	s_add_i32 s36, 0, 0x18000
	s_add_i32 s37, 0, 0x1c000
	v_add_u32_e32 v150, s36, v232
	v_add_u32_e32 v184, s37, v232
	ds_read_b128 v[138:141], v150
	ds_read_b128 v[142:145], v150 offset:1024
	ds_read_b128 v[146:149], v150 offset:2048
	ds_read_b128 v[150:153], v150 offset:3072
	ds_read_b128 v[154:157], v184
	ds_read_b128 v[158:161], v184 offset:1024
	ds_read_b128 v[162:165], v184 offset:2048
	ds_read_b128 v[184:187], v184 offset:3072
	s_add_u32 s24, vcc_lo, 0xc0000
	s_addc_u32 s25, vcc_hi, 0
	s_mov_b32 m0, s11
	v_lshl_add_u64 v[244:245], s[24:25], 0, v[132:133]
	ds_read_b128 v[188:191], v234 offset:32768
	ds_read_b128 v[192:195], v234 offset:33792
	ds_read_b128 v[196:199], v234 offset:34816
	ds_read_b128 v[200:203], v234 offset:35840
	ds_read_b128 v[204:207], v234 offset:36864
	ds_read_b128 v[208:211], v234 offset:37888
	ds_read_b128 v[236:239], v234 offset:38912
	ds_read_b128 v[240:243], v234 offset:39936
	global_load_lds_dwordx4 v[244:245], off
	v_lshl_add_u64 v[244:245], s[24:25], 0, v[130:131]
	s_mov_b32 m0, s27
	s_nop 0
	global_load_lds_dwordx4 v[244:245], off
	s_waitcnt vmcnt(8)
	s_waitcnt lgkmcnt(0)
	s_barrier
	v_mfma_f32_16x16x32_bf16 v[124:127], v[138:141], v[188:191], v[124:127]
	v_mfma_f32_16x16x32_bf16 v[120:123], v[146:149], v[188:191], v[120:123]
	v_mfma_f32_16x16x32_bf16 v[116:119], v[138:141], v[196:199], v[116:119]
	v_mfma_f32_16x16x32_bf16 v[112:115], v[146:149], v[196:199], v[112:115]
	v_mfma_f32_16x16x32_bf16 v[108:111], v[138:141], v[204:207], v[108:111]
	v_mfma_f32_16x16x32_bf16 v[104:107], v[146:149], v[204:207], v[104:107]
	v_mfma_f32_16x16x32_bf16 v[100:103], v[138:141], v[236:239], v[100:103]
	v_mfma_f32_16x16x32_bf16 v[96:99], v[146:149], v[236:239], v[96:99]
	v_mfma_f32_16x16x32_bf16 v[124:127], v[142:145], v[192:195], v[124:127]
	v_mfma_f32_16x16x32_bf16 v[120:123], v[150:153], v[192:195], v[120:123]
	v_mfma_f32_16x16x32_bf16 v[116:119], v[142:145], v[200:203], v[116:119]
	v_mfma_f32_16x16x32_bf16 v[112:115], v[150:153], v[200:203], v[112:115]
	v_mfma_f32_16x16x32_bf16 v[108:111], v[142:145], v[208:211], v[108:111]
	v_mfma_f32_16x16x32_bf16 v[104:107], v[150:153], v[208:211], v[104:107]
	v_mfma_f32_16x16x32_bf16 v[100:103], v[142:145], v[240:243], v[100:103]
	v_mfma_f32_16x16x32_bf16 v[96:99], v[150:153], v[240:243], v[96:99]
	v_mfma_f32_16x16x32_bf16 v[92:95], v[154:157], v[188:191], v[92:95]
	v_mfma_f32_16x16x32_bf16 v[88:91], v[162:165], v[188:191], v[88:91]
	v_mfma_f32_16x16x32_bf16 v[84:87], v[154:157], v[196:199], v[84:87]
	v_mfma_f32_16x16x32_bf16 v[80:83], v[162:165], v[196:199], v[80:83]
	v_mfma_f32_16x16x32_bf16 v[76:79], v[154:157], v[204:207], v[76:79]
	v_mfma_f32_16x16x32_bf16 v[72:75], v[162:165], v[204:207], v[72:75]
	v_mfma_f32_16x16x32_bf16 v[68:71], v[154:157], v[236:239], v[68:71]
	v_mfma_f32_16x16x32_bf16 v[64:67], v[162:165], v[236:239], v[64:67]
	v_mfma_f32_16x16x32_bf16 v[92:95], v[158:161], v[192:195], v[92:95]
	v_mfma_f32_16x16x32_bf16 v[88:91], v[184:187], v[192:195], v[88:91]
	v_mfma_f32_16x16x32_bf16 v[84:87], v[158:161], v[200:203], v[84:87]
	v_mfma_f32_16x16x32_bf16 v[80:83], v[184:187], v[200:203], v[80:83]
	v_mfma_f32_16x16x32_bf16 v[76:79], v[158:161], v[208:211], v[76:79]
	v_mfma_f32_16x16x32_bf16 v[72:75], v[184:187], v[208:211], v[72:75]
	v_mfma_f32_16x16x32_bf16 v[68:71], v[158:161], v[240:243], v[68:71]
	v_mfma_f32_16x16x32_bf16 v[64:67], v[184:187], v[240:243], v[64:67]
	s_barrier
; #define PG8_STAGE(bufoff, gbase, voff) do { _Pragma("unroll") for (int _i = 0; _i < 2; ++_i) \
;         __builtin_amdgcn_global_load_lds((const unsigned*)((const char*)(gbase) + (voff)[_i]), (LAS unsigned*)(lds + (bufoff) + ldsw + _i * 8192), 16, 0, 0); } while (0)
; #define PG8_LDA(dst, b, h) do { _Pragma("unroll") for (int m = 0; m < 4; ++m) _Pragma("unroll") for (int k = 0; k < 2; ++k) dst[m][k] = *(const LAS bf16x8*)(lds + PG8_SA(b, h) + aoff + m * 2048 + k * 1024); } while (0)
; #define PG8_MMA(ai, bj, At, Bt) do { __builtin_amdgcn_s_setprio(1); _Pragma("unroll") for (int m = 0; m < 4; ++m) _Pragma("unroll") for (int n = 0; n < 2; ++n) _Pragma("unroll") for (int k = 0; k < 2; ++k) \
;         acc[ai][bj][m][n] = __builtin_amdgcn_mfma_f32_16x16x32_bf16(Bt[n][k], At[m][k], acc[ai][bj][m][n], 0, 0, 0); __builtin_amdgcn_s_setprio(0); } while (0)
; #define PG8_WAIT_V(n) asm volatile("s_waitcnt vmcnt(" #n ")" ::: "memory")
; #define PG8_WAIT_L(n) asm volatile("s_waitcnt lgkmcnt(" #n ")" ::: "memory")
; #define PG8_BAR __builtin_amdgcn_s_barrier()
; #define PG8_SCHED __builtin_amdgcn_sched_barrier(0)
; template <class Epi>
; __device__ __forceinline__ void gemm_phase(LAS unsigned char* lds, const Gemm g, const StaticOrder& S, const Epi& E, const int tid) {
;     ...
;             PG8_LDA(At, 1, 1); PG8_STAGE(PG8_SB(1, 0), b3, voffB); PG8_STAGE(PG8_SB(1, 1), b3 + hsB, voffB); PG8_STAGE(PG8_SA(1, 0), a3, voffA);
;             PG8_WAIT_V(8); PG8_WAIT_L(0); PG8_BAR; PG8_MMA(1, 0, At, B0); PG8_MMA(1, 1, At, B1); PG8_BAR; PG8_SCHED;
;         }
;         if (wr == 0) PG8_BAR;
	s_add_i32 s24, s36, s6
	v_lshl_add_u64 v[166:167], v[166:167], 0, s[28:29]
	s_mov_b32 m0, s24
	ds_read_b128 v[188:191], v234 offset:49152
	ds_read_b128 v[192:195], v234 offset:50176
	ds_read_b128 v[196:199], v234 offset:51200
	ds_read_b128 v[200:203], v234 offset:52224
	ds_read_b128 v[204:207], v234 offset:53248
	ds_read_b128 v[208:211], v234 offset:54272
	ds_read_b128 v[236:239], v234 offset:55296
	ds_read_b128 v[240:243], v234 offset:56320
	global_load_lds_dwordx4 v[166:167], off
	s_add_i32 m0, s24, 0x2000
	s_add_u32 s24, s48, 0x40080
	v_lshl_add_u64 v[166:167], v[170:171], 0, s[28:29]
	s_addc_u32 s25, s49, 0
	s_add_i32 s36, s37, s6
	global_load_lds_dwordx4 v[166:167], off
	v_lshl_add_u64 v[166:167], s[24:25], 0, v[168:169]
	s_mov_b32 m0, s36
	s_nop 0
	global_load_lds_dwordx4 v[166:167], off
	v_lshl_add_u64 v[166:167], s[24:25], 0, v[128:129]
	s_add_i32 m0, s36, 0x2000
	s_nop 0
	global_load_lds_dwordx4 v[166:167], off
	v_lshl_add_u64 v[166:167], v[172:173], 0, s[28:29]
	s_mov_b32 m0, s56
	s_nop 0
	global_load_lds_dwordx4 v[166:167], off
	v_lshl_add_u64 v[166:167], v[212:213], 0, s[28:29]
	s_mov_b32 m0, s57
	s_nop 0
	global_load_lds_dwordx4 v[166:167], off
	s_waitcnt vmcnt(8)
	s_waitcnt lgkmcnt(0)
	s_barrier
	v_mfma_f32_16x16x32_bf16 v[60:63], v[138:141], v[188:191], v[60:63]
	v_mfma_f32_16x16x32_bf16 v[56:59], v[146:149], v[188:191], v[56:59]
	v_mfma_f32_16x16x32_bf16 v[52:55], v[138:141], v[196:199], v[52:55]
	v_mfma_f32_16x16x32_bf16 v[48:51], v[146:149], v[196:199], v[48:51]
	v_mfma_f32_16x16x32_bf16 v[44:47], v[138:141], v[204:207], v[44:47]
	v_mfma_f32_16x16x32_bf16 v[40:43], v[146:149], v[204:207], v[40:43]
	v_mfma_f32_16x16x32_bf16 v[36:39], v[138:141], v[236:239], v[36:39]
	v_mfma_f32_16x16x32_bf16 v[32:35], v[146:149], v[236:239], v[32:35]
	v_mfma_f32_16x16x32_bf16 v[60:63], v[142:145], v[192:195], v[60:63]
	v_mfma_f32_16x16x32_bf16 v[56:59], v[150:153], v[192:195], v[56:59]
	v_mfma_f32_16x16x32_bf16 v[52:55], v[142:145], v[200:203], v[52:55]
	v_mfma_f32_16x16x32_bf16 v[48:51], v[150:153], v[200:203], v[48:51]
	v_mfma_f32_16x16x32_bf16 v[44:47], v[142:145], v[208:211], v[44:47]
	v_mfma_f32_16x16x32_bf16 v[40:43], v[150:153], v[208:211], v[40:43]
	v_mfma_f32_16x16x32_bf16 v[36:39], v[142:145], v[240:243], v[36:39]
	v_mfma_f32_16x16x32_bf16 v[32:35], v[150:153], v[240:243], v[32:35]
	v_mfma_f32_16x16x32_bf16 v[28:31], v[154:157], v[188:191], v[28:31]
	v_mfma_f32_16x16x32_bf16 v[24:27], v[162:165], v[188:191], v[24:27]
	v_mfma_f32_16x16x32_bf16 v[20:23], v[154:157], v[196:199], v[20:23]
	v_mfma_f32_16x16x32_bf16 v[16:19], v[162:165], v[196:199], v[16:19]
	v_mfma_f32_16x16x32_bf16 v[12:15], v[154:157], v[204:207], v[12:15]
	v_mfma_f32_16x16x32_bf16 v[8:11], v[162:165], v[204:207], v[8:11]
	v_mfma_f32_16x16x32_bf16 v[4:7], v[154:157], v[236:239], v[4:7]
	v_mfma_f32_16x16x32_bf16 v[0:3], v[162:165], v[236:239], v[0:3]
	v_mfma_f32_16x16x32_bf16 v[28:31], v[158:161], v[192:195], v[28:31]
	v_mfma_f32_16x16x32_bf16 v[24:27], v[184:187], v[192:195], v[24:27]
	v_mfma_f32_16x16x32_bf16 v[20:23], v[158:161], v[200:203], v[20:23]
	v_mfma_f32_16x16x32_bf16 v[16:19], v[184:187], v[200:203], v[16:19]
	v_mfma_f32_16x16x32_bf16 v[12:15], v[158:161], v[208:211], v[12:15]
	v_mfma_f32_16x16x32_bf16 v[8:11], v[184:187], v[208:211], v[8:11]
	v_mfma_f32_16x16x32_bf16 v[4:7], v[158:161], v[240:243], v[4:7]
	v_mfma_f32_16x16x32_bf16 v[0:3], v[184:187], v[240:243], v[0:3]
	s_barrier
	s_add_i32 s96, s96, 2
	s_add_u32 s68, s68, 0x100
	s_addc_u32 s69, s69, 0
	s_cmp_gt_u32 s96, 13
	s_mov_b64 s[36:37], s[42:43]
	s_cbranch_scc0 .LBB0_823
	s_and_b64 vcc, exec, s[12:13]
	s_cbranch_vccz .LBB0_826
	s_barrier

; #define PG8_STAGE(bufoff, gbase, voff) do { _Pragma("unroll") for (int _i = 0; _i < 2; ++_i) \
;         __builtin_amdgcn_global_load_lds((const unsigned*)((const char*)(gbase) + (voff)[_i]), (LAS unsigned*)(lds + (bufoff) + ldsw + _i * 8192), 16, 0, 0); } while (0)
; #define PG8_LDA(dst, b, h) do { _Pragma("unroll") for (int m = 0; m < 4; ++m) _Pragma("unroll") for (int k = 0; k < 2; ++k) dst[m][k] = *(const LAS bf16x8*)(lds + PG8_SA(b, h) + aoff + m * 2048 + k * 1024); } while (0)
; #define PG8_LDB(dst, b, h) do { _Pragma("unroll") for (int n = 0; n < 2; ++n) _Pragma("unroll") for (int k = 0; k < 2; ++k) dst[n][k] = *(const LAS bf16x8*)(lds + PG8_SB(b, h) + boff + n * 2048 + k * 1024); } while (0)
; #define PG8_MMA(ai, bj, At, Bt) do { __builtin_amdgcn_s_setprio(1); _Pragma("unroll") for (int m = 0; m < 4; ++m) _Pragma("unroll") for (int n = 0; n < 2; ++n) _Pragma("unroll") for (int k = 0; k < 2; ++k) \
;         acc[ai][bj][m][n] = __builtin_amdgcn_mfma_f32_16x16x32_bf16(Bt[n][k], At[m][k], acc[ai][bj][m][n], 0, 0, 0); __builtin_amdgcn_s_setprio(0); } while (0)
; #define PG8_WAIT_V(n) asm volatile("s_waitcnt vmcnt(" #n ")" ::: "memory")
; #define PG8_WAIT_L(n) asm volatile("s_waitcnt lgkmcnt(" #n ")" ::: "memory")
; #define PG8_BAR __builtin_amdgcn_s_barrier()
; #define PG8_SCHED __builtin_amdgcn_sched_barrier(0)
; template <class Epi>
; __device__ __forceinline__ void gemm_phase(LAS unsigned char* lds, const Gemm g, const StaticOrder& S, const Epi& E, const int tid) {
;     ...
;             const char* a1 = cA + (size_t)(t + 1) * kstep;
;             const char* a2 = last ? nA : cA + (size_t)(t + 2) * kstep; const char* b2 = last ? nB : cB + (size_t)(t + 2) * kstep;
;             const char* a3 = a2 + kstep; const char* b3 = b2 + kstep;
;             PG8_LDB(B0, 0, 0); PG8_LDB(B1, 0, 1); PG8_SCHED; PG8_LDA(At, 0, 0); PG8_STAGE(PG8_SA(1, 1), a1 + hsA, voffA);
;             PG8_WAIT_V(8); PG8_WAIT_L(0); PG8_BAR; PG8_MMA(0, 0, At, B0); PG8_MMA(0, 1, At, B1); PG8_BAR; PG8_SCHED;
;             PG8_LDA(At, 0, 1); PG8_STAGE(PG8_SB(0, 0), b2, voffB); PG8_STAGE(PG8_SB(0, 1), b2 + hsB, voffB); PG8_STAGE(PG8_SA(0, 0), a2, voffA);
;             PG8_WAIT_V(8); PG8_WAIT_L(0); PG8_BAR; PG8_MMA(1, 0, At, B0); PG8_MMA(1, 1, At, B1); PG8_BAR; PG8_SCHED;
.Lgprio_e:
.LBB0_893:
	s_add_u32 s0, s16, 0xfff80080
	s_addc_u32 s1, s17, -1
	s_add_i32 s2, 0, 0x10000
	s_cmp_eq_u32 s57, 28
	s_cselect_b32 s19, s11, s1
	s_cselect_b32 s18, s49, s0
	s_cselect_b32 s1, s9, s56
	s_cselect_b32 s0, s52, s53
	s_add_i32 s55, 0, 0x14000
	v_add_u32_e32 v76, s2, v204
	v_add_u32_e32 v156, s55, v204
	ds_read_b128 v[64:67], v76
	ds_read_b128 v[68:71], v76 offset:1024
	ds_read_b128 v[72:75], v76 offset:2048
	ds_read_b128 v[76:79], v76 offset:3072
	ds_read_b128 v[144:147], v156
	ds_read_b128 v[148:151], v156 offset:1024
	ds_read_b128 v[152:155], v156 offset:2048
	ds_read_b128 v[156:159], v156 offset:3072
	v_lshl_add_u64 v[170:171], s[16:17], 0, v[192:193]
	s_add_i32 m0, s36, 0xc000
	ds_read_b128 v[160:163], v209
	ds_read_b128 v[164:167], v209 offset:1024
	ds_read_b128 v[196:199], v209 offset:2048
	ds_read_b128 v[200:203], v209 offset:3072
	ds_read_b128 v[210:213], v209 offset:4096
	ds_read_b128 v[230:233], v209 offset:5120
	ds_read_b128 v[234:237], v209 offset:6144
	ds_read_b128 v[238:241], v209 offset:7168
	global_load_lds_dwordx4 v[170:171], off
	v_lshl_add_u64 v[170:171], s[16:17], 0, v[194:195]
	s_add_i32 m0, s36, 0xe000
	s_nop 0
	global_load_lds_dwordx4 v[170:171], off
	s_waitcnt vmcnt(8)
	s_waitcnt lgkmcnt(0)
	s_barrier
	v_mfma_f32_16x16x32_bf16 v[140:143], v[64:67], v[160:163], v[140:143]
	v_mfma_f32_16x16x32_bf16 v[136:139], v[72:75], v[160:163], v[136:139]
	v_mfma_f32_16x16x32_bf16 v[124:127], v[64:67], v[196:199], v[124:127]
	v_mfma_f32_16x16x32_bf16 v[120:123], v[72:75], v[196:199], v[120:123]
	v_mfma_f32_16x16x32_bf16 v[108:111], v[64:67], v[210:213], v[108:111]
	v_mfma_f32_16x16x32_bf16 v[104:107], v[72:75], v[210:213], v[104:107]
	v_mfma_f32_16x16x32_bf16 v[96:99], v[64:67], v[234:237], v[96:99]
	v_mfma_f32_16x16x32_bf16 v[88:91], v[72:75], v[234:237], v[88:91]
	v_mfma_f32_16x16x32_bf16 v[140:143], v[68:71], v[164:167], v[140:143]
	v_mfma_f32_16x16x32_bf16 v[136:139], v[76:79], v[164:167], v[136:139]
	v_mfma_f32_16x16x32_bf16 v[124:127], v[68:71], v[200:203], v[124:127]
	v_mfma_f32_16x16x32_bf16 v[120:123], v[76:79], v[200:203], v[120:123]
	v_mfma_f32_16x16x32_bf16 v[108:111], v[68:71], v[230:233], v[108:111]
	v_mfma_f32_16x16x32_bf16 v[104:107], v[76:79], v[230:233], v[104:107]
	v_mfma_f32_16x16x32_bf16 v[96:99], v[68:71], v[238:241], v[96:99]
	v_mfma_f32_16x16x32_bf16 v[88:91], v[76:79], v[238:241], v[88:91]
	v_mfma_f32_16x16x32_bf16 v[132:135], v[144:147], v[160:163], v[132:135]
	v_mfma_f32_16x16x32_bf16 v[128:131], v[152:155], v[160:163], v[128:131]
	v_mfma_f32_16x16x32_bf16 v[116:119], v[144:147], v[196:199], v[116:119]
	v_mfma_f32_16x16x32_bf16 v[112:115], v[152:155], v[196:199], v[112:115]
	v_mfma_f32_16x16x32_bf16 v[100:103], v[144:147], v[210:213], v[100:103]
	v_mfma_f32_16x16x32_bf16 v[92:95], v[152:155], v[210:213], v[92:95]
	v_mfma_f32_16x16x32_bf16 v[84:87], v[144:147], v[234:237], v[84:87]
	v_mfma_f32_16x16x32_bf16 v[80:83], v[152:155], v[234:237], v[80:83]
	v_mfma_f32_16x16x32_bf16 v[132:135], v[148:151], v[164:167], v[132:135]
	v_mfma_f32_16x16x32_bf16 v[128:131], v[156:159], v[164:167], v[128:131]
	v_mfma_f32_16x16x32_bf16 v[116:119], v[148:151], v[200:203], v[116:119]
	v_mfma_f32_16x16x32_bf16 v[112:115], v[156:159], v[200:203], v[112:115]
	v_mfma_f32_16x16x32_bf16 v[100:103], v[148:151], v[230:233], v[100:103]
	v_mfma_f32_16x16x32_bf16 v[92:95], v[156:159], v[230:233], v[92:95]
	v_mfma_f32_16x16x32_bf16 v[84:87], v[148:151], v[238:241], v[84:87]
	v_mfma_f32_16x16x32_bf16 v[80:83], v[156:159], v[238:241], v[80:83]
	s_barrier
	s_add_i32 s2, s2, s35
	v_lshl_add_u64 v[170:171], s[0:1], 0, v[188:189]
	s_mov_b32 m0, s2
	ds_read_b128 v[160:163], v209 offset:16384
	ds_read_b128 v[164:167], v209 offset:17408
	ds_read_b128 v[196:199], v209 offset:18432
	ds_read_b128 v[200:203], v209 offset:19456
	ds_read_b128 v[210:213], v209 offset:20480
	ds_read_b128 v[230:233], v209 offset:21504
	ds_read_b128 v[234:237], v209 offset:22528
	ds_read_b128 v[238:241], v209 offset:23552
	global_load_lds_dwordx4 v[170:171], off
	s_add_i32 m0, s2, 0x2000
	s_add_u32 s24, s0, 0x80000
	v_lshl_add_u64 v[172:173], s[0:1], 0, v[184:185]
	s_addc_u32 s25, s1, 0
	s_add_i32 s2, s55, s35
	global_load_lds_dwordx4 v[172:173], off
	v_lshl_add_u64 v[242:243], s[24:25], 0, v[188:189]
	s_mov_b32 m0, s2
	v_lshl_add_u64 v[244:245], s[18:19], 0, v[186:187]
	global_load_lds_dwordx4 v[242:243], off
	v_lshl_add_u64 v[242:243], s[24:25], 0, v[184:185]
	s_add_i32 m0, s2, 0x2000
	s_nop 0
	global_load_lds_dwordx4 v[242:243], off
	v_lshl_add_u64 v[242:243], s[18:19], 0, v[190:191]
	s_mov_b32 m0, s36
	s_nop 0
	global_load_lds_dwordx4 v[242:243], off
	s_mov_b32 m0, s37
	s_nop 0
	global_load_lds_dwordx4 v[244:245], off
	s_waitcnt vmcnt(8)
	s_waitcnt lgkmcnt(0)
	s_barrier
; #define PG8_STAGE(bufoff, gbase, voff) do { _Pragma("unroll") for (int _i = 0; _i < 2; ++_i) \
;         __builtin_amdgcn_global_load_lds((const unsigned*)((const char*)(gbase) + (voff)[_i]), (LAS unsigned*)(lds + (bufoff) + ldsw + _i * 8192), 16, 0, 0); } while (0)
; #define PG8_LDA(dst, b, h) do { _Pragma("unroll") for (int m = 0; m < 4; ++m) _Pragma("unroll") for (int k = 0; k < 2; ++k) dst[m][k] = *(const LAS bf16x8*)(lds + PG8_SA(b, h) + aoff + m * 2048 + k * 1024); } while (0)
; #define PG8_LDB(dst, b, h) do { _Pragma("unroll") for (int n = 0; n < 2; ++n) _Pragma("unroll") for (int k = 0; k < 2; ++k) dst[n][k] = *(const LAS bf16x8*)(lds + PG8_SB(b, h) + boff + n * 2048 + k * 1024); } while (0)
; #define PG8_MMA(ai, bj, At, Bt) do { __builtin_amdgcn_s_setprio(1); _Pragma("unroll") for (int m = 0; m < 4; ++m) _Pragma("unroll") for (int n = 0; n < 2; ++n) _Pragma("unroll") for (int k = 0; k < 2; ++k) \
;         acc[ai][bj][m][n] = __builtin_amdgcn_mfma_f32_16x16x32_bf16(Bt[n][k], At[m][k], acc[ai][bj][m][n], 0, 0, 0); __builtin_amdgcn_s_setprio(0); } while (0)
; #define PG8_WAIT_V(n) asm volatile("s_waitcnt vmcnt(" #n ")" ::: "memory")
; #define PG8_WAIT_L(n) asm volatile("s_waitcnt lgkmcnt(" #n ")" ::: "memory")
; #define PG8_BAR __builtin_amdgcn_s_barrier()
; #define PG8_SCHED __builtin_amdgcn_sched_barrier(0)
; template <class Epi>
; __device__ __forceinline__ void gemm_phase(LAS unsigned char* lds, const Gemm g, const StaticOrder& S, const Epi& E, const int tid) {
;     ...
;             PG8_WAIT_V(8); PG8_WAIT_L(0); PG8_BAR; PG8_MMA(1, 0, At, B0); PG8_MMA(1, 1, At, B1); PG8_BAR; PG8_SCHED;
;             PG8_LDB(B0, 1, 0); PG8_LDB(B1, 1, 1); PG8_SCHED; PG8_LDA(At, 1, 0); PG8_STAGE(PG8_SA(0, 1), a2 + hsA, voffA);
;             PG8_WAIT_V(8); PG8_WAIT_L(0); PG8_BAR; PG8_MMA(0, 0, At, B0); PG8_MMA(0, 1, At, B1); PG8_BAR; PG8_SCHED;
	v_mfma_f32_16x16x32_bf16 v[60:63], v[64:67], v[160:163], v[60:63]
	v_mfma_f32_16x16x32_bf16 v[56:59], v[72:75], v[160:163], v[56:59]
	v_mfma_f32_16x16x32_bf16 v[44:47], v[64:67], v[196:199], v[44:47]
	v_mfma_f32_16x16x32_bf16 v[40:43], v[72:75], v[196:199], v[40:43]
	v_mfma_f32_16x16x32_bf16 v[28:31], v[64:67], v[210:213], v[28:31]
	v_mfma_f32_16x16x32_bf16 v[24:27], v[72:75], v[210:213], v[24:27]
	v_mfma_f32_16x16x32_bf16 v[12:15], v[64:67], v[234:237], v[12:15]
	v_mfma_f32_16x16x32_bf16 v[8:11], v[72:75], v[234:237], v[8:11]
	v_mfma_f32_16x16x32_bf16 v[60:63], v[68:71], v[164:167], v[60:63]
	v_mfma_f32_16x16x32_bf16 v[56:59], v[76:79], v[164:167], v[56:59]
	v_mfma_f32_16x16x32_bf16 v[44:47], v[68:71], v[200:203], v[44:47]
	v_mfma_f32_16x16x32_bf16 v[40:43], v[76:79], v[200:203], v[40:43]
	v_mfma_f32_16x16x32_bf16 v[28:31], v[68:71], v[230:233], v[28:31]
	v_mfma_f32_16x16x32_bf16 v[24:27], v[76:79], v[230:233], v[24:27]
	v_mfma_f32_16x16x32_bf16 v[12:15], v[68:71], v[238:241], v[12:15]
	v_mfma_f32_16x16x32_bf16 v[8:11], v[76:79], v[238:241], v[8:11]
	v_mfma_f32_16x16x32_bf16 v[52:55], v[144:147], v[160:163], v[52:55]
	v_mfma_f32_16x16x32_bf16 v[48:51], v[152:155], v[160:163], v[48:51]
	v_mfma_f32_16x16x32_bf16 v[36:39], v[144:147], v[196:199], v[36:39]
	v_mfma_f32_16x16x32_bf16 v[32:35], v[152:155], v[196:199], v[32:35]
	v_mfma_f32_16x16x32_bf16 v[20:23], v[144:147], v[210:213], v[20:23]
	v_mfma_f32_16x16x32_bf16 v[16:19], v[152:155], v[210:213], v[16:19]
	v_mfma_f32_16x16x32_bf16 v[4:7], v[144:147], v[234:237], v[4:7]
	v_mfma_f32_16x16x32_bf16 v[0:3], v[152:155], v[234:237], v[0:3]
	v_mfma_f32_16x16x32_bf16 v[52:55], v[148:151], v[164:167], v[52:55]
	v_mfma_f32_16x16x32_bf16 v[48:51], v[156:159], v[164:167], v[48:51]
	v_mfma_f32_16x16x32_bf16 v[36:39], v[148:151], v[200:203], v[36:39]
	v_mfma_f32_16x16x32_bf16 v[32:35], v[156:159], v[200:203], v[32:35]
	v_mfma_f32_16x16x32_bf16 v[20:23], v[148:151], v[230:233], v[20:23]
	v_mfma_f32_16x16x32_bf16 v[16:19], v[156:159], v[230:233], v[16:19]
	v_mfma_f32_16x16x32_bf16 v[4:7], v[148:151], v[238:241], v[4:7]
	v_mfma_f32_16x16x32_bf16 v[0:3], v[156:159], v[238:241], v[0:3]
	s_barrier
	s_add_i32 s2, 0, 0x18000
	s_add_i32 s24, 0, 0x1c000
	v_add_u32_e32 v76, s2, v204
	v_add_u32_e32 v156, s24, v204
	ds_read_b128 v[64:67], v76
	ds_read_b128 v[68:71], v76 offset:1024
	ds_read_b128 v[72:75], v76 offset:2048
	ds_read_b128 v[76:79], v76 offset:3072
	ds_read_b128 v[144:147], v156
	ds_read_b128 v[148:151], v156 offset:1024
	ds_read_b128 v[152:155], v156 offset:2048
	ds_read_b128 v[156:159], v156 offset:3072
	s_add_u32 s18, s18, 0x80000
	s_addc_u32 s19, s19, 0
	s_mov_b32 m0, s38
	v_lshl_add_u64 v[246:247], s[18:19], 0, v[190:191]
	ds_read_b128 v[160:163], v209 offset:32768
	ds_read_b128 v[164:167], v209 offset:33792
	ds_read_b128 v[196:199], v209 offset:34816
	ds_read_b128 v[200:203], v209 offset:35840
	ds_read_b128 v[210:213], v209 offset:36864
	ds_read_b128 v[230:233], v209 offset:37888
	ds_read_b128 v[234:237], v209 offset:38912
	ds_read_b128 v[238:241], v209 offset:39936
	global_load_lds_dwordx4 v[246:247], off
	v_lshl_add_u64 v[246:247], s[18:19], 0, v[186:187]
	s_mov_b32 m0, s39
	s_nop 0
	global_load_lds_dwordx4 v[246:247], off
	s_waitcnt vmcnt(8)
	s_waitcnt lgkmcnt(0)
	s_barrier
	v_mfma_f32_16x16x32_bf16 v[140:143], v[64:67], v[160:163], v[140:143]
	v_mfma_f32_16x16x32_bf16 v[136:139], v[72:75], v[160:163], v[136:139]
	v_mfma_f32_16x16x32_bf16 v[124:127], v[64:67], v[196:199], v[124:127]
	v_mfma_f32_16x16x32_bf16 v[120:123], v[72:75], v[196:199], v[120:123]
	v_mfma_f32_16x16x32_bf16 v[108:111], v[64:67], v[210:213], v[108:111]
	v_mfma_f32_16x16x32_bf16 v[104:107], v[72:75], v[210:213], v[104:107]
	v_mfma_f32_16x16x32_bf16 v[96:99], v[64:67], v[234:237], v[96:99]
	v_mfma_f32_16x16x32_bf16 v[88:91], v[72:75], v[234:237], v[88:91]
	v_mfma_f32_16x16x32_bf16 v[140:143], v[68:71], v[164:167], v[140:143]
	v_mfma_f32_16x16x32_bf16 v[136:139], v[76:79], v[164:167], v[136:139]
	v_mfma_f32_16x16x32_bf16 v[124:127], v[68:71], v[200:203], v[124:127]
	v_mfma_f32_16x16x32_bf16 v[120:123], v[76:79], v[200:203], v[120:123]
	v_mfma_f32_16x16x32_bf16 v[108:111], v[68:71], v[230:233], v[108:111]
	v_mfma_f32_16x16x32_bf16 v[104:107], v[76:79], v[230:233], v[104:107]
	v_mfma_f32_16x16x32_bf16 v[96:99], v[68:71], v[238:241], v[96:99]
	v_mfma_f32_16x16x32_bf16 v[88:91], v[76:79], v[238:241], v[88:91]
	v_mfma_f32_16x16x32_bf16 v[132:135], v[144:147], v[160:163], v[132:135]
	v_mfma_f32_16x16x32_bf16 v[128:131], v[152:155], v[160:163], v[128:131]
	v_mfma_f32_16x16x32_bf16 v[116:119], v[144:147], v[196:199], v[116:119]
	v_mfma_f32_16x16x32_bf16 v[112:115], v[152:155], v[196:199], v[112:115]
	v_mfma_f32_16x16x32_bf16 v[100:103], v[144:147], v[210:213], v[100:103]
	v_mfma_f32_16x16x32_bf16 v[92:95], v[152:155], v[210:213], v[92:95]
	v_mfma_f32_16x16x32_bf16 v[84:87], v[144:147], v[234:237], v[84:87]
	v_mfma_f32_16x16x32_bf16 v[80:83], v[152:155], v[234:237], v[80:83]
	v_mfma_f32_16x16x32_bf16 v[132:135], v[148:151], v[164:167], v[132:135]
	v_mfma_f32_16x16x32_bf16 v[128:131], v[156:159], v[164:167], v[128:131]
	v_mfma_f32_16x16x32_bf16 v[116:119], v[148:151], v[200:203], v[116:119]
	v_mfma_f32_16x16x32_bf16 v[112:115], v[156:159], v[200:203], v[112:115]
	v_mfma_f32_16x16x32_bf16 v[100:103], v[148:151], v[230:233], v[100:103]
	v_mfma_f32_16x16x32_bf16 v[92:95], v[156:159], v[230:233], v[92:95]
	v_mfma_f32_16x16x32_bf16 v[84:87], v[148:151], v[238:241], v[84:87]
	v_mfma_f32_16x16x32_bf16 v[80:83], v[156:159], v[238:241], v[80:83]
	s_barrier
; #define PG8_STAGE(bufoff, gbase, voff) do { _Pragma("unroll") for (int _i = 0; _i < 2; ++_i) \
;         __builtin_amdgcn_global_load_lds((const unsigned*)((const char*)(gbase) + (voff)[_i]), (LAS unsigned*)(lds + (bufoff) + ldsw + _i * 8192), 16, 0, 0); } while (0)
; #define PG8_LDA(dst, b, h) do { _Pragma("unroll") for (int m = 0; m < 4; ++m) _Pragma("unroll") for (int k = 0; k < 2; ++k) dst[m][k] = *(const LAS bf16x8*)(lds + PG8_SA(b, h) + aoff + m * 2048 + k * 1024); } while (0)
; #define PG8_MMA(ai, bj, At, Bt) do { __builtin_amdgcn_s_setprio(1); _Pragma("unroll") for (int m = 0; m < 4; ++m) _Pragma("unroll") for (int n = 0; n < 2; ++n) _Pragma("unroll") for (int k = 0; k < 2; ++k) \
;         acc[ai][bj][m][n] = __builtin_amdgcn_mfma_f32_16x16x32_bf16(Bt[n][k], At[m][k], acc[ai][bj][m][n], 0, 0, 0); __builtin_amdgcn_s_setprio(0); } while (0)
; #define PG8_WAIT_V(n) asm volatile("s_waitcnt vmcnt(" #n ")" ::: "memory")
; #define PG8_WAIT_L(n) asm volatile("s_waitcnt lgkmcnt(" #n ")" ::: "memory")
; #define PG8_BAR __builtin_amdgcn_s_barrier()
; #define PG8_SCHED __builtin_amdgcn_sched_barrier(0)
; template <class Epi>
; __device__ __forceinline__ void gemm_phase(LAS unsigned char* lds, const Gemm g, const StaticOrder& S, const Epi& E, const int tid) {
;     ...
;             PG8_LDA(At, 1, 1); PG8_STAGE(PG8_SB(1, 0), b3, voffB); PG8_STAGE(PG8_SB(1, 1), b3 + hsB, voffB); PG8_STAGE(PG8_SA(1, 0), a3, voffA);
;             PG8_WAIT_V(8); PG8_WAIT_L(0); PG8_BAR; PG8_MMA(1, 0, At, B0); PG8_MMA(1, 1, At, B1); PG8_BAR; PG8_SCHED;
;         }
;         if (wr == 0) PG8_BAR;
	s_add_i32 s2, s2, s35
	v_lshl_add_u64 v[170:171], v[170:171], 0, s[28:29]
	s_mov_b32 m0, s2
	ds_read_b128 v[160:163], v209 offset:49152
	ds_read_b128 v[164:167], v209 offset:50176
	ds_read_b128 v[196:199], v209 offset:51200
	ds_read_b128 v[200:203], v209 offset:52224
	ds_read_b128 v[210:213], v209 offset:53248
	ds_read_b128 v[230:233], v209 offset:54272
	ds_read_b128 v[234:237], v209 offset:55296
	ds_read_b128 v[238:241], v209 offset:56320
	global_load_lds_dwordx4 v[170:171], off
	s_add_i32 m0, s2, 0x2000
	s_add_u32 s0, s0, 0x80080
	v_lshl_add_u64 v[170:171], v[172:173], 0, s[28:29]
	s_addc_u32 s1, s1, 0
	s_add_i32 s2, s24, s35
	global_load_lds_dwordx4 v[170:171], off
	v_lshl_add_u64 v[170:171], s[0:1], 0, v[188:189]
	s_mov_b32 m0, s2
	s_nop 0
	global_load_lds_dwordx4 v[170:171], off
	v_lshl_add_u64 v[170:171], s[0:1], 0, v[184:185]
	s_add_i32 m0, s2, 0x2000
	s_nop 0
	global_load_lds_dwordx4 v[170:171], off
	v_lshl_add_u64 v[170:171], v[242:243], 0, s[28:29]
	s_mov_b32 m0, s44
	s_nop 0
	global_load_lds_dwordx4 v[170:171], off
	v_lshl_add_u64 v[170:171], v[244:245], 0, s[28:29]
	s_mov_b32 m0, s45
	s_nop 0
	global_load_lds_dwordx4 v[170:171], off
	s_waitcnt vmcnt(8)
	s_waitcnt lgkmcnt(0)
	s_barrier
	v_mfma_f32_16x16x32_bf16 v[60:63], v[64:67], v[160:163], v[60:63]
	v_mfma_f32_16x16x32_bf16 v[56:59], v[72:75], v[160:163], v[56:59]
	v_mfma_f32_16x16x32_bf16 v[44:47], v[64:67], v[196:199], v[44:47]
	v_mfma_f32_16x16x32_bf16 v[40:43], v[72:75], v[196:199], v[40:43]
	v_mfma_f32_16x16x32_bf16 v[28:31], v[64:67], v[210:213], v[28:31]
	v_mfma_f32_16x16x32_bf16 v[24:27], v[72:75], v[210:213], v[24:27]
	v_mfma_f32_16x16x32_bf16 v[12:15], v[64:67], v[234:237], v[12:15]
	v_mfma_f32_16x16x32_bf16 v[8:11], v[72:75], v[234:237], v[8:11]
	v_mfma_f32_16x16x32_bf16 v[60:63], v[68:71], v[164:167], v[60:63]
	v_mfma_f32_16x16x32_bf16 v[56:59], v[76:79], v[164:167], v[56:59]
	v_mfma_f32_16x16x32_bf16 v[44:47], v[68:71], v[200:203], v[44:47]
	v_mfma_f32_16x16x32_bf16 v[40:43], v[76:79], v[200:203], v[40:43]
	v_mfma_f32_16x16x32_bf16 v[28:31], v[68:71], v[230:233], v[28:31]
	v_mfma_f32_16x16x32_bf16 v[24:27], v[76:79], v[230:233], v[24:27]
	v_mfma_f32_16x16x32_bf16 v[12:15], v[68:71], v[238:241], v[12:15]
	v_mfma_f32_16x16x32_bf16 v[8:11], v[76:79], v[238:241], v[8:11]
	v_mfma_f32_16x16x32_bf16 v[52:55], v[144:147], v[160:163], v[52:55]
	v_mfma_f32_16x16x32_bf16 v[48:51], v[152:155], v[160:163], v[48:51]
	v_mfma_f32_16x16x32_bf16 v[36:39], v[144:147], v[196:199], v[36:39]
	v_mfma_f32_16x16x32_bf16 v[32:35], v[152:155], v[196:199], v[32:35]
	v_mfma_f32_16x16x32_bf16 v[20:23], v[144:147], v[210:213], v[20:23]
	v_mfma_f32_16x16x32_bf16 v[16:19], v[152:155], v[210:213], v[16:19]
	v_mfma_f32_16x16x32_bf16 v[4:7], v[144:147], v[234:237], v[4:7]
	v_mfma_f32_16x16x32_bf16 v[0:3], v[152:155], v[234:237], v[0:3]
	v_mfma_f32_16x16x32_bf16 v[52:55], v[148:151], v[164:167], v[52:55]
	v_mfma_f32_16x16x32_bf16 v[48:51], v[156:159], v[164:167], v[48:51]
	v_mfma_f32_16x16x32_bf16 v[36:39], v[148:151], v[200:203], v[36:39]
	v_mfma_f32_16x16x32_bf16 v[32:35], v[156:159], v[200:203], v[32:35]
	v_mfma_f32_16x16x32_bf16 v[20:23], v[148:151], v[230:233], v[20:23]
	v_mfma_f32_16x16x32_bf16 v[16:19], v[156:159], v[230:233], v[16:19]
	v_mfma_f32_16x16x32_bf16 v[4:7], v[148:151], v[238:241], v[4:7]
	v_mfma_f32_16x16x32_bf16 v[0:3], v[156:159], v[238:241], v[0:3]
	s_barrier
	s_add_i32 s57, s57, 2
	s_add_u32 s16, s16, 0x100
	s_addc_u32 s17, s17, 0
	s_add_u32 s53, s53, 0x100
	s_addc_u32 s56, s56, 0
	s_cmp_gt_u32 s57, 29
	s_cbranch_scc0 .LBB0_893
	s_and_b64 vcc, exec, s[6:7]
	s_movk_i32 s49, 0x300
	s_mov_b64 s[52:53], 0x60000
	s_cbranch_vccz .LBB0_896
	s_barrier

; #define PG8_STAGE(bufoff, gbase, voff) do { _Pragma("unroll") for (int _i = 0; _i < 2; ++_i) \
;         __builtin_amdgcn_global_load_lds((const unsigned*)((const char*)(gbase) + (voff)[_i]), (LAS unsigned*)(lds + (bufoff) + ldsw + _i * 8192), 16, 0, 0); } while (0)
; #define PG8_LDA(dst, b, h) do { _Pragma("unroll") for (int m = 0; m < 4; ++m) _Pragma("unroll") for (int k = 0; k < 2; ++k) dst[m][k] = *(const LAS bf16x8*)(lds + PG8_SA(b, h) + aoff + m * 2048 + k * 1024); } while (0)
; #define PG8_LDB(dst, b, h) do { _Pragma("unroll") for (int n = 0; n < 2; ++n) _Pragma("unroll") for (int k = 0; k < 2; ++k) dst[n][k] = *(const LAS bf16x8*)(lds + PG8_SB(b, h) + boff + n * 2048 + k * 1024); } while (0)
; #define PG8_MMA(ai, bj, At, Bt) do { __builtin_amdgcn_s_setprio(1); _Pragma("unroll") for (int m = 0; m < 4; ++m) _Pragma("unroll") for (int n = 0; n < 2; ++n) _Pragma("unroll") for (int k = 0; k < 2; ++k) \
;         acc[ai][bj][m][n] = __builtin_amdgcn_mfma_f32_16x16x32_bf16(Bt[n][k], At[m][k], acc[ai][bj][m][n], 0, 0, 0); __builtin_amdgcn_s_setprio(0); } while (0)
; #define PG8_WAIT_V(n) asm volatile("s_waitcnt vmcnt(" #n ")" ::: "memory")
; #define PG8_WAIT_L(n) asm volatile("s_waitcnt lgkmcnt(" #n ")" ::: "memory")
; #define PG8_BAR __builtin_amdgcn_s_barrier()
; #define PG8_SCHED __builtin_amdgcn_sched_barrier(0)
; template <class Epi>
; __device__ __forceinline__ void gemm_phase(LAS unsigned char* lds, const Gemm g, const StaticOrder& S, const Epi& E, const int tid) {
;     ...
;             const char* a1 = cA + (size_t)(t + 1) * kstep;
;             const char* a2 = last ? nA : cA + (size_t)(t + 2) * kstep; const char* b2 = last ? nB : cB + (size_t)(t + 2) * kstep;
;             const char* a3 = a2 + kstep; const char* b3 = b2 + kstep;
;             PG8_LDB(B0, 0, 0); PG8_LDB(B1, 0, 1); PG8_SCHED; PG8_LDA(At, 0, 0); PG8_STAGE(PG8_SA(1, 1), a1 + hsA, voffA);
;             PG8_WAIT_V(8); PG8_WAIT_L(0); PG8_BAR; PG8_MMA(0, 0, At, B0); PG8_MMA(0, 1, At, B1); PG8_BAR; PG8_SCHED;
;             PG8_LDA(At, 0, 1); PG8_STAGE(PG8_SB(0, 0), b2, voffB); PG8_STAGE(PG8_SB(0, 1), b2 + hsB, voffB); PG8_STAGE(PG8_SA(0, 0), a2, voffA);
;             PG8_WAIT_V(8); PG8_WAIT_L(0); PG8_BAR; PG8_MMA(1, 0, At, B0); PG8_MMA(1, 1, At, B1); PG8_BAR; PG8_SCHED;
.Lgprio_f:
.LBB0_1004:
	s_add_u32 s0, s18, 0xfff80080
	s_addc_u32 s1, s19, -1
	s_add_i32 s2, 0, 0x10000
	s_cmp_eq_u32 s57, 28
	s_cselect_b32 s35, s13, s1
	s_cselect_b32 s34, s49, s0
	s_cselect_b32 s1, s11, s56
	s_cselect_b32 s0, s52, s53
	s_add_i32 s55, 0, 0x14000
	v_add_u32_e32 v154, s2, v143
	v_add_u32_e32 v166, s55, v143
	ds_read_b128 v[138:141], v154
	ds_read_b128 v[146:149], v154 offset:1024
	ds_read_b128 v[150:153], v154 offset:2048
	ds_read_b128 v[154:157], v154 offset:3072
	ds_read_b128 v[158:161], v166
	ds_read_b128 v[162:165], v166 offset:1024
	ds_read_b128 v[184:187], v166 offset:2048
	ds_read_b128 v[188:191], v166 offset:3072
	v_lshl_add_u64 v[166:167], s[18:19], 0, v[134:135]
	s_add_i32 m0, s40, 0xc000
	ds_read_b128 v[192:195], v145
	ds_read_b128 v[196:199], v145 offset:1024
	ds_read_b128 v[200:203], v145 offset:2048
	ds_read_b128 v[204:207], v145 offset:3072
	ds_read_b128 v[208:211], v145 offset:4096
	ds_read_b128 v[230:233], v145 offset:5120
	ds_read_b128 v[234:237], v145 offset:6144
	ds_read_b128 v[238:241], v145 offset:7168
	global_load_lds_dwordx4 v[166:167], off
	v_lshl_add_u64 v[166:167], s[18:19], 0, v[136:137]
	s_add_i32 m0, s40, 0xe000
	s_nop 0
	global_load_lds_dwordx4 v[166:167], off
	s_waitcnt vmcnt(8)
	s_waitcnt lgkmcnt(0)
	s_barrier
	v_mfma_f32_16x16x32_bf16 v[124:127], v[138:141], v[192:195], v[124:127]
	v_mfma_f32_16x16x32_bf16 v[116:119], v[150:153], v[192:195], v[116:119]
	v_mfma_f32_16x16x32_bf16 v[108:111], v[138:141], v[200:203], v[108:111]
	v_mfma_f32_16x16x32_bf16 v[100:103], v[150:153], v[200:203], v[100:103]
	v_mfma_f32_16x16x32_bf16 v[92:95], v[138:141], v[208:211], v[92:95]
	v_mfma_f32_16x16x32_bf16 v[84:87], v[150:153], v[208:211], v[84:87]
	v_mfma_f32_16x16x32_bf16 v[76:79], v[138:141], v[234:237], v[76:79]
	v_mfma_f32_16x16x32_bf16 v[68:71], v[150:153], v[234:237], v[68:71]
	v_mfma_f32_16x16x32_bf16 v[124:127], v[146:149], v[196:199], v[124:127]
	v_mfma_f32_16x16x32_bf16 v[116:119], v[154:157], v[196:199], v[116:119]
	v_mfma_f32_16x16x32_bf16 v[108:111], v[146:149], v[204:207], v[108:111]
	v_mfma_f32_16x16x32_bf16 v[100:103], v[154:157], v[204:207], v[100:103]
	v_mfma_f32_16x16x32_bf16 v[92:95], v[146:149], v[230:233], v[92:95]
	v_mfma_f32_16x16x32_bf16 v[84:87], v[154:157], v[230:233], v[84:87]
	v_mfma_f32_16x16x32_bf16 v[76:79], v[146:149], v[238:241], v[76:79]
	v_mfma_f32_16x16x32_bf16 v[68:71], v[154:157], v[238:241], v[68:71]
	v_mfma_f32_16x16x32_bf16 v[120:123], v[158:161], v[192:195], v[120:123]
	v_mfma_f32_16x16x32_bf16 v[112:115], v[184:187], v[192:195], v[112:115]
	v_mfma_f32_16x16x32_bf16 v[104:107], v[158:161], v[200:203], v[104:107]
	v_mfma_f32_16x16x32_bf16 v[96:99], v[184:187], v[200:203], v[96:99]
	v_mfma_f32_16x16x32_bf16 v[88:91], v[158:161], v[208:211], v[88:91]
	v_mfma_f32_16x16x32_bf16 v[80:83], v[184:187], v[208:211], v[80:83]
	v_mfma_f32_16x16x32_bf16 v[72:75], v[158:161], v[234:237], v[72:75]
	v_mfma_f32_16x16x32_bf16 v[64:67], v[184:187], v[234:237], v[64:67]
	v_mfma_f32_16x16x32_bf16 v[120:123], v[162:165], v[196:199], v[120:123]
	v_mfma_f32_16x16x32_bf16 v[112:115], v[188:191], v[196:199], v[112:115]
	v_mfma_f32_16x16x32_bf16 v[104:107], v[162:165], v[204:207], v[104:107]
	v_mfma_f32_16x16x32_bf16 v[96:99], v[188:191], v[204:207], v[96:99]
	v_mfma_f32_16x16x32_bf16 v[88:91], v[162:165], v[230:233], v[88:91]
	v_mfma_f32_16x16x32_bf16 v[80:83], v[188:191], v[230:233], v[80:83]
	v_mfma_f32_16x16x32_bf16 v[72:75], v[162:165], v[238:241], v[72:75]
	v_mfma_f32_16x16x32_bf16 v[64:67], v[188:191], v[238:241], v[64:67]
	s_barrier
	s_add_i32 s2, s2, s27
	v_lshl_add_u64 v[166:167], s[0:1], 0, v[168:169]
	s_mov_b32 m0, s2
	ds_read_b128 v[192:195], v145 offset:16384
	ds_read_b128 v[196:199], v145 offset:17408
	ds_read_b128 v[200:203], v145 offset:18432
	ds_read_b128 v[204:207], v145 offset:19456
	ds_read_b128 v[208:211], v145 offset:20480
	ds_read_b128 v[230:233], v145 offset:21504
	ds_read_b128 v[234:237], v145 offset:22528
	ds_read_b128 v[238:241], v145 offset:23552
	global_load_lds_dwordx4 v[166:167], off
	s_add_i32 m0, s2, 0x2000
	s_add_u32 s24, s0, 0x80000
	v_lshl_add_u64 v[170:171], s[0:1], 0, v[132:133]
	s_addc_u32 s25, s1, 0
	s_add_i32 s2, s55, s27
	global_load_lds_dwordx4 v[170:171], off
	v_lshl_add_u64 v[172:173], s[24:25], 0, v[168:169]
	s_mov_b32 m0, s2
	v_lshl_add_u64 v[212:213], s[34:35], 0, v[130:131]
	global_load_lds_dwordx4 v[172:173], off
	v_lshl_add_u64 v[172:173], s[24:25], 0, v[132:133]
	s_add_i32 m0, s2, 0x2000
	s_nop 0
	global_load_lds_dwordx4 v[172:173], off
	v_lshl_add_u64 v[172:173], s[34:35], 0, v[128:129]
	s_mov_b32 m0, s40
	s_nop 0
	global_load_lds_dwordx4 v[172:173], off
	s_mov_b32 m0, s41
	s_nop 0
	global_load_lds_dwordx4 v[212:213], off
	s_waitcnt vmcnt(8)
	s_waitcnt lgkmcnt(0)
	s_barrier
; #define PG8_STAGE(bufoff, gbase, voff) do { _Pragma("unroll") for (int _i = 0; _i < 2; ++_i) \
;         __builtin_amdgcn_global_load_lds((const unsigned*)((const char*)(gbase) + (voff)[_i]), (LAS unsigned*)(lds + (bufoff) + ldsw + _i * 8192), 16, 0, 0); } while (0)
; #define PG8_LDA(dst, b, h) do { _Pragma("unroll") for (int m = 0; m < 4; ++m) _Pragma("unroll") for (int k = 0; k < 2; ++k) dst[m][k] = *(const LAS bf16x8*)(lds + PG8_SA(b, h) + aoff + m * 2048 + k * 1024); } while (0)
; #define PG8_LDB(dst, b, h) do { _Pragma("unroll") for (int n = 0; n < 2; ++n) _Pragma("unroll") for (int k = 0; k < 2; ++k) dst[n][k] = *(const LAS bf16x8*)(lds + PG8_SB(b, h) + boff + n * 2048 + k * 1024); } while (0)
; #define PG8_MMA(ai, bj, At, Bt) do { __builtin_amdgcn_s_setprio(1); _Pragma("unroll") for (int m = 0; m < 4; ++m) _Pragma("unroll") for (int n = 0; n < 2; ++n) _Pragma("unroll") for (int k = 0; k < 2; ++k) \
;         acc[ai][bj][m][n] = __builtin_amdgcn_mfma_f32_16x16x32_bf16(Bt[n][k], At[m][k], acc[ai][bj][m][n], 0, 0, 0); __builtin_amdgcn_s_setprio(0); } while (0)
; #define PG8_WAIT_V(n) asm volatile("s_waitcnt vmcnt(" #n ")" ::: "memory")
; #define PG8_WAIT_L(n) asm volatile("s_waitcnt lgkmcnt(" #n ")" ::: "memory")
; #define PG8_BAR __builtin_amdgcn_s_barrier()
; #define PG8_SCHED __builtin_amdgcn_sched_barrier(0)
; template <class Epi>
; __device__ __forceinline__ void gemm_phase(LAS unsigned char* lds, const Gemm g, const StaticOrder& S, const Epi& E, const int tid) {
;     ...
;             PG8_WAIT_V(8); PG8_WAIT_L(0); PG8_BAR; PG8_MMA(1, 0, At, B0); PG8_MMA(1, 1, At, B1); PG8_BAR; PG8_SCHED;
;             PG8_LDB(B0, 1, 0); PG8_LDB(B1, 1, 1); PG8_SCHED; PG8_LDA(At, 1, 0); PG8_STAGE(PG8_SA(0, 1), a2 + hsA, voffA);
;             PG8_WAIT_V(8); PG8_WAIT_L(0); PG8_BAR; PG8_MMA(0, 0, At, B0); PG8_MMA(0, 1, At, B1); PG8_BAR; PG8_SCHED;
	v_mfma_f32_16x16x32_bf16 v[60:63], v[138:141], v[192:195], v[60:63]
	v_mfma_f32_16x16x32_bf16 v[52:55], v[150:153], v[192:195], v[52:55]
	v_mfma_f32_16x16x32_bf16 v[44:47], v[138:141], v[200:203], v[44:47]
	v_mfma_f32_16x16x32_bf16 v[36:39], v[150:153], v[200:203], v[36:39]
	v_mfma_f32_16x16x32_bf16 v[28:31], v[138:141], v[208:211], v[28:31]
	v_mfma_f32_16x16x32_bf16 v[20:23], v[150:153], v[208:211], v[20:23]
	v_mfma_f32_16x16x32_bf16 v[12:15], v[138:141], v[234:237], v[12:15]
	v_mfma_f32_16x16x32_bf16 v[4:7], v[150:153], v[234:237], v[4:7]
	v_mfma_f32_16x16x32_bf16 v[60:63], v[146:149], v[196:199], v[60:63]
	v_mfma_f32_16x16x32_bf16 v[52:55], v[154:157], v[196:199], v[52:55]
	v_mfma_f32_16x16x32_bf16 v[44:47], v[146:149], v[204:207], v[44:47]
	v_mfma_f32_16x16x32_bf16 v[36:39], v[154:157], v[204:207], v[36:39]
	v_mfma_f32_16x16x32_bf16 v[28:31], v[146:149], v[230:233], v[28:31]
	v_mfma_f32_16x16x32_bf16 v[20:23], v[154:157], v[230:233], v[20:23]
	v_mfma_f32_16x16x32_bf16 v[12:15], v[146:149], v[238:241], v[12:15]
	v_mfma_f32_16x16x32_bf16 v[4:7], v[154:157], v[238:241], v[4:7]
	v_mfma_f32_16x16x32_bf16 v[56:59], v[158:161], v[192:195], v[56:59]
	v_mfma_f32_16x16x32_bf16 v[48:51], v[184:187], v[192:195], v[48:51]
	v_mfma_f32_16x16x32_bf16 v[40:43], v[158:161], v[200:203], v[40:43]
	v_mfma_f32_16x16x32_bf16 v[32:35], v[184:187], v[200:203], v[32:35]
	v_mfma_f32_16x16x32_bf16 v[24:27], v[158:161], v[208:211], v[24:27]
	v_mfma_f32_16x16x32_bf16 v[16:19], v[184:187], v[208:211], v[16:19]
	v_mfma_f32_16x16x32_bf16 v[8:11], v[158:161], v[234:237], v[8:11]
	v_mfma_f32_16x16x32_bf16 v[0:3], v[184:187], v[234:237], v[0:3]
	v_mfma_f32_16x16x32_bf16 v[56:59], v[162:165], v[196:199], v[56:59]
	v_mfma_f32_16x16x32_bf16 v[48:51], v[188:191], v[196:199], v[48:51]
	v_mfma_f32_16x16x32_bf16 v[40:43], v[162:165], v[204:207], v[40:43]
	v_mfma_f32_16x16x32_bf16 v[32:35], v[188:191], v[204:207], v[32:35]
	v_mfma_f32_16x16x32_bf16 v[24:27], v[162:165], v[230:233], v[24:27]
	v_mfma_f32_16x16x32_bf16 v[16:19], v[188:191], v[230:233], v[16:19]
	v_mfma_f32_16x16x32_bf16 v[8:11], v[162:165], v[238:241], v[8:11]
	v_mfma_f32_16x16x32_bf16 v[0:3], v[188:191], v[238:241], v[0:3]
	s_barrier
	s_add_i32 s2, 0, 0x18000
	s_add_i32 s55, 0, 0x1c000
	v_add_u32_e32 v154, s2, v143
	v_add_u32_e32 v188, s55, v143
	ds_read_b128 v[138:141], v154
	ds_read_b128 v[146:149], v154 offset:1024
	ds_read_b128 v[150:153], v154 offset:2048
	ds_read_b128 v[154:157], v154 offset:3072
	ds_read_b128 v[158:161], v188
	ds_read_b128 v[162:165], v188 offset:1024
	ds_read_b128 v[184:187], v188 offset:2048
	ds_read_b128 v[188:191], v188 offset:3072
	s_add_u32 s24, s34, 0x80000
	s_addc_u32 s25, s35, 0
	s_mov_b32 m0, s42
	v_lshl_add_u64 v[242:243], s[24:25], 0, v[128:129]
	ds_read_b128 v[192:195], v145 offset:32768
	ds_read_b128 v[196:199], v145 offset:33792
	ds_read_b128 v[200:203], v145 offset:34816
	ds_read_b128 v[204:207], v145 offset:35840
	ds_read_b128 v[208:211], v145 offset:36864
	ds_read_b128 v[230:233], v145 offset:37888
	ds_read_b128 v[234:237], v145 offset:38912
	ds_read_b128 v[238:241], v145 offset:39936
	global_load_lds_dwordx4 v[242:243], off
	v_lshl_add_u64 v[242:243], s[24:25], 0, v[130:131]
	s_mov_b32 m0, s43
	s_nop 0
	global_load_lds_dwordx4 v[242:243], off
	s_waitcnt vmcnt(8)
	s_waitcnt lgkmcnt(0)
	s_barrier
	v_mfma_f32_16x16x32_bf16 v[124:127], v[138:141], v[192:195], v[124:127]
	v_mfma_f32_16x16x32_bf16 v[116:119], v[150:153], v[192:195], v[116:119]
	v_mfma_f32_16x16x32_bf16 v[108:111], v[138:141], v[200:203], v[108:111]
	v_mfma_f32_16x16x32_bf16 v[100:103], v[150:153], v[200:203], v[100:103]
	v_mfma_f32_16x16x32_bf16 v[92:95], v[138:141], v[208:211], v[92:95]
	v_mfma_f32_16x16x32_bf16 v[84:87], v[150:153], v[208:211], v[84:87]
	v_mfma_f32_16x16x32_bf16 v[76:79], v[138:141], v[234:237], v[76:79]
	v_mfma_f32_16x16x32_bf16 v[68:71], v[150:153], v[234:237], v[68:71]
	v_mfma_f32_16x16x32_bf16 v[124:127], v[146:149], v[196:199], v[124:127]
	v_mfma_f32_16x16x32_bf16 v[116:119], v[154:157], v[196:199], v[116:119]
	v_mfma_f32_16x16x32_bf16 v[108:111], v[146:149], v[204:207], v[108:111]
	v_mfma_f32_16x16x32_bf16 v[100:103], v[154:157], v[204:207], v[100:103]
	v_mfma_f32_16x16x32_bf16 v[92:95], v[146:149], v[230:233], v[92:95]
	v_mfma_f32_16x16x32_bf16 v[84:87], v[154:157], v[230:233], v[84:87]
	v_mfma_f32_16x16x32_bf16 v[76:79], v[146:149], v[238:241], v[76:79]
	v_mfma_f32_16x16x32_bf16 v[68:71], v[154:157], v[238:241], v[68:71]
	v_mfma_f32_16x16x32_bf16 v[120:123], v[158:161], v[192:195], v[120:123]
	v_mfma_f32_16x16x32_bf16 v[112:115], v[184:187], v[192:195], v[112:115]
	v_mfma_f32_16x16x32_bf16 v[104:107], v[158:161], v[200:203], v[104:107]
	v_mfma_f32_16x16x32_bf16 v[96:99], v[184:187], v[200:203], v[96:99]
	v_mfma_f32_16x16x32_bf16 v[88:91], v[158:161], v[208:211], v[88:91]
	v_mfma_f32_16x16x32_bf16 v[80:83], v[184:187], v[208:211], v[80:83]
	v_mfma_f32_16x16x32_bf16 v[72:75], v[158:161], v[234:237], v[72:75]
	v_mfma_f32_16x16x32_bf16 v[64:67], v[184:187], v[234:237], v[64:67]
	v_mfma_f32_16x16x32_bf16 v[120:123], v[162:165], v[196:199], v[120:123]
	v_mfma_f32_16x16x32_bf16 v[112:115], v[188:191], v[196:199], v[112:115]
	v_mfma_f32_16x16x32_bf16 v[104:107], v[162:165], v[204:207], v[104:107]
	v_mfma_f32_16x16x32_bf16 v[96:99], v[188:191], v[204:207], v[96:99]
	v_mfma_f32_16x16x32_bf16 v[88:91], v[162:165], v[230:233], v[88:91]
	v_mfma_f32_16x16x32_bf16 v[80:83], v[188:191], v[230:233], v[80:83]
	v_mfma_f32_16x16x32_bf16 v[72:75], v[162:165], v[238:241], v[72:75]
	v_mfma_f32_16x16x32_bf16 v[64:67], v[188:191], v[238:241], v[64:67]
	s_barrier
; #define PG8_STAGE(bufoff, gbase, voff) do { _Pragma("unroll") for (int _i = 0; _i < 2; ++_i) \
;         __builtin_amdgcn_global_load_lds((const unsigned*)((const char*)(gbase) + (voff)[_i]), (LAS unsigned*)(lds + (bufoff) + ldsw + _i * 8192), 16, 0, 0); } while (0)
; #define PG8_LDA(dst, b, h) do { _Pragma("unroll") for (int m = 0; m < 4; ++m) _Pragma("unroll") for (int k = 0; k < 2; ++k) dst[m][k] = *(const LAS bf16x8*)(lds + PG8_SA(b, h) + aoff + m * 2048 + k * 1024); } while (0)
; #define PG8_MMA(ai, bj, At, Bt) do { __builtin_amdgcn_s_setprio(1); _Pragma("unroll") for (int m = 0; m < 4; ++m) _Pragma("unroll") for (int n = 0; n < 2; ++n) _Pragma("unroll") for (int k = 0; k < 2; ++k) \
;         acc[ai][bj][m][n] = __builtin_amdgcn_mfma_f32_16x16x32_bf16(Bt[n][k], At[m][k], acc[ai][bj][m][n], 0, 0, 0); __builtin_amdgcn_s_setprio(0); } while (0)
; #define PG8_WAIT_V(n) asm volatile("s_waitcnt vmcnt(" #n ")" ::: "memory")
; #define PG8_WAIT_L(n) asm volatile("s_waitcnt lgkmcnt(" #n ")" ::: "memory")
; #define PG8_BAR __builtin_amdgcn_s_barrier()
; #define PG8_SCHED __builtin_amdgcn_sched_barrier(0)
; template <class Epi>
; __device__ __forceinline__ void gemm_phase(LAS unsigned char* lds, const Gemm g, const StaticOrder& S, const Epi& E, const int tid) {
;     ...
;             PG8_LDA(At, 1, 1); PG8_STAGE(PG8_SB(1, 0), b3, voffB); PG8_STAGE(PG8_SB(1, 1), b3 + hsB, voffB); PG8_STAGE(PG8_SA(1, 0), a3, voffA);
;             PG8_WAIT_V(8); PG8_WAIT_L(0); PG8_BAR; PG8_MMA(1, 0, At, B0); PG8_MMA(1, 1, At, B1); PG8_BAR; PG8_SCHED;
;         }
;         if (wr == 0) PG8_BAR;
	s_add_i32 s2, s2, s27
	v_lshl_add_u64 v[166:167], v[166:167], 0, s[28:29]
	s_mov_b32 m0, s2
	ds_read_b128 v[192:195], v145 offset:49152
	ds_read_b128 v[196:199], v145 offset:50176
	ds_read_b128 v[200:203], v145 offset:51200
	ds_read_b128 v[204:207], v145 offset:52224
	ds_read_b128 v[208:211], v145 offset:53248
	ds_read_b128 v[230:233], v145 offset:54272
	ds_read_b128 v[234:237], v145 offset:55296
	ds_read_b128 v[238:241], v145 offset:56320
	global_load_lds_dwordx4 v[166:167], off
	s_add_i32 m0, s2, 0x2000
	s_add_u32 s0, s0, 0x80080
	v_lshl_add_u64 v[166:167], v[170:171], 0, s[28:29]
	s_addc_u32 s1, s1, 0
	s_add_i32 s2, s55, s27
	global_load_lds_dwordx4 v[166:167], off
	v_lshl_add_u64 v[166:167], s[0:1], 0, v[168:169]
	s_mov_b32 m0, s2
	s_nop 0
	global_load_lds_dwordx4 v[166:167], off
	v_lshl_add_u64 v[166:167], s[0:1], 0, v[132:133]
	s_add_i32 m0, s2, 0x2000
	s_nop 0
	global_load_lds_dwordx4 v[166:167], off
	v_lshl_add_u64 v[166:167], v[172:173], 0, s[28:29]
	s_mov_b32 m0, s44
	s_nop 0
	global_load_lds_dwordx4 v[166:167], off
	v_lshl_add_u64 v[166:167], v[212:213], 0, s[28:29]
	s_mov_b32 m0, s45
	s_nop 0
	global_load_lds_dwordx4 v[166:167], off
	s_waitcnt vmcnt(8)
	s_waitcnt lgkmcnt(0)
	s_barrier
	v_mfma_f32_16x16x32_bf16 v[60:63], v[138:141], v[192:195], v[60:63]
	v_mfma_f32_16x16x32_bf16 v[52:55], v[150:153], v[192:195], v[52:55]
	v_mfma_f32_16x16x32_bf16 v[44:47], v[138:141], v[200:203], v[44:47]
	v_mfma_f32_16x16x32_bf16 v[36:39], v[150:153], v[200:203], v[36:39]
	v_mfma_f32_16x16x32_bf16 v[28:31], v[138:141], v[208:211], v[28:31]
	v_mfma_f32_16x16x32_bf16 v[20:23], v[150:153], v[208:211], v[20:23]
	v_mfma_f32_16x16x32_bf16 v[12:15], v[138:141], v[234:237], v[12:15]
	v_mfma_f32_16x16x32_bf16 v[4:7], v[150:153], v[234:237], v[4:7]
	v_mfma_f32_16x16x32_bf16 v[60:63], v[146:149], v[196:199], v[60:63]
	v_mfma_f32_16x16x32_bf16 v[52:55], v[154:157], v[196:199], v[52:55]
	v_mfma_f32_16x16x32_bf16 v[44:47], v[146:149], v[204:207], v[44:47]
	v_mfma_f32_16x16x32_bf16 v[36:39], v[154:157], v[204:207], v[36:39]
	v_mfma_f32_16x16x32_bf16 v[28:31], v[146:149], v[230:233], v[28:31]
	v_mfma_f32_16x16x32_bf16 v[20:23], v[154:157], v[230:233], v[20:23]
	v_mfma_f32_16x16x32_bf16 v[12:15], v[146:149], v[238:241], v[12:15]
	v_mfma_f32_16x16x32_bf16 v[4:7], v[154:157], v[238:241], v[4:7]
	v_mfma_f32_16x16x32_bf16 v[56:59], v[158:161], v[192:195], v[56:59]
	v_mfma_f32_16x16x32_bf16 v[48:51], v[184:187], v[192:195], v[48:51]
	v_mfma_f32_16x16x32_bf16 v[40:43], v[158:161], v[200:203], v[40:43]
	v_mfma_f32_16x16x32_bf16 v[32:35], v[184:187], v[200:203], v[32:35]
	v_mfma_f32_16x16x32_bf16 v[24:27], v[158:161], v[208:211], v[24:27]
	v_mfma_f32_16x16x32_bf16 v[16:19], v[184:187], v[208:211], v[16:19]
	v_mfma_f32_16x16x32_bf16 v[8:11], v[158:161], v[234:237], v[8:11]
	v_mfma_f32_16x16x32_bf16 v[0:3], v[184:187], v[234:237], v[0:3]
	v_mfma_f32_16x16x32_bf16 v[56:59], v[162:165], v[196:199], v[56:59]
	v_mfma_f32_16x16x32_bf16 v[48:51], v[188:191], v[196:199], v[48:51]
	v_mfma_f32_16x16x32_bf16 v[40:43], v[162:165], v[204:207], v[40:43]
	v_mfma_f32_16x16x32_bf16 v[32:35], v[188:191], v[204:207], v[32:35]
	v_mfma_f32_16x16x32_bf16 v[24:27], v[162:165], v[230:233], v[24:27]
	v_mfma_f32_16x16x32_bf16 v[16:19], v[188:191], v[230:233], v[16:19]
	v_mfma_f32_16x16x32_bf16 v[8:11], v[162:165], v[238:241], v[8:11]
	v_mfma_f32_16x16x32_bf16 v[0:3], v[188:191], v[238:241], v[0:3]
	s_barrier
	s_add_i32 s57, s57, 2
	s_add_u32 s18, s18, 0x100
	s_addc_u32 s19, s19, 0
	s_add_u32 s53, s53, 0x100
	s_addc_u32 s56, s56, 0
	s_cmp_gt_u32 s57, 29
	s_cbranch_scc0 .LBB0_1004
	s_and_b64 vcc, exec, s[8:9]
	s_cbranch_vccz .LBB0_1007
	s_barrier

; #define PG8_STAGE(bufoff, gbase, voff) do { _Pragma("unroll") for (int _i = 0; _i < 2; ++_i) \
;         __builtin_amdgcn_global_load_lds((const unsigned*)((const char*)(gbase) + (voff)[_i]), (LAS unsigned*)(lds + (bufoff) + ldsw + _i * 8192), 16, 0, 0); } while (0)
; #define PG8_LDA(dst, b, h) do { _Pragma("unroll") for (int m = 0; m < 4; ++m) _Pragma("unroll") for (int k = 0; k < 2; ++k) dst[m][k] = *(const LAS bf16x8*)(lds + PG8_SA(b, h) + aoff + m * 2048 + k * 1024); } while (0)
; #define PG8_LDB(dst, b, h) do { _Pragma("unroll") for (int n = 0; n < 2; ++n) _Pragma("unroll") for (int k = 0; k < 2; ++k) dst[n][k] = *(const LAS bf16x8*)(lds + PG8_SB(b, h) + boff + n * 2048 + k * 1024); } while (0)
; #define PG8_MMA(ai, bj, At, Bt) do { __builtin_amdgcn_s_setprio(1); _Pragma("unroll") for (int m = 0; m < 4; ++m) _Pragma("unroll") for (int n = 0; n < 2; ++n) _Pragma("unroll") for (int k = 0; k < 2; ++k) \
;         acc[ai][bj][m][n] = __builtin_amdgcn_mfma_f32_16x16x32_bf16(Bt[n][k], At[m][k], acc[ai][bj][m][n], 0, 0, 0); __builtin_amdgcn_s_setprio(0); } while (0)
; #define PG8_WAIT_V(n) asm volatile("s_waitcnt vmcnt(" #n ")" ::: "memory")
; #define PG8_WAIT_L(n) asm volatile("s_waitcnt lgkmcnt(" #n ")" ::: "memory")
; #define PG8_BAR __builtin_amdgcn_s_barrier()
; #define PG8_SCHED __builtin_amdgcn_sched_barrier(0)
; template <class Epi>
; __device__ __forceinline__ void gemm_phase(LAS unsigned char* lds, const Gemm g, const StaticOrder& S, const Epi& E, const int tid) {
;     ...
;             const char* a1 = cA + (size_t)(t + 1) * kstep;
;             const char* a2 = last ? nA : cA + (size_t)(t + 2) * kstep; const char* b2 = last ? nB : cB + (size_t)(t + 2) * kstep;
;             const char* a3 = a2 + kstep; const char* b3 = b2 + kstep;
;             PG8_LDB(B0, 0, 0); PG8_LDB(B1, 0, 1); PG8_SCHED; PG8_LDA(At, 0, 0); PG8_STAGE(PG8_SA(1, 1), a1 + hsA, voffA);
;             PG8_WAIT_V(8); PG8_WAIT_L(0); PG8_BAR; PG8_MMA(0, 0, At, B0); PG8_MMA(0, 1, At, B1); PG8_BAR; PG8_SCHED;
;             PG8_LDA(At, 0, 1); PG8_STAGE(PG8_SB(0, 0), b2, voffB); PG8_STAGE(PG8_SB(0, 1), b2 + hsB, voffB); PG8_STAGE(PG8_SA(0, 0), a2, voffA);
;             PG8_WAIT_V(8); PG8_WAIT_L(0); PG8_BAR; PG8_MMA(1, 0, At, B0); PG8_MMA(1, 1, At, B1); PG8_BAR; PG8_SCHED;
.Lgprio_g:
.LBB0_1076:
	s_add_u32 s0, s12, 0x100
	s_addc_u32 s1, s13, 0
	s_add_i32 s2, 0, 0x10000
	s_cmpk_eq_i32 s53, 0x54
	s_cselect_b32 s17, s9, s1
	s_cselect_b32 s16, s8, s0
	s_cselect_b32 s15, s11, s39
	s_cselect_b32 s14, s10, s38
	s_add_i32 s24, 0, 0x14000
	v_add_u32_e32 v152, s2, v184
	v_add_u32_e32 v170, s24, v184
	ds_read_b128 v[128:131], v152
	ds_read_b128 v[144:147], v152 offset:1024
	ds_read_b128 v[148:151], v152 offset:2048
	ds_read_b128 v[152:155], v152 offset:3072
	ds_read_b128 v[156:159], v170
	ds_read_b128 v[160:163], v170 offset:1024
	ds_read_b128 v[164:167], v170 offset:2048
	ds_read_b128 v[190:193], v170 offset:3072
	v_lshl_add_u64 v[170:171], s[12:13], 0, v[140:141]
	s_add_i32 m0, s34, 0xc000
	ds_read_b128 v[194:197], v189
	ds_read_b128 v[198:201], v189 offset:1024
	ds_read_b128 v[202:205], v189 offset:2048
	ds_read_b128 v[206:209], v189 offset:3072
	ds_read_b128 v[210:213], v189 offset:4096
	ds_read_b128 v[230:233], v189 offset:5120
	ds_read_b128 v[234:237], v189 offset:6144
	ds_read_b128 v[238:241], v189 offset:7168
	global_load_lds_dwordx4 v[170:171], off
	v_lshl_add_u64 v[170:171], s[12:13], 0, v[142:143]
	s_add_i32 m0, s34, 0xe000
	s_nop 0
	global_load_lds_dwordx4 v[170:171], off
	s_waitcnt vmcnt(8)
	s_waitcnt lgkmcnt(0)
	s_barrier
	v_mfma_f32_16x16x32_bf16 v[124:127], v[128:131], v[194:197], v[124:127]
	v_mfma_f32_16x16x32_bf16 v[120:123], v[148:151], v[194:197], v[120:123]
	v_mfma_f32_16x16x32_bf16 v[108:111], v[128:131], v[202:205], v[108:111]
	v_mfma_f32_16x16x32_bf16 v[104:107], v[148:151], v[202:205], v[104:107]
	v_mfma_f32_16x16x32_bf16 v[92:95], v[128:131], v[210:213], v[92:95]
	v_mfma_f32_16x16x32_bf16 v[88:91], v[148:151], v[210:213], v[88:91]
	v_mfma_f32_16x16x32_bf16 v[80:83], v[128:131], v[234:237], v[80:83]
	v_mfma_f32_16x16x32_bf16 v[72:75], v[148:151], v[234:237], v[72:75]
	v_mfma_f32_16x16x32_bf16 v[124:127], v[144:147], v[198:201], v[124:127]
	v_mfma_f32_16x16x32_bf16 v[120:123], v[152:155], v[198:201], v[120:123]
	v_mfma_f32_16x16x32_bf16 v[108:111], v[144:147], v[206:209], v[108:111]
	v_mfma_f32_16x16x32_bf16 v[104:107], v[152:155], v[206:209], v[104:107]
	v_mfma_f32_16x16x32_bf16 v[92:95], v[144:147], v[230:233], v[92:95]
	v_mfma_f32_16x16x32_bf16 v[88:91], v[152:155], v[230:233], v[88:91]
	v_mfma_f32_16x16x32_bf16 v[80:83], v[144:147], v[238:241], v[80:83]
	v_mfma_f32_16x16x32_bf16 v[72:75], v[152:155], v[238:241], v[72:75]
	v_mfma_f32_16x16x32_bf16 v[116:119], v[156:159], v[194:197], v[116:119]
	v_mfma_f32_16x16x32_bf16 v[112:115], v[164:167], v[194:197], v[112:115]
	v_mfma_f32_16x16x32_bf16 v[100:103], v[156:159], v[202:205], v[100:103]
	v_mfma_f32_16x16x32_bf16 v[96:99], v[164:167], v[202:205], v[96:99]
	v_mfma_f32_16x16x32_bf16 v[84:87], v[156:159], v[210:213], v[84:87]
	v_mfma_f32_16x16x32_bf16 v[76:79], v[164:167], v[210:213], v[76:79]
	v_mfma_f32_16x16x32_bf16 v[68:71], v[156:159], v[234:237], v[68:71]
	v_mfma_f32_16x16x32_bf16 v[64:67], v[164:167], v[234:237], v[64:67]
	v_mfma_f32_16x16x32_bf16 v[116:119], v[160:163], v[198:201], v[116:119]
	v_mfma_f32_16x16x32_bf16 v[112:115], v[190:193], v[198:201], v[112:115]
	v_mfma_f32_16x16x32_bf16 v[100:103], v[160:163], v[206:209], v[100:103]
	v_mfma_f32_16x16x32_bf16 v[96:99], v[190:193], v[206:209], v[96:99]
	v_mfma_f32_16x16x32_bf16 v[84:87], v[160:163], v[230:233], v[84:87]
	v_mfma_f32_16x16x32_bf16 v[76:79], v[190:193], v[230:233], v[76:79]
	v_mfma_f32_16x16x32_bf16 v[68:71], v[160:163], v[238:241], v[68:71]
	v_mfma_f32_16x16x32_bf16 v[64:67], v[190:193], v[238:241], v[64:67]
	s_barrier
	s_add_i32 s2, s2, s27
	v_lshl_add_u64 v[170:171], s[14:15], 0, v[136:137]
	s_mov_b32 m0, s2
	ds_read_b128 v[194:197], v189 offset:16384
	ds_read_b128 v[198:201], v189 offset:17408
	ds_read_b128 v[202:205], v189 offset:18432
	ds_read_b128 v[206:209], v189 offset:19456
	ds_read_b128 v[210:213], v189 offset:20480
	ds_read_b128 v[230:233], v189 offset:21504
	ds_read_b128 v[234:237], v189 offset:22528
	ds_read_b128 v[238:241], v189 offset:23552
	global_load_lds_dwordx4 v[170:171], off
	s_add_i32 m0, s2, 0x2000
	s_add_u32 s12, s14, 0x160000
	v_lshl_add_u64 v[172:173], s[14:15], 0, v[132:133]
	s_addc_u32 s13, s15, 0
	s_add_i32 s2, s24, s27
	global_load_lds_dwordx4 v[172:173], off
	v_lshl_add_u64 v[242:243], s[12:13], 0, v[136:137]
	s_mov_b32 m0, s2
	v_lshl_add_u64 v[244:245], s[16:17], 0, v[134:135]
	global_load_lds_dwordx4 v[242:243], off
	v_lshl_add_u64 v[242:243], s[12:13], 0, v[132:133]
	s_add_i32 m0, s2, 0x2000
	s_nop 0
	global_load_lds_dwordx4 v[242:243], off
	v_lshl_add_u64 v[242:243], s[16:17], 0, v[138:139]
	s_mov_b32 m0, s34
	s_nop 0
	global_load_lds_dwordx4 v[242:243], off
	s_mov_b32 m0, s35
	s_nop 0
	global_load_lds_dwordx4 v[244:245], off
	s_waitcnt vmcnt(8)
	s_waitcnt lgkmcnt(0)
	s_barrier
; #define PG8_STAGE(bufoff, gbase, voff) do { _Pragma("unroll") for (int _i = 0; _i < 2; ++_i) \
;         __builtin_amdgcn_global_load_lds((const unsigned*)((const char*)(gbase) + (voff)[_i]), (LAS unsigned*)(lds + (bufoff) + ldsw + _i * 8192), 16, 0, 0); } while (0)
; #define PG8_LDA(dst, b, h) do { _Pragma("unroll") for (int m = 0; m < 4; ++m) _Pragma("unroll") for (int k = 0; k < 2; ++k) dst[m][k] = *(const LAS bf16x8*)(lds + PG8_SA(b, h) + aoff + m * 2048 + k * 1024); } while (0)
; #define PG8_LDB(dst, b, h) do { _Pragma("unroll") for (int n = 0; n < 2; ++n) _Pragma("unroll") for (int k = 0; k < 2; ++k) dst[n][k] = *(const LAS bf16x8*)(lds + PG8_SB(b, h) + boff + n * 2048 + k * 1024); } while (0)
; #define PG8_MMA(ai, bj, At, Bt) do { __builtin_amdgcn_s_setprio(1); _Pragma("unroll") for (int m = 0; m < 4; ++m) _Pragma("unroll") for (int n = 0; n < 2; ++n) _Pragma("unroll") for (int k = 0; k < 2; ++k) \
;         acc[ai][bj][m][n] = __builtin_amdgcn_mfma_f32_16x16x32_bf16(Bt[n][k], At[m][k], acc[ai][bj][m][n], 0, 0, 0); __builtin_amdgcn_s_setprio(0); } while (0)
; #define PG8_WAIT_V(n) asm volatile("s_waitcnt vmcnt(" #n ")" ::: "memory")
; #define PG8_WAIT_L(n) asm volatile("s_waitcnt lgkmcnt(" #n ")" ::: "memory")
; #define PG8_BAR __builtin_amdgcn_s_barrier()
; #define PG8_SCHED __builtin_amdgcn_sched_barrier(0)
; template <class Epi>
; __device__ __forceinline__ void gemm_phase(LAS unsigned char* lds, const Gemm g, const StaticOrder& S, const Epi& E, const int tid) {
;     ...
;             PG8_WAIT_V(8); PG8_WAIT_L(0); PG8_BAR; PG8_MMA(1, 0, At, B0); PG8_MMA(1, 1, At, B1); PG8_BAR; PG8_SCHED;
;             PG8_LDB(B0, 1, 0); PG8_LDB(B1, 1, 1); PG8_SCHED; PG8_LDA(At, 1, 0); PG8_STAGE(PG8_SA(0, 1), a2 + hsA, voffA);
;             PG8_WAIT_V(8); PG8_WAIT_L(0); PG8_BAR; PG8_MMA(0, 0, At, B0); PG8_MMA(0, 1, At, B1); PG8_BAR; PG8_SCHED;
	v_mfma_f32_16x16x32_bf16 v[60:63], v[128:131], v[194:197], v[60:63]
	v_mfma_f32_16x16x32_bf16 v[56:59], v[148:151], v[194:197], v[56:59]
	v_mfma_f32_16x16x32_bf16 v[44:47], v[128:131], v[202:205], v[44:47]
	v_mfma_f32_16x16x32_bf16 v[40:43], v[148:151], v[202:205], v[40:43]
	v_mfma_f32_16x16x32_bf16 v[28:31], v[128:131], v[210:213], v[28:31]
	v_mfma_f32_16x16x32_bf16 v[24:27], v[148:151], v[210:213], v[24:27]
	v_mfma_f32_16x16x32_bf16 v[12:15], v[128:131], v[234:237], v[12:15]
	v_mfma_f32_16x16x32_bf16 v[8:11], v[148:151], v[234:237], v[8:11]
	v_mfma_f32_16x16x32_bf16 v[60:63], v[144:147], v[198:201], v[60:63]
	v_mfma_f32_16x16x32_bf16 v[56:59], v[152:155], v[198:201], v[56:59]
	v_mfma_f32_16x16x32_bf16 v[44:47], v[144:147], v[206:209], v[44:47]
	v_mfma_f32_16x16x32_bf16 v[40:43], v[152:155], v[206:209], v[40:43]
	v_mfma_f32_16x16x32_bf16 v[28:31], v[144:147], v[230:233], v[28:31]
	v_mfma_f32_16x16x32_bf16 v[24:27], v[152:155], v[230:233], v[24:27]
	v_mfma_f32_16x16x32_bf16 v[12:15], v[144:147], v[238:241], v[12:15]
	v_mfma_f32_16x16x32_bf16 v[8:11], v[152:155], v[238:241], v[8:11]
	v_mfma_f32_16x16x32_bf16 v[52:55], v[156:159], v[194:197], v[52:55]
	v_mfma_f32_16x16x32_bf16 v[48:51], v[164:167], v[194:197], v[48:51]
	v_mfma_f32_16x16x32_bf16 v[36:39], v[156:159], v[202:205], v[36:39]
	v_mfma_f32_16x16x32_bf16 v[32:35], v[164:167], v[202:205], v[32:35]
	v_mfma_f32_16x16x32_bf16 v[20:23], v[156:159], v[210:213], v[20:23]
	v_mfma_f32_16x16x32_bf16 v[16:19], v[164:167], v[210:213], v[16:19]
	v_mfma_f32_16x16x32_bf16 v[4:7], v[156:159], v[234:237], v[4:7]
	v_mfma_f32_16x16x32_bf16 v[0:3], v[164:167], v[234:237], v[0:3]
	v_mfma_f32_16x16x32_bf16 v[52:55], v[160:163], v[198:201], v[52:55]
	v_mfma_f32_16x16x32_bf16 v[48:51], v[190:193], v[198:201], v[48:51]
	v_mfma_f32_16x16x32_bf16 v[36:39], v[160:163], v[206:209], v[36:39]
	v_mfma_f32_16x16x32_bf16 v[32:35], v[190:193], v[206:209], v[32:35]
	v_mfma_f32_16x16x32_bf16 v[20:23], v[160:163], v[230:233], v[20:23]
	v_mfma_f32_16x16x32_bf16 v[16:19], v[190:193], v[230:233], v[16:19]
	v_mfma_f32_16x16x32_bf16 v[4:7], v[160:163], v[238:241], v[4:7]
	v_mfma_f32_16x16x32_bf16 v[0:3], v[190:193], v[238:241], v[0:3]
	s_barrier
	s_add_i32 s2, 0, 0x18000
	s_add_i32 s24, 0, 0x1c000
	v_add_u32_e32 v152, s2, v184
	v_add_u32_e32 v190, s24, v184
	ds_read_b128 v[128:131], v152
	ds_read_b128 v[144:147], v152 offset:1024
	ds_read_b128 v[148:151], v152 offset:2048
	ds_read_b128 v[152:155], v152 offset:3072
	ds_read_b128 v[156:159], v190
	ds_read_b128 v[160:163], v190 offset:1024
	ds_read_b128 v[164:167], v190 offset:2048
	ds_read_b128 v[190:193], v190 offset:3072
	s_add_u32 s12, s16, 0x160000
	s_addc_u32 s13, s17, 0
	s_mov_b32 m0, s40
	v_lshl_add_u64 v[246:247], s[12:13], 0, v[138:139]
	ds_read_b128 v[194:197], v189 offset:32768
	ds_read_b128 v[198:201], v189 offset:33792
	ds_read_b128 v[202:205], v189 offset:34816
	ds_read_b128 v[206:209], v189 offset:35840
	ds_read_b128 v[210:213], v189 offset:36864
	ds_read_b128 v[230:233], v189 offset:37888
	ds_read_b128 v[234:237], v189 offset:38912
	ds_read_b128 v[238:241], v189 offset:39936
	global_load_lds_dwordx4 v[246:247], off
	v_lshl_add_u64 v[246:247], s[12:13], 0, v[134:135]
	s_mov_b32 m0, s41
	s_nop 0
	global_load_lds_dwordx4 v[246:247], off
	s_waitcnt vmcnt(8)
	s_waitcnt lgkmcnt(0)
	s_barrier
	v_mfma_f32_16x16x32_bf16 v[124:127], v[128:131], v[194:197], v[124:127]
	v_mfma_f32_16x16x32_bf16 v[120:123], v[148:151], v[194:197], v[120:123]
	v_mfma_f32_16x16x32_bf16 v[108:111], v[128:131], v[202:205], v[108:111]
	v_mfma_f32_16x16x32_bf16 v[104:107], v[148:151], v[202:205], v[104:107]
	v_mfma_f32_16x16x32_bf16 v[92:95], v[128:131], v[210:213], v[92:95]
	v_mfma_f32_16x16x32_bf16 v[88:91], v[148:151], v[210:213], v[88:91]
	v_mfma_f32_16x16x32_bf16 v[80:83], v[128:131], v[234:237], v[80:83]
	v_mfma_f32_16x16x32_bf16 v[72:75], v[148:151], v[234:237], v[72:75]
	v_mfma_f32_16x16x32_bf16 v[124:127], v[144:147], v[198:201], v[124:127]
	v_mfma_f32_16x16x32_bf16 v[120:123], v[152:155], v[198:201], v[120:123]
	v_mfma_f32_16x16x32_bf16 v[108:111], v[144:147], v[206:209], v[108:111]
	v_mfma_f32_16x16x32_bf16 v[104:107], v[152:155], v[206:209], v[104:107]
	v_mfma_f32_16x16x32_bf16 v[92:95], v[144:147], v[230:233], v[92:95]
	v_mfma_f32_16x16x32_bf16 v[88:91], v[152:155], v[230:233], v[88:91]
	v_mfma_f32_16x16x32_bf16 v[80:83], v[144:147], v[238:241], v[80:83]
	v_mfma_f32_16x16x32_bf16 v[72:75], v[152:155], v[238:241], v[72:75]
	v_mfma_f32_16x16x32_bf16 v[116:119], v[156:159], v[194:197], v[116:119]
	v_mfma_f32_16x16x32_bf16 v[112:115], v[164:167], v[194:197], v[112:115]
	v_mfma_f32_16x16x32_bf16 v[100:103], v[156:159], v[202:205], v[100:103]
	v_mfma_f32_16x16x32_bf16 v[96:99], v[164:167], v[202:205], v[96:99]
	v_mfma_f32_16x16x32_bf16 v[84:87], v[156:159], v[210:213], v[84:87]
	v_mfma_f32_16x16x32_bf16 v[76:79], v[164:167], v[210:213], v[76:79]
	v_mfma_f32_16x16x32_bf16 v[68:71], v[156:159], v[234:237], v[68:71]
	v_mfma_f32_16x16x32_bf16 v[64:67], v[164:167], v[234:237], v[64:67]
	v_mfma_f32_16x16x32_bf16 v[116:119], v[160:163], v[198:201], v[116:119]
	v_mfma_f32_16x16x32_bf16 v[112:115], v[190:193], v[198:201], v[112:115]
	v_mfma_f32_16x16x32_bf16 v[100:103], v[160:163], v[206:209], v[100:103]
	v_mfma_f32_16x16x32_bf16 v[96:99], v[190:193], v[206:209], v[96:99]
	v_mfma_f32_16x16x32_bf16 v[84:87], v[160:163], v[230:233], v[84:87]
	v_mfma_f32_16x16x32_bf16 v[76:79], v[190:193], v[230:233], v[76:79]
	v_mfma_f32_16x16x32_bf16 v[68:71], v[160:163], v[238:241], v[68:71]
	v_mfma_f32_16x16x32_bf16 v[64:67], v[190:193], v[238:241], v[64:67]
	s_barrier
; #define PG8_STAGE(bufoff, gbase, voff) do { _Pragma("unroll") for (int _i = 0; _i < 2; ++_i) \
;         __builtin_amdgcn_global_load_lds((const unsigned*)((const char*)(gbase) + (voff)[_i]), (LAS unsigned*)(lds + (bufoff) + ldsw + _i * 8192), 16, 0, 0); } while (0)
; #define PG8_LDA(dst, b, h) do { _Pragma("unroll") for (int m = 0; m < 4; ++m) _Pragma("unroll") for (int k = 0; k < 2; ++k) dst[m][k] = *(const LAS bf16x8*)(lds + PG8_SA(b, h) + aoff + m * 2048 + k * 1024); } while (0)
; #define PG8_MMA(ai, bj, At, Bt) do { __builtin_amdgcn_s_setprio(1); _Pragma("unroll") for (int m = 0; m < 4; ++m) _Pragma("unroll") for (int n = 0; n < 2; ++n) _Pragma("unroll") for (int k = 0; k < 2; ++k) \
;         acc[ai][bj][m][n] = __builtin_amdgcn_mfma_f32_16x16x32_bf16(Bt[n][k], At[m][k], acc[ai][bj][m][n], 0, 0, 0); __builtin_amdgcn_s_setprio(0); } while (0)
; #define PG8_WAIT_V(n) asm volatile("s_waitcnt vmcnt(" #n ")" ::: "memory")
; #define PG8_WAIT_L(n) asm volatile("s_waitcnt lgkmcnt(" #n ")" ::: "memory")
; #define PG8_BAR __builtin_amdgcn_s_barrier()
; #define PG8_SCHED __builtin_amdgcn_sched_barrier(0)
; template <class Epi>
; __device__ __forceinline__ void gemm_phase(LAS unsigned char* lds, const Gemm g, const StaticOrder& S, const Epi& E, const int tid) {
;     ...
;             PG8_LDA(At, 1, 1); PG8_STAGE(PG8_SB(1, 0), b3, voffB); PG8_STAGE(PG8_SB(1, 1), b3 + hsB, voffB); PG8_STAGE(PG8_SA(1, 0), a3, voffA);
;             PG8_WAIT_V(8); PG8_WAIT_L(0); PG8_BAR; PG8_MMA(1, 0, At, B0); PG8_MMA(1, 1, At, B1); PG8_BAR; PG8_SCHED;
;         }
;         if (wr == 0) PG8_BAR;
	s_add_i32 s2, s2, s27
	v_lshl_add_u64 v[170:171], v[170:171], 0, s[28:29]
	s_mov_b32 m0, s2
	ds_read_b128 v[194:197], v189 offset:49152
	ds_read_b128 v[198:201], v189 offset:50176
	ds_read_b128 v[202:205], v189 offset:51200
	ds_read_b128 v[206:209], v189 offset:52224
	ds_read_b128 v[210:213], v189 offset:53248
	ds_read_b128 v[230:233], v189 offset:54272
	ds_read_b128 v[234:237], v189 offset:55296
	ds_read_b128 v[238:241], v189 offset:56320
	global_load_lds_dwordx4 v[170:171], off
	s_add_i32 m0, s2, 0x2000
	s_add_u32 s12, s14, 0x160080
	v_lshl_add_u64 v[170:171], v[172:173], 0, s[28:29]
	s_addc_u32 s13, s15, 0
	s_add_i32 s2, s24, s27
	global_load_lds_dwordx4 v[170:171], off
	v_lshl_add_u64 v[170:171], s[12:13], 0, v[136:137]
	s_mov_b32 m0, s2
	s_nop 0
	global_load_lds_dwordx4 v[170:171], off
	v_lshl_add_u64 v[170:171], s[12:13], 0, v[132:133]
	s_add_i32 m0, s2, 0x2000
	s_nop 0
	global_load_lds_dwordx4 v[170:171], off
	v_lshl_add_u64 v[170:171], v[242:243], 0, s[28:29]
	s_mov_b32 m0, s44
	s_nop 0
	global_load_lds_dwordx4 v[170:171], off
	v_lshl_add_u64 v[170:171], v[244:245], 0, s[28:29]
	s_mov_b32 m0, s45
	s_nop 0
	global_load_lds_dwordx4 v[170:171], off
	s_waitcnt vmcnt(8)
	s_waitcnt lgkmcnt(0)
	s_barrier
	v_mfma_f32_16x16x32_bf16 v[60:63], v[128:131], v[194:197], v[60:63]
	v_mfma_f32_16x16x32_bf16 v[56:59], v[148:151], v[194:197], v[56:59]
	v_mfma_f32_16x16x32_bf16 v[44:47], v[128:131], v[202:205], v[44:47]
	v_mfma_f32_16x16x32_bf16 v[40:43], v[148:151], v[202:205], v[40:43]
	v_mfma_f32_16x16x32_bf16 v[28:31], v[128:131], v[210:213], v[28:31]
	v_mfma_f32_16x16x32_bf16 v[24:27], v[148:151], v[210:213], v[24:27]
	v_mfma_f32_16x16x32_bf16 v[12:15], v[128:131], v[234:237], v[12:15]
	v_mfma_f32_16x16x32_bf16 v[8:11], v[148:151], v[234:237], v[8:11]
	v_mfma_f32_16x16x32_bf16 v[60:63], v[144:147], v[198:201], v[60:63]
	v_mfma_f32_16x16x32_bf16 v[56:59], v[152:155], v[198:201], v[56:59]
	v_mfma_f32_16x16x32_bf16 v[44:47], v[144:147], v[206:209], v[44:47]
	v_mfma_f32_16x16x32_bf16 v[40:43], v[152:155], v[206:209], v[40:43]
	v_mfma_f32_16x16x32_bf16 v[28:31], v[144:147], v[230:233], v[28:31]
	v_mfma_f32_16x16x32_bf16 v[24:27], v[152:155], v[230:233], v[24:27]
	v_mfma_f32_16x16x32_bf16 v[12:15], v[144:147], v[238:241], v[12:15]
	v_mfma_f32_16x16x32_bf16 v[8:11], v[152:155], v[238:241], v[8:11]
	v_mfma_f32_16x16x32_bf16 v[52:55], v[156:159], v[194:197], v[52:55]
	v_mfma_f32_16x16x32_bf16 v[48:51], v[164:167], v[194:197], v[48:51]
	v_mfma_f32_16x16x32_bf16 v[36:39], v[156:159], v[202:205], v[36:39]
	v_mfma_f32_16x16x32_bf16 v[32:35], v[164:167], v[202:205], v[32:35]
	v_mfma_f32_16x16x32_bf16 v[20:23], v[156:159], v[210:213], v[20:23]
	v_mfma_f32_16x16x32_bf16 v[16:19], v[164:167], v[210:213], v[16:19]
	v_mfma_f32_16x16x32_bf16 v[4:7], v[156:159], v[234:237], v[4:7]
	v_mfma_f32_16x16x32_bf16 v[0:3], v[164:167], v[234:237], v[0:3]
	v_mfma_f32_16x16x32_bf16 v[52:55], v[160:163], v[198:201], v[52:55]
	v_mfma_f32_16x16x32_bf16 v[48:51], v[190:193], v[198:201], v[48:51]
	v_mfma_f32_16x16x32_bf16 v[36:39], v[160:163], v[206:209], v[36:39]
	v_mfma_f32_16x16x32_bf16 v[32:35], v[190:193], v[206:209], v[32:35]
	v_mfma_f32_16x16x32_bf16 v[20:23], v[160:163], v[230:233], v[20:23]
	v_mfma_f32_16x16x32_bf16 v[16:19], v[190:193], v[230:233], v[16:19]
	v_mfma_f32_16x16x32_bf16 v[4:7], v[160:163], v[238:241], v[4:7]
	v_mfma_f32_16x16x32_bf16 v[0:3], v[190:193], v[238:241], v[0:3]
	s_barrier
	s_add_i32 s53, s53, 2
	s_add_u32 s38, s38, 0x100
	s_addc_u32 s39, s39, 0
	s_cmpk_gt_u32 s53, 0x55
	s_mov_b64 s[12:13], s[0:1]
	s_cbranch_scc0 .LBB0_1076
	s_and_b64 vcc, exec, s[6:7]
	s_cbranch_vccz .LBB0_1079
	s_barrier
